# GEMM K-loops: per-segment s_setprio toggling replaced by one static priority per block (blockIdx bit 8 -> prio 2, else 0)
# speedup vs baseline: 1.0175x; 1.0014x over previous
.LBB0_286:
	s_and_b32 s0, s33, 7
	s_lshl_b32 s0, s0, 3
	s_lshr_b32 s1, s3, 3
	s_or_b32 s0, s0, s1
	s_lshl_b32 s34, s0, 7
	v_or_b32_e32 v0, s34, v149
	v_lshl_or_b32 v128, v0, 11, v158
	v_lshl_add_u64 v[98:99], s[14:15], 0, v[128:129]
	v_add_co_u32_e32 v6, vcc, 0x10000, v98
	s_lshl_b32 s1, s33, 4
	s_nop 0
	v_addc_co_u32_e32 v7, vcc, 0, v99, vcc
	s_and_b32 s0, s1, 0x7fffff80
	v_add_co_u32_e32 v8, vcc, 0x20000, v98
	v_or_b32_e32 v0, s0, v149
	s_nop 0
	v_addc_co_u32_e32 v9, vcc, 0, v99, vcc
	v_lshl_or_b32 v96, v0, 11, v158
	v_add_co_u32_e32 v10, vcc, 0x30000, v98
	v_mov_b32_e32 v97, v129
	s_nop 0
	v_addc_co_u32_e32 v11, vcc, 0, v99, vcc
	v_lshl_add_u64 v[100:101], s[12:13], 0, v[96:97]
	v_add_co_u32_e32 v12, vcc, s4, v100
	v_addc_co_u32_e32 v13, vcc, 0, v101, vcc
	v_add_co_u32_e32 v46, vcc, s5, v100
	v_addc_co_u32_e32 v47, vcc, 0, v101, vcc
	v_add_co_u32_e32 v48, vcc, s26, v100
	v_addc_co_u32_e32 v49, vcc, 0, v101, vcc
	s_movk_i32 s1, 0x100
	s_mov_b32 s6, s23
	v_mov_b32_e32 v0, 0
	v_mov_b32_e32 v1, v129
	v_mov_b32_e32 v2, v129
	v_mov_b32_e32 v3, v129
	v_mov_b32_e32 v4, 0
	v_mov_b32_e32 v5, v129
	v_mov_b32_e32 v6, v129
	v_mov_b32_e32 v7, v129
	v_mov_b32_e32 v8, 0
	v_mov_b32_e32 v9, v129
	v_mov_b32_e32 v10, v129
	v_mov_b32_e32 v11, v129
	v_mov_b32_e32 v12, 0
	v_mov_b32_e32 v13, v129
	v_lshl_add_u64 v[102:103], v[100:101], 0, s[10:11]
	v_lshl_add_u64 v[104:105], v[100:101], 0, s[18:19]
	v_lshl_add_u64 v[106:107], v[100:101], 0, s[20:21]
	v_lshl_add_u64 v[108:109], v[98:99], 0, s[10:11]
	v_lshl_add_u64 v[110:111], v[98:99], 0, s[18:19]
	v_lshl_add_u64 v[112:113], v[98:99], 0, s[20:21]
	s_barrier
	v_mov_b32_e32 v46, v129
	v_mov_b32_e32 v47, v129
	v_mov_b32_e32 v48, 0
	v_mov_b32_e32 v49, v129
	v_mov_b32_e32 v50, v129
	v_mov_b32_e32 v51, v129
	v_mov_b32_e32 v52, 0
	v_mov_b32_e32 v53, v129
	v_mov_b32_e32 v54, v129
	v_mov_b32_e32 v55, v129
	v_mov_b32_e32 v56, 0
	v_mov_b32_e32 v57, v129
	v_mov_b32_e32 v58, v129
	v_mov_b32_e32 v59, v129
	v_mov_b32_e32 v60, 0
	v_mov_b32_e32 v61, v129
	v_mov_b32_e32 v62, v129
	v_mov_b32_e32 v63, v129
	v_mov_b32_e32 v14, v129
	v_mov_b32_e32 v15, v129
	v_mov_b32_e32 v16, 0
	v_mov_b32_e32 v17, v129
	v_mov_b32_e32 v18, v129
	v_mov_b32_e32 v19, v129
	v_mov_b32_e32 v20, 0
	v_mov_b32_e32 v21, v129
	v_mov_b32_e32 v22, v129
	v_mov_b32_e32 v23, v129
	v_mov_b32_e32 v24, 0
	v_mov_b32_e32 v25, v129
	v_mov_b32_e32 v26, v129
	v_mov_b32_e32 v27, v129
	v_mov_b32_e32 v28, 0
	v_mov_b32_e32 v29, v129
	v_mov_b32_e32 v30, v129
	v_mov_b32_e32 v31, v129
	v_mov_b32_e32 v32, 0
	v_mov_b32_e32 v33, v129
	v_mov_b32_e32 v34, v129
	v_mov_b32_e32 v35, v129
	v_mov_b32_e32 v36, 0
	v_mov_b32_e32 v37, v129
	v_mov_b32_e32 v38, v129
	v_mov_b32_e32 v39, v129
	v_mov_b32_e32 v40, 0
	v_mov_b32_e32 v41, v129
	v_mov_b32_e32 v42, v129
	v_mov_b32_e32 v43, v129
	v_mov_b32_e32 v44, 0
	v_mov_b32_e32 v45, v129
	v_readlane_b32 s100, v253, 0
	v_readlane_b32 s101, v253, 1
	s_load_dwordx2 s[100:101], s[100:101], 0x160
	v_lshrrev_b32_e32 v71, 6, v146
	s_nop 0
	v_readfirstlane_b32 s24, v71
	v_lshrrev_b32_e32 v69, 3, v146
	v_and_b32_e32 v70, 7, v146
	v_xor_b32_e32 v70, v69, v70
	v_and_b32_e32 v70, 7, v70
	v_lshlrev_b32_e32 v70, 4, v70
	v_lshl_or_b32 v68, v69, 11, v70
	v_add_u32_e32 v69, 0x10000, v68
	v_add_u32_e32 v70, 0x20000, v68
	v_add_u32_e32 v71, 0x30000, v68
	s_and_b32 s98, s33, 7
	s_lshl_b32 s98, s98, 3
	s_and_b32 s99, s69, 7
	s_or_b32 s98, s98, s99
	s_lshl_b32 s98, s98, 18
	s_add_u32 s98, s98, 0x2000000
	s_lshr_b32 s99, s33, 3
	s_lshl_b32 s99, s99, 18
	s_add_u32 s99, s99, 0x7200000
	s_lshl_b32 s24, s24, 10
	s_waitcnt lgkmcnt(0)
	s_mov_b32 m0, s99
	s_add_u32 s98, s100, s98
	s_addc_u32 s99, s101, 0
	s_add_u32 s100, s100, m0
	s_addc_u32 s101, s101, 0
	s_add_u32 m0, s24, 0x0
	s_nop 0
	global_load_lds_dwordx4 v68, s[98:99]
	s_add_u32 m0, s24, 0x1000
	s_nop 0
	global_load_lds_dwordx4 v69, s[98:99]
	s_add_u32 m0, s24, 0x2000
	s_nop 0
	global_load_lds_dwordx4 v70, s[98:99]
	s_add_u32 m0, s24, 0x3000
	s_nop 0
	global_load_lds_dwordx4 v71, s[98:99]
	s_add_u32 m0, s24, 0x8000
	s_nop 0
	global_load_lds_dwordx4 v68, s[100:101]
	s_add_u32 m0, s24, 0x9000
	s_nop 0
	global_load_lds_dwordx4 v69, s[100:101]
	s_add_u32 m0, s24, 0xa000
	s_nop 0
	global_load_lds_dwordx4 v70, s[100:101]
	s_add_u32 m0, s24, 0xb000
	s_nop 0
	global_load_lds_dwordx4 v71, s[100:101]
	s_add_u32 s98, s98, 0x80
	s_addc_u32 s99, s99, 0
	s_add_u32 s100, s100, 0x80
	s_addc_u32 s101, s101, 0
	s_waitcnt vmcnt(0)
	s_waitcnt lgkmcnt(0)
	s_barrier
	s_bitcmp1_b32 s69, 8
	s_cbranch_scc1 .Lprio_h287
	s_setprio 0
	s_branch .Lprio_j287
.Lprio_h287:
	s_setprio 2
.Lprio_j287:
.LBB0_287:
	s_add_i32 s2, s6, 2
	ds_read_b128 v[114:117], v165 offset:32768
	ds_read_b128 v[122:125], v165 offset:34816
	ds_read_b128 v[118:121], v161
	ds_read_b128 v[138:141], v161 offset:2048
	ds_read_b128 v[174:177], v161 offset:4096
	ds_read_b128 v[178:181], v161 offset:6144
	s_waitcnt lgkmcnt(3)
	v_mfma_f32_16x16x32_bf16 v[0:3], v[114:117], v[118:121], v[0:3]
	ds_read_b128 v[182:185], v165 offset:36864
	v_mfma_f32_16x16x32_bf16 v[4:7], v[122:125], v[118:121], v[4:7]
	ds_read_b128 v[186:189], v165 offset:38912
	s_waitcnt lgkmcnt(1)
	v_mfma_f32_16x16x32_bf16 v[8:11], v[182:185], v[118:121], v[8:11]
	s_waitcnt lgkmcnt(0)
	v_mfma_f32_16x16x32_bf16 v[12:15], v[186:189], v[118:121], v[12:15]
	s_add_u32 m0, s24, 0x4000
	s_nop 0
	global_load_lds_dwordx4 v68, s[98:99]
	ds_read_b128 v[190:193], v166
	v_mfma_f32_16x16x32_bf16 v[16:19], v[114:117], v[138:141], v[16:19]
	v_mfma_f32_16x16x32_bf16 v[20:23], v[122:125], v[138:141], v[20:23]
	s_add_u32 m0, s24, 0x5000
	s_nop 0
	global_load_lds_dwordx4 v69, s[98:99]
	ds_read_b128 v[198:201], v166 offset:2048
	v_mfma_f32_16x16x32_bf16 v[24:27], v[182:185], v[138:141], v[24:27]
	v_mfma_f32_16x16x32_bf16 v[28:31], v[186:189], v[138:141], v[28:31]
	s_add_u32 m0, s24, 0x6000
	s_nop 0
	global_load_lds_dwordx4 v70, s[98:99]
	ds_read_b128 v[202:205], v166 offset:4096
	v_mfma_f32_16x16x32_bf16 v[32:35], v[114:117], v[174:177], v[32:35]
	v_mfma_f32_16x16x32_bf16 v[36:39], v[122:125], v[174:177], v[36:39]
	s_add_u32 m0, s24, 0x7000
	s_nop 0
	global_load_lds_dwordx4 v71, s[98:99]
	ds_read_b128 v[210:213], v166 offset:6144
	v_mfma_f32_16x16x32_bf16 v[40:43], v[182:185], v[174:177], v[40:43]
	v_mfma_f32_16x16x32_bf16 v[44:47], v[186:189], v[174:177], v[44:47]
	s_add_u32 m0, s24, 0xc000
	s_nop 0
	global_load_lds_dwordx4 v68, s[100:101]
	ds_read_b128 v[214:217], v167 offset:32768
	v_mfma_f32_16x16x32_bf16 v[48:51], v[114:117], v[178:181], v[48:51]
	v_mfma_f32_16x16x32_bf16 v[52:55], v[122:125], v[178:181], v[52:55]
	s_add_u32 m0, s24, 0xd000
	s_nop 0
	global_load_lds_dwordx4 v69, s[100:101]
	ds_read_b128 v[122:125], v167 offset:34816
	v_mfma_f32_16x16x32_bf16 v[56:59], v[182:185], v[178:181], v[56:59]
	v_mfma_f32_16x16x32_bf16 v[60:63], v[186:189], v[178:181], v[60:63]
	s_add_u32 m0, s24, 0xe000
	s_nop 0
	global_load_lds_dwordx4 v70, s[100:101]
	ds_read_b128 v[182:185], v167 offset:36864
	s_waitcnt lgkmcnt(2)
	v_mfma_f32_16x16x32_bf16 v[0:3], v[214:217], v[190:193], v[0:3]
	s_waitcnt lgkmcnt(1)
	v_mfma_f32_16x16x32_bf16 v[4:7], v[122:125], v[190:193], v[4:7]
	s_add_u32 m0, s24, 0xf000
	s_nop 0
	global_load_lds_dwordx4 v71, s[100:101]
	s_add_u32 s98, s98, 0x80
	s_addc_u32 s99, s99, 0
	s_add_u32 s100, s100, 0x80
	s_addc_u32 s101, s101, 0
	ds_read_b128 v[218:221], v167 offset:38912
	s_waitcnt lgkmcnt(1)
	v_mfma_f32_16x16x32_bf16 v[8:11], v[182:185], v[190:193], v[8:11]
	s_waitcnt lgkmcnt(0)
	v_mfma_f32_16x16x32_bf16 v[12:15], v[218:221], v[190:193], v[12:15]
	v_mfma_f32_16x16x32_bf16 v[16:19], v[214:217], v[198:201], v[16:19]
	v_mfma_f32_16x16x32_bf16 v[20:23], v[122:125], v[198:201], v[20:23]
	v_mfma_f32_16x16x32_bf16 v[24:27], v[182:185], v[198:201], v[24:27]
	v_mfma_f32_16x16x32_bf16 v[28:31], v[218:221], v[198:201], v[28:31]
	v_mfma_f32_16x16x32_bf16 v[32:35], v[214:217], v[202:205], v[32:35]
	v_mfma_f32_16x16x32_bf16 v[36:39], v[122:125], v[202:205], v[36:39]
	v_mfma_f32_16x16x32_bf16 v[40:43], v[182:185], v[202:205], v[40:43]
	v_mfma_f32_16x16x32_bf16 v[44:47], v[218:221], v[202:205], v[44:47]
	v_mfma_f32_16x16x32_bf16 v[48:51], v[214:217], v[210:213], v[48:51]
	v_mfma_f32_16x16x32_bf16 v[52:55], v[122:125], v[210:213], v[52:55]
	v_mfma_f32_16x16x32_bf16 v[56:59], v[182:185], v[210:213], v[56:59]
	v_mfma_f32_16x16x32_bf16 v[60:63], v[218:221], v[210:213], v[60:63]
	s_waitcnt vmcnt(0) lgkmcnt(0)
	s_barrier
	ds_read_b128 v[84:87], v165 offset:49152
	ds_read_b128 v[88:91], v165 offset:51200
	ds_read_b128 v[64:67], v161 offset:16384
	ds_read_b128 v[72:75], v161 offset:18432
	ds_read_b128 v[76:79], v161 offset:20480
	ds_read_b128 v[92:95], v161 offset:22528
	s_waitcnt lgkmcnt(3)
	v_mfma_f32_16x16x32_bf16 v[0:3], v[84:87], v[64:67], v[0:3]
	ds_read_b128 v[122:125], v165 offset:53248
	v_mfma_f32_16x16x32_bf16 v[4:7], v[88:91], v[64:67], v[4:7]
	ds_read_b128 v[182:185], v165 offset:55296
	s_waitcnt lgkmcnt(1)
	v_mfma_f32_16x16x32_bf16 v[8:11], v[122:125], v[64:67], v[8:11]
	s_waitcnt lgkmcnt(0)
	v_mfma_f32_16x16x32_bf16 v[12:15], v[182:185], v[64:67], v[12:15]
	s_add_u32 m0, s24, 0x0
	s_nop 0
	global_load_lds_dwordx4 v68, s[98:99]
	ds_read_b128 v[190:193], v166 offset:16384
	v_mfma_f32_16x16x32_bf16 v[16:19], v[84:87], v[72:75], v[16:19]
	v_mfma_f32_16x16x32_bf16 v[20:23], v[88:91], v[72:75], v[20:23]
	s_add_u32 m0, s24, 0x1000
	s_nop 0
	global_load_lds_dwordx4 v69, s[98:99]
	ds_read_b128 v[198:201], v166 offset:18432
	v_mfma_f32_16x16x32_bf16 v[24:27], v[122:125], v[72:75], v[24:27]
	v_mfma_f32_16x16x32_bf16 v[28:31], v[182:185], v[72:75], v[28:31]
	s_add_u32 m0, s24, 0x2000
	s_nop 0
	global_load_lds_dwordx4 v70, s[98:99]
	ds_read_b128 v[202:205], v166 offset:20480
	v_mfma_f32_16x16x32_bf16 v[32:35], v[84:87], v[76:79], v[32:35]
	v_mfma_f32_16x16x32_bf16 v[36:39], v[88:91], v[76:79], v[36:39]
	s_add_u32 m0, s24, 0x3000
	s_nop 0
	global_load_lds_dwordx4 v71, s[98:99]
	ds_read_b128 v[210:213], v166 offset:22528
	v_mfma_f32_16x16x32_bf16 v[40:43], v[122:125], v[76:79], v[40:43]
	v_mfma_f32_16x16x32_bf16 v[44:47], v[182:185], v[76:79], v[44:47]
	s_add_u32 m0, s24, 0x8000
	s_nop 0
	global_load_lds_dwordx4 v68, s[100:101]
	ds_read_b128 v[214:217], v167 offset:49152
	v_mfma_f32_16x16x32_bf16 v[48:51], v[84:87], v[92:95], v[48:51]
	v_mfma_f32_16x16x32_bf16 v[52:55], v[88:91], v[92:95], v[52:55]
	s_add_u32 m0, s24, 0x9000
	s_nop 0
	global_load_lds_dwordx4 v69, s[100:101]
	ds_read_b128 v[218:221], v167 offset:51200
	v_mfma_f32_16x16x32_bf16 v[56:59], v[122:125], v[92:95], v[56:59]
	v_mfma_f32_16x16x32_bf16 v[60:63], v[182:185], v[92:95], v[60:63]
	s_add_u32 m0, s24, 0xa000
	s_nop 0
	global_load_lds_dwordx4 v70, s[100:101]
	ds_read_b128 v[122:125], v167 offset:53248
	s_waitcnt lgkmcnt(2)
	v_mfma_f32_16x16x32_bf16 v[0:3], v[214:217], v[190:193], v[0:3]
	s_waitcnt lgkmcnt(1)
	v_mfma_f32_16x16x32_bf16 v[4:7], v[218:221], v[190:193], v[4:7]
	s_add_u32 m0, s24, 0xb000
	s_nop 0
	global_load_lds_dwordx4 v71, s[100:101]
	s_add_u32 s98, s98, 0x80
	s_addc_u32 s99, s99, 0
	s_add_u32 s100, s100, 0x80
	s_addc_u32 s101, s101, 0
	ds_read_b128 v[182:185], v167 offset:55296
	s_waitcnt lgkmcnt(1)
	v_mfma_f32_16x16x32_bf16 v[8:11], v[122:125], v[190:193], v[8:11]
	s_waitcnt lgkmcnt(0)
	v_mfma_f32_16x16x32_bf16 v[12:15], v[182:185], v[190:193], v[12:15]
	v_mfma_f32_16x16x32_bf16 v[16:19], v[214:217], v[198:201], v[16:19]
	v_mfma_f32_16x16x32_bf16 v[20:23], v[218:221], v[198:201], v[20:23]
	v_mfma_f32_16x16x32_bf16 v[24:27], v[122:125], v[198:201], v[24:27]
	v_mfma_f32_16x16x32_bf16 v[28:31], v[182:185], v[198:201], v[28:31]
	v_mfma_f32_16x16x32_bf16 v[32:35], v[214:217], v[202:205], v[32:35]
	v_mfma_f32_16x16x32_bf16 v[36:39], v[218:221], v[202:205], v[36:39]
	v_mfma_f32_16x16x32_bf16 v[40:43], v[122:125], v[202:205], v[40:43]
	v_mfma_f32_16x16x32_bf16 v[44:47], v[182:185], v[202:205], v[44:47]
	v_mfma_f32_16x16x32_bf16 v[48:51], v[214:217], v[210:213], v[48:51]
	v_mfma_f32_16x16x32_bf16 v[52:55], v[218:221], v[210:213], v[52:55]
	v_mfma_f32_16x16x32_bf16 v[56:59], v[122:125], v[210:213], v[56:59]
	v_mfma_f32_16x16x32_bf16 v[60:63], v[182:185], v[210:213], v[60:63]
	s_mov_b32 s6, s2
	s_waitcnt vmcnt(0) lgkmcnt(0)
	s_barrier
	s_cmp_lt_u32 s6, 16
	s_cbranch_scc1 .LBB0_287
	s_setprio 0
	s_cmpk_lt_u32 s33, 0x50
	v_or_b32_e32 v138, s0, v234
	v_add_u32_e32 v128, s34, v164
	s_cselect_b64 s[24:25], -1, 0
	s_and_b32 s0, s33, 0x7ffffff0
	v_or_b32_e32 v173, v128, v148
	s_cmpk_lg_i32 s0, 0x50
	s_mov_b64 s[6:7], -1
	s_cbranch_scc0 .LBB0_298
	s_waitcnt vmcnt(7)
	v_lshlrev_b32_e32 v64, 1, v128
	s_and_b64 s[0:1], s[16:17], s[24:25]
	v_and_b32_e32 v128, 0x780, v64
	v_cndmask_b32_e64 v64, 0, 1, s[0:1]
	v_cmp_ne_u32_e64 s[6:7], 1, v64
	v_mov_b64_e32 v[66:67], v[2:3]
	s_waitcnt vmcnt(6)
	v_mov_b64_e32 v[70:71], v[6:7]
	s_waitcnt vmcnt(5)
	v_mov_b64_e32 v[74:75], v[10:11]
	s_waitcnt vmcnt(3)
	v_mov_b64_e32 v[78:79], v[14:15]
	v_lshl_add_u64 v[140:141], v[132:133], 0, v[128:129]
	s_andn2_b64 vcc, exec, s[0:1]
	v_lshlrev_b32_e32 v137, 7, v173
	v_mov_b64_e32 v[64:65], v[0:1]
	v_mov_b64_e32 v[68:69], v[4:5]
	v_mov_b64_e32 v[72:73], v[8:9]
	v_mov_b64_e32 v[76:77], v[12:13]
	s_cbranch_vccnz .LBB0_291
	v_and_b32_e32 v128, 0x780, v137
	v_lshl_add_u64 v[76:77], v[132:133], 0, v[128:129]
	global_load_dwordx4 v[64:67], v[140:141], off
	global_load_dwordx4 v[68:71], v[140:141], off offset:16
	global_load_dwordx4 v[72:75], v[76:77], off
	s_nop 0
	global_load_dwordx4 v[76:79], v[76:77], off offset:16
	v_mov_b32_e32 v80, v3
	v_mov_b32_e32 v81, v7
	v_mov_b32_e32 v82, v7
	v_mov_b32_e32 v83, v3
	s_waitcnt vmcnt(6)
	v_mov_b32_e32 v84, v11
	v_mov_b32_e32 v85, v15
	v_mov_b32_e32 v86, v15
	v_mov_b32_e32 v87, v11
	s_waitcnt vmcnt(3)
	v_mov_b32_e32 v88, v64
	v_mov_b32_e32 v89, v66
	v_mov_b32_e32 v66, v65
	s_waitcnt vmcnt(2)
	v_mul_f32_e32 v90, v2, v68
	v_mul_f32_e32 v92, v6, v69
	v_mul_f32_e32 v94, v6, v68
	v_mul_f32_e32 v96, v2, v69
	v_pk_mul_f32 v[64:65], v[80:81], v[70:71]
	v_pk_mul_f32 v[68:69], v[82:83], v[70:71]
	s_waitcnt vmcnt(1)
	v_mov_b32_e32 v80, v72
	v_mov_b32_e32 v81, v74
	v_mov_b32_e32 v74, v73
	s_waitcnt vmcnt(0)
	v_mul_f32_e32 v82, v10, v76
	v_mul_f32_e32 v98, v14, v77
	v_mul_f32_e32 v100, v14, v76
	v_mul_f32_e32 v102, v10, v77
	v_pk_mul_f32 v[72:73], v[84:85], v[78:79]
	v_pk_mul_f32 v[76:77], v[86:87], v[78:79]
	v_pk_mul_f32 v[70:71], v[0:1], v[66:67]
	v_pk_mul_f32 v[66:67], v[4:5], v[66:67]
	v_mov_b32_e32 v91, v64
	v_mov_b32_e32 v93, v65
	v_mov_b32_e32 v95, v68
	v_mov_b32_e32 v97, v69
	v_pk_mul_f32 v[78:79], v[8:9], v[74:75]
	v_pk_mul_f32 v[74:75], v[12:13], v[74:75]
	v_mov_b32_e32 v83, v72
	v_mov_b32_e32 v99, v73
	v_mov_b32_e32 v101, v76
	v_mov_b32_e32 v103, v77
	v_pk_fma_f32 v[64:65], v[0:1], v[88:89], v[66:67] neg_lo:[0,0,1] neg_hi:[0,0,1]
	v_pk_add_f32 v[66:67], v[90:91], v[92:93] neg_lo:[0,1] neg_hi:[0,1]
	v_pk_fma_f32 v[68:69], v[4:5], v[88:89], v[70:71]
	v_pk_add_f32 v[70:71], v[94:95], v[96:97]
	v_pk_fma_f32 v[72:73], v[8:9], v[80:81], v[74:75] neg_lo:[0,0,1] neg_hi:[0,0,1]
	v_pk_add_f32 v[74:75], v[82:83], v[98:99] neg_lo:[0,1] neg_hi:[0,1]
	v_pk_fma_f32 v[76:77], v[12:13], v[80:81], v[78:79]
	v_pk_add_f32 v[78:79], v[100:101], v[102:103]

.LBB0_462:
	s_and_b32 s0, s49, 7
	s_or_b32 s0, s0, s3
	s_lshl_b32 s1, s0, 7
	v_or_b32_e32 v0, s1, v149
	v_lshl_or_b32 v96, v0, 11, v116
	v_lshl_add_u64 v[100:101], s[16:17], 0, v[96:97]
	v_add_co_u32_e32 v12, vcc, 0x10000, v100
	s_lshl_b32 s2, s49, 4
	s_nop 0
	v_addc_co_u32_e32 v13, vcc, 0, v101, vcc
	s_and_b32 s0, s2, 0x7fffff80
	v_add_co_u32_e32 v26, vcc, 0x20000, v100
	v_or_b32_e32 v0, s0, v149
	s_nop 0
	v_addc_co_u32_e32 v27, vcc, 0, v101, vcc
	v_lshl_or_b32 v98, v0, 11, v116
	v_add_co_u32_e32 v28, vcc, 0x30000, v100
	v_mov_b32_e32 v99, v97
	s_nop 0
	v_addc_co_u32_e32 v29, vcc, 0, v101, vcc
	v_lshl_add_u64 v[102:103], s[14:15], 0, v[98:99]
	v_add_co_u32_e32 v30, vcc, s33, v102
	s_waitcnt lgkmcnt(0)
	v_addc_co_u32_e32 v31, vcc, 0, v103, vcc
	v_add_co_u32_e32 v42, vcc, s46, v102
	s_nop 0
	v_addc_co_u32_e32 v43, vcc, 0, v103, vcc
	v_add_co_u32_e32 v44, vcc, s47, v102
	s_nop 0
	v_addc_co_u32_e32 v45, vcc, 0, v103, vcc
	s_movk_i32 s2, 0x100
	s_mov_b32 s43, s27
	v_mov_b32_e32 v60, 0
	v_mov_b32_e32 v61, v97
	v_mov_b32_e32 v62, v97
	v_mov_b32_e32 v63, v97
	v_mov_b32_e32 v40, 0
	v_mov_b32_e32 v41, v97
	v_mov_b32_e32 v42, v97
	v_mov_b32_e32 v43, v97
	v_mov_b32_e32 v28, 0
	v_mov_b32_e32 v29, v97
	v_mov_b32_e32 v30, v97
	v_mov_b32_e32 v31, v97
	v_mov_b32_e32 v12, 0
	v_mov_b32_e32 v13, v97
	v_lshl_add_u64 v[104:105], v[102:103], 0, s[30:31]
	v_lshl_add_u64 v[106:107], v[102:103], 0, s[34:35]
	v_lshl_add_u64 v[108:109], v[102:103], 0, s[36:37]
	v_lshl_add_u64 v[110:111], v[100:101], 0, s[30:31]
	v_lshl_add_u64 v[112:113], v[100:101], 0, s[34:35]
	v_lshl_add_u64 v[114:115], v[100:101], 0, s[36:37]
	s_waitcnt lgkmcnt(0)
	s_barrier
	v_mov_b32_e32 v56, 0
	v_mov_b32_e32 v57, v97
	v_mov_b32_e32 v58, v97
	v_mov_b32_e32 v59, v97
	v_mov_b32_e32 v44, 0
	v_mov_b32_e32 v45, v97
	v_mov_b32_e32 v46, v97
	v_mov_b32_e32 v47, v97
	v_mov_b32_e32 v26, v97
	v_mov_b32_e32 v27, v97
	v_mov_b32_e32 v52, 0
	v_mov_b32_e32 v53, v97
	v_mov_b32_e32 v54, v97
	v_mov_b32_e32 v55, v97
	v_mov_b32_e32 v48, 0
	v_mov_b32_e32 v49, v97
	v_mov_b32_e32 v50, v97
	v_mov_b32_e32 v51, v97
	v_mov_b32_e32 v14, v97
	v_mov_b32_e32 v15, v97
	v_mov_b32_e32 v24, 0
	v_mov_b32_e32 v25, v97
	v_mov_b32_e32 v8, 0
	v_mov_b32_e32 v9, v97
	v_mov_b32_e32 v10, v97
	v_mov_b32_e32 v11, v97
	v_mov_b32_e32 v36, 0
	v_mov_b32_e32 v37, v97
	v_mov_b32_e32 v38, v97
	v_mov_b32_e32 v39, v97
	v_mov_b32_e32 v20, 0
	v_mov_b32_e32 v21, v97
	v_mov_b32_e32 v22, v97
	v_mov_b32_e32 v23, v97
	v_mov_b32_e32 v4, 0
	v_mov_b32_e32 v5, v97
	v_mov_b32_e32 v6, v97
	v_mov_b32_e32 v7, v97
	v_mov_b32_e32 v32, 0
	v_mov_b32_e32 v33, v97
	v_mov_b32_e32 v34, v97
	v_mov_b32_e32 v35, v97
	v_mov_b32_e32 v16, 0
	v_mov_b32_e32 v17, v97
	v_mov_b32_e32 v18, v97
	v_mov_b32_e32 v19, v97
	v_mov_b32_e32 v0, 0
	v_mov_b32_e32 v1, v97
	v_mov_b32_e32 v2, v97
	v_mov_b32_e32 v3, v97
	v_readlane_b32 s100, v253, 0
	v_readlane_b32 s101, v253, 1
	s_load_dwordx2 s[100:101], s[100:101], 0x160
	v_lshrrev_b32_e32 v71, 6, v146
	s_nop 0
	v_readfirstlane_b32 s44, v71
	v_lshrrev_b32_e32 v69, 3, v146
	v_and_b32_e32 v70, 7, v146
	v_xor_b32_e32 v70, v69, v70
	v_and_b32_e32 v70, 7, v70
	v_lshlrev_b32_e32 v70, 4, v70
	v_lshl_or_b32 v68, v69, 11, v70
	v_add_u32_e32 v69, 0x10000, v68
	v_add_u32_e32 v70, 0x20000, v68
	v_add_u32_e32 v71, 0x30000, v68
	s_and_b32 s98, s49, 7
	s_and_b32 s99, s69, 7
	s_lshl_b32 s99, s99, 3
	s_or_b32 s98, s98, s99
	s_lshl_b32 s98, s98, 18
	s_add_u32 s98, s98, 0x2000000
	s_lshr_b32 s99, s49, 3
	s_lshl_b32 s99, s99, 18
	s_add_u32 s99, s99, 0x8c40000
	s_lshl_b32 s44, s44, 10
	s_waitcnt lgkmcnt(0)
	s_mov_b32 m0, s99
	s_add_u32 s98, s100, s98
	s_addc_u32 s99, s101, 0
	s_add_u32 s100, s100, m0
	s_addc_u32 s101, s101, 0
	s_add_u32 m0, s44, 0x0
	s_nop 0
	global_load_lds_dwordx4 v68, s[98:99]
	s_add_u32 m0, s44, 0x1000
	s_nop 0
	global_load_lds_dwordx4 v69, s[98:99]
	s_add_u32 m0, s44, 0x2000
	s_nop 0
	global_load_lds_dwordx4 v70, s[98:99]
	s_add_u32 m0, s44, 0x3000
	s_nop 0
	global_load_lds_dwordx4 v71, s[98:99]
	s_add_u32 m0, s44, 0x8000
	s_nop 0
	global_load_lds_dwordx4 v68, s[100:101]
	s_add_u32 m0, s44, 0x9000
	s_nop 0
	global_load_lds_dwordx4 v69, s[100:101]
	s_add_u32 m0, s44, 0xa000
	s_nop 0
	global_load_lds_dwordx4 v70, s[100:101]
	s_add_u32 m0, s44, 0xb000
	s_nop 0
	global_load_lds_dwordx4 v71, s[100:101]
	s_add_u32 s98, s98, 0x80
	s_addc_u32 s99, s99, 0
	s_add_u32 s100, s100, 0x80
	s_addc_u32 s101, s101, 0
	s_waitcnt vmcnt(0)
	s_waitcnt lgkmcnt(0)
	s_barrier
	s_bitcmp1_b32 s69, 8
	s_cbranch_scc1 .Lprio_h463
	s_setprio 0
	s_branch .Lprio_j463

.Lprio_j463:
.LBB0_463:
	s_add_i32 s42, s43, 2
	ds_read_b128 v[126:129], v120 offset:32768
	ds_read_b128 v[134:137], v120 offset:34816
	ds_read_b128 v[130:133], v119
	ds_read_b128 v[138:141], v119 offset:2048
	ds_read_b128 v[164:167], v119 offset:4096
	ds_read_b128 v[168:171], v119 offset:6144
	s_waitcnt lgkmcnt(3)
	v_mfma_f32_16x16x32_bf16 v[60:63], v[126:129], v[130:133], v[60:63]
	ds_read_b128 v[172:175], v120 offset:36864
	v_mfma_f32_16x16x32_bf16 v[40:43], v[134:137], v[130:133], v[40:43]
	ds_read_b128 v[176:179], v120 offset:38912
	s_waitcnt lgkmcnt(1)
	v_mfma_f32_16x16x32_bf16 v[28:31], v[172:175], v[130:133], v[28:31]
	s_waitcnt lgkmcnt(0)
	v_mfma_f32_16x16x32_bf16 v[12:15], v[176:179], v[130:133], v[12:15]
	s_add_u32 m0, s44, 0x4000
	s_nop 0
	global_load_lds_dwordx4 v68, s[98:99]
	ds_read_b128 v[180:183], v121
	v_mfma_f32_16x16x32_bf16 v[56:59], v[126:129], v[138:141], v[56:59]
	v_mfma_f32_16x16x32_bf16 v[44:47], v[134:137], v[138:141], v[44:47]
	s_add_u32 m0, s44, 0x5000
	s_nop 0
	global_load_lds_dwordx4 v69, s[98:99]
	ds_read_b128 v[188:191], v121 offset:2048
	v_mfma_f32_16x16x32_bf16 v[24:27], v[172:175], v[138:141], v[24:27]
	v_mfma_f32_16x16x32_bf16 v[8:11], v[176:179], v[138:141], v[8:11]
	s_add_u32 m0, s44, 0x6000
	s_nop 0
	global_load_lds_dwordx4 v70, s[98:99]
	ds_read_b128 v[192:195], v121 offset:4096
	v_mfma_f32_16x16x32_bf16 v[52:55], v[126:129], v[164:167], v[52:55]
	v_mfma_f32_16x16x32_bf16 v[36:39], v[134:137], v[164:167], v[36:39]
	s_add_u32 m0, s44, 0x7000
	s_nop 0
	global_load_lds_dwordx4 v71, s[98:99]
	ds_read_b128 v[200:203], v121 offset:6144
	v_mfma_f32_16x16x32_bf16 v[20:23], v[172:175], v[164:167], v[20:23]
	v_mfma_f32_16x16x32_bf16 v[4:7], v[176:179], v[164:167], v[4:7]
	s_add_u32 m0, s44, 0xc000
	s_nop 0
	global_load_lds_dwordx4 v68, s[100:101]
	ds_read_b128 v[204:207], v122 offset:32768
	v_mfma_f32_16x16x32_bf16 v[48:51], v[126:129], v[168:171], v[48:51]
	v_mfma_f32_16x16x32_bf16 v[32:35], v[134:137], v[168:171], v[32:35]
	s_add_u32 m0, s44, 0xd000
	s_nop 0
	global_load_lds_dwordx4 v69, s[100:101]
	ds_read_b128 v[134:137], v122 offset:34816
	v_mfma_f32_16x16x32_bf16 v[16:19], v[172:175], v[168:171], v[16:19]
	v_mfma_f32_16x16x32_bf16 v[0:3], v[176:179], v[168:171], v[0:3]
	s_add_u32 m0, s44, 0xe000
	s_nop 0
	global_load_lds_dwordx4 v70, s[100:101]
	ds_read_b128 v[172:175], v122 offset:36864
	s_waitcnt lgkmcnt(2)
	v_mfma_f32_16x16x32_bf16 v[60:63], v[204:207], v[180:183], v[60:63]
	s_waitcnt lgkmcnt(1)
	v_mfma_f32_16x16x32_bf16 v[40:43], v[134:137], v[180:183], v[40:43]
	s_add_u32 m0, s44, 0xf000
	s_nop 0
	global_load_lds_dwordx4 v71, s[100:101]
	s_add_u32 s98, s98, 0x80
	s_addc_u32 s99, s99, 0
	s_add_u32 s100, s100, 0x80
	s_addc_u32 s101, s101, 0
	ds_read_b128 v[208:211], v122 offset:38912
	s_waitcnt lgkmcnt(1)
	v_mfma_f32_16x16x32_bf16 v[28:31], v[172:175], v[180:183], v[28:31]
	s_waitcnt lgkmcnt(0)
	v_mfma_f32_16x16x32_bf16 v[12:15], v[208:211], v[180:183], v[12:15]
	v_mfma_f32_16x16x32_bf16 v[56:59], v[204:207], v[188:191], v[56:59]
	v_mfma_f32_16x16x32_bf16 v[44:47], v[134:137], v[188:191], v[44:47]
	v_mfma_f32_16x16x32_bf16 v[24:27], v[172:175], v[188:191], v[24:27]
	v_mfma_f32_16x16x32_bf16 v[8:11], v[208:211], v[188:191], v[8:11]
	v_mfma_f32_16x16x32_bf16 v[52:55], v[204:207], v[192:195], v[52:55]
	v_mfma_f32_16x16x32_bf16 v[36:39], v[134:137], v[192:195], v[36:39]
	v_mfma_f32_16x16x32_bf16 v[20:23], v[172:175], v[192:195], v[20:23]
	v_mfma_f32_16x16x32_bf16 v[4:7], v[208:211], v[192:195], v[4:7]
	v_mfma_f32_16x16x32_bf16 v[48:51], v[204:207], v[200:203], v[48:51]
	v_mfma_f32_16x16x32_bf16 v[32:35], v[134:137], v[200:203], v[32:35]
	v_mfma_f32_16x16x32_bf16 v[16:19], v[172:175], v[200:203], v[16:19]
	v_mfma_f32_16x16x32_bf16 v[0:3], v[208:211], v[200:203], v[0:3]
	s_waitcnt vmcnt(0) lgkmcnt(0)
	s_barrier
	ds_read_b128 v[84:87], v120 offset:49152
	ds_read_b128 v[88:91], v120 offset:51200
	ds_read_b128 v[64:67], v119 offset:16384
	ds_read_b128 v[72:75], v119 offset:18432
	ds_read_b128 v[76:79], v119 offset:20480
	ds_read_b128 v[92:95], v119 offset:22528
	s_waitcnt lgkmcnt(3)
	v_mfma_f32_16x16x32_bf16 v[60:63], v[84:87], v[64:67], v[60:63]
	ds_read_b128 v[134:137], v120 offset:53248
	v_mfma_f32_16x16x32_bf16 v[40:43], v[88:91], v[64:67], v[40:43]
	ds_read_b128 v[172:175], v120 offset:55296
	s_waitcnt lgkmcnt(1)
	v_mfma_f32_16x16x32_bf16 v[28:31], v[134:137], v[64:67], v[28:31]
	s_waitcnt lgkmcnt(0)
	v_mfma_f32_16x16x32_bf16 v[12:15], v[172:175], v[64:67], v[12:15]
	s_add_u32 m0, s44, 0x0
	s_nop 0
	global_load_lds_dwordx4 v68, s[98:99]
	ds_read_b128 v[180:183], v121 offset:16384
	v_mfma_f32_16x16x32_bf16 v[56:59], v[84:87], v[72:75], v[56:59]
	v_mfma_f32_16x16x32_bf16 v[44:47], v[88:91], v[72:75], v[44:47]
	s_add_u32 m0, s44, 0x1000
	s_nop 0
	global_load_lds_dwordx4 v69, s[98:99]
	ds_read_b128 v[188:191], v121 offset:18432
	v_mfma_f32_16x16x32_bf16 v[24:27], v[134:137], v[72:75], v[24:27]
	v_mfma_f32_16x16x32_bf16 v[8:11], v[172:175], v[72:75], v[8:11]
	s_add_u32 m0, s44, 0x2000
	s_nop 0
	global_load_lds_dwordx4 v70, s[98:99]
	ds_read_b128 v[192:195], v121 offset:20480
	v_mfma_f32_16x16x32_bf16 v[52:55], v[84:87], v[76:79], v[52:55]
	v_mfma_f32_16x16x32_bf16 v[36:39], v[88:91], v[76:79], v[36:39]
	s_add_u32 m0, s44, 0x3000
	s_nop 0
	global_load_lds_dwordx4 v71, s[98:99]
	ds_read_b128 v[200:203], v121 offset:22528
	v_mfma_f32_16x16x32_bf16 v[20:23], v[134:137], v[76:79], v[20:23]
	v_mfma_f32_16x16x32_bf16 v[4:7], v[172:175], v[76:79], v[4:7]
	s_add_u32 m0, s44, 0x8000
	s_nop 0
	global_load_lds_dwordx4 v68, s[100:101]
	ds_read_b128 v[204:207], v122 offset:49152
	v_mfma_f32_16x16x32_bf16 v[48:51], v[84:87], v[92:95], v[48:51]
	v_mfma_f32_16x16x32_bf16 v[32:35], v[88:91], v[92:95], v[32:35]
	s_add_u32 m0, s44, 0x9000
	s_nop 0
	global_load_lds_dwordx4 v69, s[100:101]
	ds_read_b128 v[208:211], v122 offset:51200
	v_mfma_f32_16x16x32_bf16 v[16:19], v[134:137], v[92:95], v[16:19]
	v_mfma_f32_16x16x32_bf16 v[0:3], v[172:175], v[92:95], v[0:3]
	s_add_u32 m0, s44, 0xa000
	s_nop 0
	global_load_lds_dwordx4 v70, s[100:101]
	ds_read_b128 v[134:137], v122 offset:53248
	s_waitcnt lgkmcnt(2)
	v_mfma_f32_16x16x32_bf16 v[60:63], v[204:207], v[180:183], v[60:63]
	s_waitcnt lgkmcnt(1)
	v_mfma_f32_16x16x32_bf16 v[40:43], v[208:211], v[180:183], v[40:43]
	s_add_u32 m0, s44, 0xb000
	s_nop 0
	global_load_lds_dwordx4 v71, s[100:101]
	s_add_u32 s98, s98, 0x80
	s_addc_u32 s99, s99, 0
	s_add_u32 s100, s100, 0x80
	s_addc_u32 s101, s101, 0
	ds_read_b128 v[172:175], v122 offset:55296
	s_waitcnt lgkmcnt(1)
	v_mfma_f32_16x16x32_bf16 v[28:31], v[134:137], v[180:183], v[28:31]
	s_waitcnt lgkmcnt(0)
	v_mfma_f32_16x16x32_bf16 v[12:15], v[172:175], v[180:183], v[12:15]
	v_mfma_f32_16x16x32_bf16 v[56:59], v[204:207], v[188:191], v[56:59]
	v_mfma_f32_16x16x32_bf16 v[44:47], v[208:211], v[188:191], v[44:47]
	v_mfma_f32_16x16x32_bf16 v[24:27], v[134:137], v[188:191], v[24:27]
	v_mfma_f32_16x16x32_bf16 v[8:11], v[172:175], v[188:191], v[8:11]
	v_mfma_f32_16x16x32_bf16 v[52:55], v[204:207], v[192:195], v[52:55]
	v_mfma_f32_16x16x32_bf16 v[36:39], v[208:211], v[192:195], v[36:39]
	v_mfma_f32_16x16x32_bf16 v[20:23], v[134:137], v[192:195], v[20:23]
	v_mfma_f32_16x16x32_bf16 v[4:7], v[172:175], v[192:195], v[4:7]
	v_mfma_f32_16x16x32_bf16 v[48:51], v[204:207], v[200:203], v[48:51]
	v_mfma_f32_16x16x32_bf16 v[32:35], v[208:211], v[200:203], v[32:35]
	v_mfma_f32_16x16x32_bf16 v[16:19], v[134:137], v[200:203], v[16:19]
	v_mfma_f32_16x16x32_bf16 v[0:3], v[172:175], v[200:203], v[0:3]
	s_mov_b32 s43, s42
	s_waitcnt vmcnt(0) lgkmcnt(0)
	s_barrier
	s_cmp_lt_u32 s43, 16
	s_cbranch_scc1 .LBB0_463
	s_setprio 0
	s_waitcnt vmcnt(0)
	s_and_b32 s2, s49, 7
	s_and_b32 s26, s69, 7
	s_lshl_b32 s26, s26, 3
	s_or_b32 s2, s2, s26
	s_lshl_b32 s2, s2, 7
	s_lshr_b32 s26, s49, 3
	s_lshl_b32 s26, s26, 7
	v_readlane_b32 s42, v253, 0
	v_readlane_b32 s43, v253, 1
	s_load_dwordx2 s[98:99], s[42:43], 0x160
	s_load_dwordx2 s[100:101], s[42:43], 0x88
	s_cmp_lt_u32 s2, 0x1000
	s_cselect_b32 s44, 0, 8
	s_load_dwordx2 s[42:43], s[42:43], s44
	v_and_b32_e32 v227, 15, v146
	v_bfe_u32 v228, v146, 7, 1
	v_lshl_add_u32 v227, v228, 6, v227
	v_add_u32_e32 v227, s2, v227
	v_bfe_u32 v228, v146, 4, 2
	v_lshlrev_b32_e32 v228, 2, v228
	v_bfe_u32 v218, v146, 6, 1
	v_lshl_add_u32 v228, v218, 6, v228
	v_add_u32_e32 v228, s26, v228
	v_lshlrev_b32_e32 v218, 2, v228
	v_lshl_add_u32 v96, v227, 12, v218
	v_add_u32_e32 v114, 0x10000, v96
	v_add_u32_e32 v115, 0x20000, v96
	v_add_u32_e32 v142, 0x30000, v96
	v_lshrrev_b32_e32 v214, 1, v96
	v_add_u32_e32 v214, 0xdc40000, v214
	v_lshrrev_b32_e32 v215, 1, v114
	v_add_u32_e32 v215, 0xdc40000, v215
	v_lshrrev_b32_e32 v216, 1, v115
	v_add_u32_e32 v216, 0xdc40000, v216
	v_lshrrev_b32_e32 v217, 1, v142
	v_add_u32_e32 v217, 0xdc40000, v217
	v_lshlrev_b32_e32 v222, 2, v227
	v_add_u32_e32 v222, 0xfa8a100, v222
	s_sub_u32 s44, s2, 0x1000
	s_lshr_b32 s44, s44, 10
	s_add_u32 s44, s44, 1
	s_cmp_lt_u32 s2, 0x1000
	s_cselect_b32 s44, 0, s44
	s_mul_i32 s44, s44, 0x3000
	v_add_u32_e32 v219, s44, v218
	v_add_u32_e32 v221, 0xf450000, v219
	v_add_u32_e32 v219, 0xf442000, v219
	v_mbcnt_lo_u32_b32 v229, -1, 0
	v_mbcnt_hi_u32_b32 v229, -1, v229
	v_xor_b32_e32 v244, 32, v229
	v_xor_b32_e32 v229, 16, v229
	v_lshlrev_b32_e32 v244, 2, v244
	v_lshlrev_b32_e32 v229, 2, v229
	s_waitcnt lgkmcnt(0)
	s_cmp_lt_u32 s2, 0x1000
	s_cselect_b32 s44, 0, 0x1000000
	s_sub_u32 s42, s42, s44
	s_subb_u32 s43, s43, 0
	global_load_dwordx4 v[164:167], v219, s[98:99]
	global_load_dwordx4 v[168:171], v219, s[98:99] offset:64
	global_load_dwordx4 v[172:175], v219, s[98:99] offset:128
	global_load_dwordx4 v[176:179], v219, s[98:99] offset:192
	global_load_dwordx4 v[180:183], v218, s[100:101]
	global_load_dwordx4 v[184:187], v218, s[100:101] offset:64
	global_load_dwordx4 v[188:191], v218, s[100:101] offset:128
	global_load_dwordx4 v[192:195], v218, s[100:101] offset:192
	global_load_dwordx4 v[196:199], v221, s[98:99]
	global_load_dwordx4 v[200:203], v221, s[98:99] offset:64
	global_load_dwordx4 v[204:207], v221, s[98:99] offset:128
	global_load_dwordx4 v[208:211], v221, s[98:99] offset:192
	global_load_dwordx4 v[64:67], v96, s[42:43] nt
	global_load_dwordx4 v[80:83], v114, s[42:43] nt
	global_load_dwordx4 v[98:101], v115, s[42:43] nt
	global_load_dwordx4 v[126:129], v142, s[42:43] nt
	global_load_dwordx4 v[68:71], v96, s[42:43] offset:64 nt
	global_load_dwordx4 v[84:87], v114, s[42:43] offset:64 nt
	global_load_dwordx4 v[102:105], v115, s[42:43] offset:64 nt
	global_load_dwordx4 v[130:133], v142, s[42:43] offset:64 nt
	global_load_dwordx4 v[72:75], v96, s[42:43] offset:128 nt
	global_load_dwordx4 v[88:91], v114, s[42:43] offset:128 nt
	global_load_dwordx4 v[106:109], v115, s[42:43] offset:128 nt
	global_load_dwordx4 v[134:137], v142, s[42:43] offset:128 nt
	global_load_dwordx4 v[76:79], v96, s[42:43] offset:192 nt
	global_load_dwordx4 v[92:95], v114, s[42:43] offset:192 nt
	global_load_dwordx4 v[110:113], v115, s[42:43] offset:192 nt
	global_load_dwordx4 v[138:141], v142, s[42:43] offset:192 nt
	v_mov_b32_e32 v223, 0
	v_mov_b32_e32 v224, 0
	v_mov_b32_e32 v225, 0
	v_mov_b32_e32 v226, 0
	s_waitcnt vmcnt(16)
	v_pk_add_f32 v[196:197], v[196:197], 1.0 op_sel_hi:[1,0]
	v_pk_add_f32 v[198:199], v[198:199], 1.0 op_sel_hi:[1,0]
	v_pk_mul_f32 v[196:197], v[180:181], v[196:197]
	v_pk_mul_f32 v[198:199], v[182:183], v[198:199]
	v_pk_add_f32 v[200:201], v[200:201], 1.0 op_sel_hi:[1,0]
	v_pk_add_f32 v[202:203], v[202:203], 1.0 op_sel_hi:[1,0]
	v_pk_mul_f32 v[200:201], v[184:185], v[200:201]
	v_pk_mul_f32 v[202:203], v[186:187], v[202:203]
	v_pk_add_f32 v[204:205], v[204:205], 1.0 op_sel_hi:[1,0]
	v_pk_add_f32 v[206:207], v[206:207], 1.0 op_sel_hi:[1,0]
	v_pk_mul_f32 v[204:205], v[188:189], v[204:205]
	v_pk_mul_f32 v[206:207], v[190:191], v[206:207]
	v_pk_add_f32 v[208:209], v[208:209], 1.0 op_sel_hi:[1,0]
	v_pk_add_f32 v[210:211], v[210:211], 1.0 op_sel_hi:[1,0]
	v_pk_mul_f32 v[208:209], v[192:193], v[208:209]
	v_pk_mul_f32 v[210:211], v[194:195], v[210:211]
	s_waitcnt vmcnt(15)
	v_pk_fma_f32 v[60:61], v[60:61], v[164:165], v[64:65]
	v_pk_fma_f32 v[62:63], v[62:63], v[166:167], v[66:67]
	global_store_dwordx4 v96, v[60:63], s[98:99]
	v_pk_mul_f32 v[64:65], v[196:197], v[60:61]
	v_pk_mul_f32 v[66:67], v[198:199], v[62:63]
	v_cvt_pk_bf16_f32 v64, v64, v65
	v_cvt_pk_bf16_f32 v65, v66, v67
	global_store_dwordx2 v214, v[64:65], s[98:99]
	v_pk_mul_f32 v[66:67], v[60:61], v[60:61]
	v_pk_fma_f32 v[66:67], v[62:63], v[62:63], v[66:67]
	v_add_f32_e32 v227, v66, v67
	v_add_f32_e32 v223, v223, v227
	s_waitcnt vmcnt(16)
	v_pk_fma_f32 v[56:57], v[56:57], v[164:165], v[80:81]
	v_pk_fma_f32 v[58:59], v[58:59], v[166:167], v[82:83]
	global_store_dwordx4 v114, v[56:59], s[98:99]
	v_pk_mul_f32 v[80:81], v[196:197], v[56:57]
	v_pk_mul_f32 v[82:83], v[198:199], v[58:59]
	v_cvt_pk_bf16_f32 v80, v80, v81
	v_cvt_pk_bf16_f32 v81, v82, v83
	global_store_dwordx2 v215, v[80:81], s[98:99]
	v_pk_mul_f32 v[82:83], v[56:57], v[56:57]
	v_pk_fma_f32 v[82:83], v[58:59], v[58:59], v[82:83]
	v_add_f32_e32 v227, v82, v83
	v_add_f32_e32 v224, v224, v227
	s_waitcnt vmcnt(17)
	v_pk_fma_f32 v[52:53], v[52:53], v[164:165], v[98:99]
	v_pk_fma_f32 v[54:55], v[54:55], v[166:167], v[100:101]
	global_store_dwordx4 v115, v[52:55], s[98:99]
	v_pk_mul_f32 v[98:99], v[196:197], v[52:53]
	v_pk_mul_f32 v[100:101], v[198:199], v[54:55]
	v_cvt_pk_bf16_f32 v98, v98, v99
	v_cvt_pk_bf16_f32 v99, v100, v101
	global_store_dwordx2 v216, v[98:99], s[98:99]
	v_pk_mul_f32 v[100:101], v[52:53], v[52:53]
	v_pk_fma_f32 v[100:101], v[54:55], v[54:55], v[100:101]
	v_add_f32_e32 v227, v100, v101
	v_add_f32_e32 v225, v225, v227
	s_waitcnt vmcnt(18)
	v_pk_fma_f32 v[48:49], v[48:49], v[164:165], v[126:127]
	v_pk_fma_f32 v[50:51], v[50:51], v[166:167], v[128:129]
	global_store_dwordx4 v142, v[48:51], s[98:99]
	v_pk_mul_f32 v[126:127], v[196:197], v[48:49]
	v_pk_mul_f32 v[128:129], v[198:199], v[50:51]
	v_cvt_pk_bf16_f32 v126, v126, v127
	v_cvt_pk_bf16_f32 v127, v128, v129
	global_store_dwordx2 v217, v[126:127], s[98:99]
	v_pk_mul_f32 v[128:129], v[48:49], v[48:49]
	v_pk_fma_f32 v[128:129], v[50:51], v[50:51], v[128:129]
	v_add_f32_e32 v227, v128, v129
	v_add_f32_e32 v226, v226, v227
	s_waitcnt vmcnt(19)
	v_pk_fma_f32 v[40:41], v[40:41], v[168:169], v[68:69]
	v_pk_fma_f32 v[42:43], v[42:43], v[170:171], v[70:71]
	global_store_dwordx4 v96, v[40:43], s[98:99] offset:64
	v_pk_mul_f32 v[68:69], v[200:201], v[40:41]
	v_pk_mul_f32 v[70:71], v[202:203], v[42:43]
	v_cvt_pk_bf16_f32 v68, v68, v69
	v_cvt_pk_bf16_f32 v69, v70, v71
	global_store_dwordx2 v214, v[68:69], s[98:99] offset:32
	v_pk_mul_f32 v[70:71], v[40:41], v[40:41]
	v_pk_fma_f32 v[70:71], v[42:43], v[42:43], v[70:71]
	v_add_f32_e32 v227, v70, v71
	v_add_f32_e32 v223, v223, v227
	s_waitcnt vmcnt(20)
	v_pk_fma_f32 v[44:45], v[44:45], v[168:169], v[84:85]
	v_pk_fma_f32 v[46:47], v[46:47], v[170:171], v[86:87]
	global_store_dwordx4 v114, v[44:47], s[98:99] offset:64
	v_pk_mul_f32 v[84:85], v[200:201], v[44:45]
	v_pk_mul_f32 v[86:87], v[202:203], v[46:47]
	v_cvt_pk_bf16_f32 v84, v84, v85
	v_cvt_pk_bf16_f32 v85, v86, v87
	global_store_dwordx2 v215, v[84:85], s[98:99] offset:32
	v_pk_mul_f32 v[86:87], v[44:45], v[44:45]
	v_pk_fma_f32 v[86:87], v[46:47], v[46:47], v[86:87]
	v_add_f32_e32 v227, v86, v87
	v_add_f32_e32 v224, v224, v227
	s_waitcnt vmcnt(21)
	v_pk_fma_f32 v[36:37], v[36:37], v[168:169], v[102:103]
	v_pk_fma_f32 v[38:39], v[38:39], v[170:171], v[104:105]
	global_store_dwordx4 v115, v[36:39], s[98:99] offset:64
	v_pk_mul_f32 v[102:103], v[200:201], v[36:37]
	v_pk_mul_f32 v[104:105], v[202:203], v[38:39]
	v_cvt_pk_bf16_f32 v102, v102, v103
	v_cvt_pk_bf16_f32 v103, v104, v105
	global_store_dwordx2 v216, v[102:103], s[98:99] offset:32
	v_pk_mul_f32 v[104:105], v[36:37], v[36:37]
	v_pk_fma_f32 v[104:105], v[38:39], v[38:39], v[104:105]
	v_add_f32_e32 v227, v104, v105
	v_add_f32_e32 v225, v225, v227
	s_waitcnt vmcnt(22)
	v_pk_fma_f32 v[32:33], v[32:33], v[168:169], v[130:131]
	v_pk_fma_f32 v[34:35], v[34:35], v[170:171], v[132:133]
	global_store_dwordx4 v142, v[32:35], s[98:99] offset:64
	v_pk_mul_f32 v[130:131], v[200:201], v[32:33]
	v_pk_mul_f32 v[132:133], v[202:203], v[34:35]
	v_cvt_pk_bf16_f32 v130, v130, v131
	v_cvt_pk_bf16_f32 v131, v132, v133
	global_store_dwordx2 v217, v[130:131], s[98:99] offset:32
	v_pk_mul_f32 v[132:133], v[32:33], v[32:33]
	v_pk_fma_f32 v[132:133], v[34:35], v[34:35], v[132:133]
	v_add_f32_e32 v227, v132, v133
	v_add_f32_e32 v226, v226, v227
	s_waitcnt vmcnt(23)
	v_pk_fma_f32 v[28:29], v[28:29], v[172:173], v[72:73]
	v_pk_fma_f32 v[30:31], v[30:31], v[174:175], v[74:75]
	global_store_dwordx4 v96, v[28:31], s[98:99] offset:128
	v_pk_mul_f32 v[72:73], v[204:205], v[28:29]
	v_pk_mul_f32 v[74:75], v[206:207], v[30:31]
	v_cvt_pk_bf16_f32 v72, v72, v73
	v_cvt_pk_bf16_f32 v73, v74, v75
	global_store_dwordx2 v214, v[72:73], s[98:99] offset:64
	v_pk_mul_f32 v[74:75], v[28:29], v[28:29]
	v_pk_fma_f32 v[74:75], v[30:31], v[30:31], v[74:75]
	v_add_f32_e32 v227, v74, v75
	v_add_f32_e32 v223, v223, v227
	s_waitcnt vmcnt(24)
	v_pk_fma_f32 v[24:25], v[24:25], v[172:173], v[88:89]
	v_pk_fma_f32 v[26:27], v[26:27], v[174:175], v[90:91]
	global_store_dwordx4 v114, v[24:27], s[98:99] offset:128
	v_pk_mul_f32 v[88:89], v[204:205], v[24:25]
	v_pk_mul_f32 v[90:91], v[206:207], v[26:27]
	v_cvt_pk_bf16_f32 v88, v88, v89
	v_cvt_pk_bf16_f32 v89, v90, v91
	global_store_dwordx2 v215, v[88:89], s[98:99] offset:64
	v_pk_mul_f32 v[90:91], v[24:25], v[24:25]
	v_pk_fma_f32 v[90:91], v[26:27], v[26:27], v[90:91]
	v_add_f32_e32 v227, v90, v91
	v_add_f32_e32 v224, v224, v227
	s_waitcnt vmcnt(25)
	v_pk_fma_f32 v[20:21], v[20:21], v[172:173], v[106:107]
	v_pk_fma_f32 v[22:23], v[22:23], v[174:175], v[108:109]
	global_store_dwordx4 v115, v[20:23], s[98:99] offset:128
	v_pk_mul_f32 v[106:107], v[204:205], v[20:21]
	v_pk_mul_f32 v[108:109], v[206:207], v[22:23]
	v_cvt_pk_bf16_f32 v106, v106, v107
	v_cvt_pk_bf16_f32 v107, v108, v109
	global_store_dwordx2 v216, v[106:107], s[98:99] offset:64
	v_pk_mul_f32 v[108:109], v[20:21], v[20:21]
	v_pk_fma_f32 v[108:109], v[22:23], v[22:23], v[108:109]
	v_add_f32_e32 v227, v108, v109
	v_add_f32_e32 v225, v225, v227
	s_waitcnt vmcnt(26)
	v_pk_fma_f32 v[16:17], v[16:17], v[172:173], v[134:135]
	v_pk_fma_f32 v[18:19], v[18:19], v[174:175], v[136:137]
	global_store_dwordx4 v142, v[16:19], s[98:99] offset:128
	v_pk_mul_f32 v[134:135], v[204:205], v[16:17]
	v_pk_mul_f32 v[136:137], v[206:207], v[18:19]
	v_cvt_pk_bf16_f32 v134, v134, v135
	v_cvt_pk_bf16_f32 v135, v136, v137
	global_store_dwordx2 v217, v[134:135], s[98:99] offset:64
	v_pk_mul_f32 v[136:137], v[16:17], v[16:17]
	v_pk_fma_f32 v[136:137], v[18:19], v[18:19], v[136:137]
	v_add_f32_e32 v227, v136, v137
	v_add_f32_e32 v226, v226, v227
	s_waitcnt vmcnt(27)
	v_pk_fma_f32 v[12:13], v[12:13], v[176:177], v[76:77]
	v_pk_fma_f32 v[14:15], v[14:15], v[178:179], v[78:79]
	global_store_dwordx4 v96, v[12:15], s[98:99] offset:192
	v_pk_mul_f32 v[76:77], v[208:209], v[12:13]
	v_pk_mul_f32 v[78:79], v[210:211], v[14:15]
	v_cvt_pk_bf16_f32 v76, v76, v77
	v_cvt_pk_bf16_f32 v77, v78, v79
	global_store_dwordx2 v214, v[76:77], s[98:99] offset:96
	v_pk_mul_f32 v[78:79], v[12:13], v[12:13]
	v_pk_fma_f32 v[78:79], v[14:15], v[14:15], v[78:79]
	v_add_f32_e32 v227, v78, v79
	v_add_f32_e32 v223, v223, v227
	s_waitcnt vmcnt(28)
	v_pk_fma_f32 v[8:9], v[8:9], v[176:177], v[92:93]
	v_pk_fma_f32 v[10:11], v[10:11], v[178:179], v[94:95]
	global_store_dwordx4 v114, v[8:11], s[98:99] offset:192
	v_pk_mul_f32 v[92:93], v[208:209], v[8:9]
	v_pk_mul_f32 v[94:95], v[210:211], v[10:11]
	v_cvt_pk_bf16_f32 v92, v92, v93
	v_cvt_pk_bf16_f32 v93, v94, v95
	global_store_dwordx2 v215, v[92:93], s[98:99] offset:96
	v_pk_mul_f32 v[94:95], v[8:9], v[8:9]
	v_pk_fma_f32 v[94:95], v[10:11], v[10:11], v[94:95]
	v_add_f32_e32 v227, v94, v95
	v_add_f32_e32 v224, v224, v227
	s_waitcnt vmcnt(29)
	v_pk_fma_f32 v[4:5], v[4:5], v[176:177], v[110:111]
	v_pk_fma_f32 v[6:7], v[6:7], v[178:179], v[112:113]
	global_store_dwordx4 v115, v[4:7], s[98:99] offset:192
	v_pk_mul_f32 v[110:111], v[208:209], v[4:5]
	v_pk_mul_f32 v[112:113], v[210:211], v[6:7]
	v_cvt_pk_bf16_f32 v110, v110, v111
	v_cvt_pk_bf16_f32 v111, v112, v113
	global_store_dwordx2 v216, v[110:111], s[98:99] offset:96
	v_pk_mul_f32 v[112:113], v[4:5], v[4:5]
	v_pk_fma_f32 v[112:113], v[6:7], v[6:7], v[112:113]
	v_add_f32_e32 v227, v112, v113
	v_add_f32_e32 v225, v225, v227
	s_waitcnt vmcnt(30)
	v_pk_fma_f32 v[0:1], v[0:1], v[176:177], v[138:139]
	v_pk_fma_f32 v[2:3], v[2:3], v[178:179], v[140:141]
	global_store_dwordx4 v142, v[0:3], s[98:99] offset:192
	v_pk_mul_f32 v[138:139], v[208:209], v[0:1]
	v_pk_mul_f32 v[140:141], v[210:211], v[2:3]
	v_cvt_pk_bf16_f32 v138, v138, v139
	v_cvt_pk_bf16_f32 v139, v140, v141
	global_store_dwordx2 v217, v[138:139], s[98:99] offset:96
	v_pk_mul_f32 v[140:141], v[0:1], v[0:1]
	v_pk_fma_f32 v[140:141], v[2:3], v[2:3], v[140:141]
	v_add_f32_e32 v227, v140, v141
	v_add_f32_e32 v226, v226, v227
	ds_bpermute_b32 v64, v229, v223
	ds_bpermute_b32 v80, v229, v224
	ds_bpermute_b32 v98, v229, v225
	ds_bpermute_b32 v126, v229, v226
	s_waitcnt lgkmcnt(0)
	v_add_f32_e32 v223, v223, v64
	v_add_f32_e32 v224, v224, v80
	v_add_f32_e32 v225, v225, v98
	v_add_f32_e32 v226, v226, v126
	ds_bpermute_b32 v64, v244, v223
	ds_bpermute_b32 v80, v244, v224
	ds_bpermute_b32 v98, v244, v225
	ds_bpermute_b32 v126, v244, v226
	s_waitcnt lgkmcnt(0)
	v_add_f32_e32 v223, v223, v64
	v_add_f32_e32 v224, v224, v80
	v_add_f32_e32 v225, v225, v98
	v_add_f32_e32 v226, v226, v126
	s_mov_b64 exec, 0xffff
	global_atomic_add_f32 v222, v223, s[98:99]
	global_atomic_add_f32 v222, v224, s[98:99] offset:64
	global_atomic_add_f32 v222, v225, s[98:99] offset:128
	global_atomic_add_f32 v222, v226, s[98:99] offset:192
	s_mov_b64 exec, -1
	s_mov_b32 s98, 0
	s_branch .LBB0_461

.LBB0_527:
	s_and_b32 s0, s43, 7
	s_lshl_b32 s0, s0, 3
	s_lshr_b32 s1, s3, 3
	s_or_b32 s0, s0, s1
	s_lshl_b32 s44, s0, 7
	v_or_b32_e32 v0, s44, v149
	v_lshl_or_b32 v160, v0, 11, v159
	v_lshl_add_u64 v[30:31], s[22:23], 0, v[160:161]
	v_add_co_u32_e32 v4, vcc, 0x10000, v30
	s_lshl_b32 s1, s43, 4
	s_nop 0
	v_addc_co_u32_e32 v5, vcc, 0, v31, vcc
	s_and_b32 s0, s1, 0x7fffff80
	v_add_co_u32_e32 v12, vcc, 0x20000, v30
	v_or_b32_e32 v0, s0, v149
	s_nop 0
	v_addc_co_u32_e32 v13, vcc, 0, v31, vcc
	v_lshl_or_b32 v24, v0, 11, v159
	v_add_co_u32_e32 v16, vcc, 0x30000, v30
	v_mov_b32_e32 v25, v161
	s_nop 0
	v_addc_co_u32_e32 v17, vcc, 0, v31, vcc
	v_lshl_add_u64 v[52:53], s[16:17], 0, v[24:25]
	v_add_co_u32_e32 v18, vcc, s38, v52
	s_nop 0
	v_addc_co_u32_e32 v19, vcc, 0, v53, vcc
	v_add_co_u32_e32 v28, vcc, s39, v52
	s_nop 0
	v_addc_co_u32_e32 v29, vcc, 0, v53, vcc
	v_add_co_u32_e32 v58, vcc, s40, v52
	s_nop 0
	v_addc_co_u32_e32 v59, vcc, 0, v53, vcc
	s_nop 0
	s_nop 0
	s_nop 0
	s_movk_i32 s1, 0x100
	s_mov_b32 s6, s37
	v_mov_b32_e32 v8, 0
	v_mov_b32_e32 v9, v161
	v_mov_b32_e32 v10, v161
	v_mov_b32_e32 v11, v161
	v_mov_b32_e32 v26, 0
	v_mov_b32_e32 v27, v161
	v_mov_b32_e32 v28, v161
	v_mov_b32_e32 v29, v161
	v_mov_b32_e32 v16, 0
	v_mov_b32_e32 v17, v161
	v_mov_b32_e32 v18, v161
	v_mov_b32_e32 v19, v161
	v_mov_b32_e32 v60, 0
	v_mov_b32_e32 v61, v161
	v_lshl_add_u64 v[58:59], v[52:53], 0, s[14:15]
	v_lshl_add_u64 v[104:105], v[52:53], 0, s[30:31]
	v_lshl_add_u64 v[106:107], v[52:53], 0, s[34:35]
	v_lshl_add_u64 v[108:109], v[30:31], 0, s[14:15]
	v_lshl_add_u64 v[110:111], v[30:31], 0, s[30:31]
	v_lshl_add_u64 v[112:113], v[30:31], 0, s[34:35]
	s_barrier
	v_mov_b32_e32 v88, 0
	v_mov_b32_e32 v89, v161
	v_mov_b32_e32 v90, v161
	v_mov_b32_e32 v91, v161
	v_mov_b32_e32 v76, 0
	v_mov_b32_e32 v77, v161
	v_mov_b32_e32 v78, v161
	v_mov_b32_e32 v79, v161
	v_mov_b32_e32 v80, 0
	v_mov_b32_e32 v81, v161
	v_mov_b32_e32 v82, v161
	v_mov_b32_e32 v83, v161
	v_mov_b32_e32 v84, 0
	v_mov_b32_e32 v85, v161
	v_mov_b32_e32 v86, v161
	v_mov_b32_e32 v87, v161
	v_mov_b32_e32 v74, v161
	v_mov_b32_e32 v75, v161
	v_mov_b32_e32 v62, v161
	v_mov_b32_e32 v63, v161
	v_mov_b32_e32 v36, 0
	v_mov_b32_e32 v37, v161
	v_mov_b32_e32 v38, v161
	v_mov_b32_e32 v39, v161
	v_mov_b32_e32 v54, 0
	v_mov_b32_e32 v55, v161
	v_mov_b32_e32 v56, v161
	v_mov_b32_e32 v57, v161
	v_mov_b32_e32 v32, 0
	v_mov_b32_e32 v33, v161
	v_mov_b32_e32 v34, v161
	v_mov_b32_e32 v35, v161
	v_mov_b32_e32 v64, 0
	v_mov_b32_e32 v65, v161
	v_mov_b32_e32 v66, v161
	v_mov_b32_e32 v67, v161
	v_mov_b32_e32 v40, 0
	v_mov_b32_e32 v41, v161
	v_mov_b32_e32 v42, v161
	v_mov_b32_e32 v43, v161
	v_mov_b32_e32 v48, 0
	v_mov_b32_e32 v49, v161
	v_mov_b32_e32 v50, v161
	v_mov_b32_e32 v51, v161
	v_mov_b32_e32 v68, 0
	v_mov_b32_e32 v69, v161
	v_mov_b32_e32 v70, v161
	v_mov_b32_e32 v71, v161
	v_mov_b32_e32 v72, 0
	v_mov_b32_e32 v73, v161
	v_readlane_b32 s100, v253, 0
	v_readlane_b32 s101, v253, 1
	s_load_dwordx2 s[100:101], s[100:101], 0x160
	v_lshrrev_b32_e32 v7, 6, v146
	s_nop 0
	v_readfirstlane_b32 s8, v7
	v_lshrrev_b32_e32 v5, 3, v146
	v_and_b32_e32 v6, 7, v146
	v_xor_b32_e32 v6, v5, v6
	v_and_b32_e32 v6, 7, v6
	v_lshlrev_b32_e32 v6, 4, v6
	v_lshl_or_b32 v4, v5, 11, v6
	v_add_u32_e32 v5, 0x10000, v4
	v_add_u32_e32 v6, 0x20000, v4
	v_add_u32_e32 v7, 0x30000, v4
	s_and_b32 s98, s43, 7
	s_lshl_b32 s98, s98, 3
	s_and_b32 s99, s69, 7
	s_or_b32 s98, s98, s99
	s_lshl_b32 s98, s98, 18
	s_add_u32 s98, s98, 0xdc40000
	s_lshr_b32 s99, s43, 3
	s_lshl_b32 s99, s99, 18
	s_add_u32 s99, s99, 0x7700000
	s_lshl_b32 s8, s8, 10
	s_waitcnt lgkmcnt(0)
	s_mov_b32 m0, s99
	s_add_u32 s98, s100, s98
	s_addc_u32 s99, s101, 0
	s_add_u32 s100, s100, m0
	s_addc_u32 s101, s101, 0
	s_add_u32 m0, s8, 0x0
	s_nop 0
	global_load_lds_dwordx4 v4, s[98:99]
	s_add_u32 m0, s8, 0x1000
	s_nop 0
	global_load_lds_dwordx4 v5, s[98:99]
	s_add_u32 m0, s8, 0x2000
	s_nop 0
	global_load_lds_dwordx4 v6, s[98:99]
	s_add_u32 m0, s8, 0x3000
	s_nop 0
	global_load_lds_dwordx4 v7, s[98:99]
	s_add_u32 m0, s8, 0x8000
	s_nop 0
	global_load_lds_dwordx4 v4, s[100:101]
	s_add_u32 m0, s8, 0x9000
	s_nop 0
	global_load_lds_dwordx4 v5, s[100:101]
	s_add_u32 m0, s8, 0xa000
	s_nop 0
	global_load_lds_dwordx4 v6, s[100:101]
	s_add_u32 m0, s8, 0xb000
	s_nop 0
	global_load_lds_dwordx4 v7, s[100:101]
	s_add_u32 s98, s98, 0x80
	s_addc_u32 s99, s99, 0
	s_add_u32 s100, s100, 0x80
	s_addc_u32 s101, s101, 0
	s_waitcnt vmcnt(0)
	s_waitcnt lgkmcnt(0)
	s_barrier
	s_bitcmp1_b32 s69, 8
	s_cbranch_scc1 .Lprio_h528
	s_setprio 0
	s_branch .Lprio_j528

.Lprio_j528:
.LBB0_528:
	s_add_i32 s2, s6, 2
	ds_read_b128 v[114:117], v175 offset:32768
	ds_read_b128 v[122:125], v175 offset:34816
	ds_read_b128 v[118:121], v174
	ds_read_b128 v[136:139], v174 offset:2048
	ds_read_b128 v[140:143], v174 offset:4096
	ds_read_b128 v[162:165], v174 offset:6144
	s_waitcnt lgkmcnt(3)
	v_mfma_f32_16x16x32_bf16 v[8:11], v[114:117], v[118:121], v[8:11]
	ds_read_b128 v[166:169], v175 offset:36864
	v_mfma_f32_16x16x32_bf16 v[26:29], v[122:125], v[118:121], v[26:29]
	ds_read_b128 v[182:185], v175 offset:38912
	s_waitcnt lgkmcnt(1)
	v_mfma_f32_16x16x32_bf16 v[16:19], v[166:169], v[118:121], v[16:19]
	s_waitcnt lgkmcnt(0)
	v_mfma_f32_16x16x32_bf16 v[60:63], v[182:185], v[118:121], v[60:63]
	s_add_u32 m0, s8, 0x4000
	s_nop 0
	global_load_lds_dwordx4 v4, s[98:99]
	ds_read_b128 v[186:189], v176
	v_mfma_f32_16x16x32_bf16 v[36:39], v[114:117], v[136:139], v[36:39]
	v_mfma_f32_16x16x32_bf16 v[54:57], v[122:125], v[136:139], v[54:57]
	s_add_u32 m0, s8, 0x5000
	s_nop 0
	global_load_lds_dwordx4 v5, s[98:99]
	ds_read_b128 v[194:197], v176 offset:2048
	v_mfma_f32_16x16x32_bf16 v[32:35], v[166:169], v[136:139], v[32:35]
	v_mfma_f32_16x16x32_bf16 v[64:67], v[182:185], v[136:139], v[64:67]
	s_add_u32 m0, s8, 0x6000
	s_nop 0
	global_load_lds_dwordx4 v6, s[98:99]
	ds_read_b128 v[198:201], v176 offset:4096
	v_mfma_f32_16x16x32_bf16 v[40:43], v[114:117], v[140:143], v[40:43]
	v_mfma_f32_16x16x32_bf16 v[88:91], v[122:125], v[140:143], v[88:91]
	s_add_u32 m0, s8, 0x7000
	s_nop 0
	global_load_lds_dwordx4 v7, s[98:99]
	ds_read_b128 v[206:209], v176 offset:6144
	v_mfma_f32_16x16x32_bf16 v[48:51], v[166:169], v[140:143], v[48:51]
	v_mfma_f32_16x16x32_bf16 v[76:79], v[182:185], v[140:143], v[76:79]
	s_add_u32 m0, s8, 0xc000
	s_nop 0
	global_load_lds_dwordx4 v4, s[100:101]
	ds_read_b128 v[210:213], v177 offset:32768
	v_mfma_f32_16x16x32_bf16 v[80:83], v[114:117], v[162:165], v[80:83]
	v_mfma_f32_16x16x32_bf16 v[84:87], v[122:125], v[162:165], v[84:87]
	s_add_u32 m0, s8, 0xd000
	s_nop 0
	global_load_lds_dwordx4 v5, s[100:101]
	ds_read_b128 v[122:125], v177 offset:34816
	v_mfma_f32_16x16x32_bf16 v[68:71], v[166:169], v[162:165], v[68:71]
	v_mfma_f32_16x16x32_bf16 v[72:75], v[182:185], v[162:165], v[72:75]
	s_add_u32 m0, s8, 0xe000
	s_nop 0
	global_load_lds_dwordx4 v6, s[100:101]
	ds_read_b128 v[166:169], v177 offset:36864
	s_waitcnt lgkmcnt(2)
	v_mfma_f32_16x16x32_bf16 v[8:11], v[210:213], v[186:189], v[8:11]
	s_waitcnt lgkmcnt(1)
	v_mfma_f32_16x16x32_bf16 v[26:29], v[122:125], v[186:189], v[26:29]
	s_add_u32 m0, s8, 0xf000
	s_nop 0
	global_load_lds_dwordx4 v7, s[100:101]
	s_add_u32 s98, s98, 0x80
	s_addc_u32 s99, s99, 0
	s_add_u32 s100, s100, 0x80
	s_addc_u32 s101, s101, 0
	ds_read_b128 v[214:217], v177 offset:38912
	s_waitcnt lgkmcnt(1)
	v_mfma_f32_16x16x32_bf16 v[16:19], v[166:169], v[186:189], v[16:19]
	s_waitcnt lgkmcnt(0)
	v_mfma_f32_16x16x32_bf16 v[60:63], v[214:217], v[186:189], v[60:63]
	v_mfma_f32_16x16x32_bf16 v[36:39], v[210:213], v[194:197], v[36:39]
	v_mfma_f32_16x16x32_bf16 v[54:57], v[122:125], v[194:197], v[54:57]
	v_mfma_f32_16x16x32_bf16 v[32:35], v[166:169], v[194:197], v[32:35]
	v_mfma_f32_16x16x32_bf16 v[64:67], v[214:217], v[194:197], v[64:67]
	v_mfma_f32_16x16x32_bf16 v[40:43], v[210:213], v[198:201], v[40:43]
	v_mfma_f32_16x16x32_bf16 v[88:91], v[122:125], v[198:201], v[88:91]
	v_mfma_f32_16x16x32_bf16 v[48:51], v[166:169], v[198:201], v[48:51]
	v_mfma_f32_16x16x32_bf16 v[76:79], v[214:217], v[198:201], v[76:79]
	v_mfma_f32_16x16x32_bf16 v[80:83], v[210:213], v[206:209], v[80:83]
	v_mfma_f32_16x16x32_bf16 v[84:87], v[122:125], v[206:209], v[84:87]
	v_mfma_f32_16x16x32_bf16 v[68:71], v[166:169], v[206:209], v[68:71]
	v_mfma_f32_16x16x32_bf16 v[72:75], v[214:217], v[206:209], v[72:75]
	s_waitcnt vmcnt(0) lgkmcnt(0)
	s_barrier
	ds_read_b128 v[92:95], v175 offset:49152
	ds_read_b128 v[96:99], v175 offset:51200
	ds_read_b128 v[0:3], v174 offset:16384
	ds_read_b128 v[12:15], v174 offset:18432
	ds_read_b128 v[20:23], v174 offset:20480
	ds_read_b128 v[100:103], v174 offset:22528
	s_waitcnt lgkmcnt(3)
	v_mfma_f32_16x16x32_bf16 v[8:11], v[92:95], v[0:3], v[8:11]
	ds_read_b128 v[122:125], v175 offset:53248
	v_mfma_f32_16x16x32_bf16 v[26:29], v[96:99], v[0:3], v[26:29]
	ds_read_b128 v[166:169], v175 offset:55296
	s_waitcnt lgkmcnt(1)
	v_mfma_f32_16x16x32_bf16 v[16:19], v[122:125], v[0:3], v[16:19]
	s_waitcnt lgkmcnt(0)
	v_mfma_f32_16x16x32_bf16 v[60:63], v[166:169], v[0:3], v[60:63]
	s_add_u32 m0, s8, 0x0
	s_nop 0
	global_load_lds_dwordx4 v4, s[98:99]
	ds_read_b128 v[186:189], v176 offset:16384
	v_mfma_f32_16x16x32_bf16 v[36:39], v[92:95], v[12:15], v[36:39]
	v_mfma_f32_16x16x32_bf16 v[54:57], v[96:99], v[12:15], v[54:57]
	s_add_u32 m0, s8, 0x1000
	s_nop 0
	global_load_lds_dwordx4 v5, s[98:99]
	ds_read_b128 v[194:197], v176 offset:18432
	v_mfma_f32_16x16x32_bf16 v[32:35], v[122:125], v[12:15], v[32:35]
	v_mfma_f32_16x16x32_bf16 v[64:67], v[166:169], v[12:15], v[64:67]
	s_add_u32 m0, s8, 0x2000
	s_nop 0
	global_load_lds_dwordx4 v6, s[98:99]
	ds_read_b128 v[198:201], v176 offset:20480
	v_mfma_f32_16x16x32_bf16 v[40:43], v[92:95], v[20:23], v[40:43]
	v_mfma_f32_16x16x32_bf16 v[88:91], v[96:99], v[20:23], v[88:91]
	s_add_u32 m0, s8, 0x3000
	s_nop 0
	global_load_lds_dwordx4 v7, s[98:99]
	ds_read_b128 v[206:209], v176 offset:22528
	v_mfma_f32_16x16x32_bf16 v[48:51], v[122:125], v[20:23], v[48:51]
	v_mfma_f32_16x16x32_bf16 v[76:79], v[166:169], v[20:23], v[76:79]
	s_add_u32 m0, s8, 0x8000
	s_nop 0
	global_load_lds_dwordx4 v4, s[100:101]
	ds_read_b128 v[210:213], v177 offset:49152
	v_mfma_f32_16x16x32_bf16 v[80:83], v[92:95], v[100:103], v[80:83]
	v_mfma_f32_16x16x32_bf16 v[84:87], v[96:99], v[100:103], v[84:87]
	s_add_u32 m0, s8, 0x9000
	s_nop 0
	global_load_lds_dwordx4 v5, s[100:101]
	ds_read_b128 v[214:217], v177 offset:51200
	v_mfma_f32_16x16x32_bf16 v[68:71], v[122:125], v[100:103], v[68:71]
	v_mfma_f32_16x16x32_bf16 v[72:75], v[166:169], v[100:103], v[72:75]
	s_add_u32 m0, s8, 0xa000
	s_nop 0
	global_load_lds_dwordx4 v6, s[100:101]
	ds_read_b128 v[122:125], v177 offset:53248
	s_waitcnt lgkmcnt(2)
	v_mfma_f32_16x16x32_bf16 v[8:11], v[210:213], v[186:189], v[8:11]
	s_waitcnt lgkmcnt(1)
	v_mfma_f32_16x16x32_bf16 v[26:29], v[214:217], v[186:189], v[26:29]
	s_add_u32 m0, s8, 0xb000
	s_nop 0
	global_load_lds_dwordx4 v7, s[100:101]
	s_add_u32 s98, s98, 0x80
	s_addc_u32 s99, s99, 0
	s_add_u32 s100, s100, 0x80
	s_addc_u32 s101, s101, 0
	ds_read_b128 v[166:169], v177 offset:55296
	s_waitcnt lgkmcnt(1)
	v_mfma_f32_16x16x32_bf16 v[16:19], v[122:125], v[186:189], v[16:19]
	s_waitcnt lgkmcnt(0)
	v_mfma_f32_16x16x32_bf16 v[60:63], v[166:169], v[186:189], v[60:63]
	v_mfma_f32_16x16x32_bf16 v[36:39], v[210:213], v[194:197], v[36:39]
	v_mfma_f32_16x16x32_bf16 v[54:57], v[214:217], v[194:197], v[54:57]
	v_mfma_f32_16x16x32_bf16 v[32:35], v[122:125], v[194:197], v[32:35]
	v_mfma_f32_16x16x32_bf16 v[64:67], v[166:169], v[194:197], v[64:67]
	v_mfma_f32_16x16x32_bf16 v[40:43], v[210:213], v[198:201], v[40:43]
	v_mfma_f32_16x16x32_bf16 v[88:91], v[214:217], v[198:201], v[88:91]
	v_mfma_f32_16x16x32_bf16 v[48:51], v[122:125], v[198:201], v[48:51]
	v_mfma_f32_16x16x32_bf16 v[76:79], v[166:169], v[198:201], v[76:79]
	v_mfma_f32_16x16x32_bf16 v[80:83], v[210:213], v[206:209], v[80:83]
	v_mfma_f32_16x16x32_bf16 v[84:87], v[214:217], v[206:209], v[84:87]
	v_mfma_f32_16x16x32_bf16 v[68:71], v[122:125], v[206:209], v[68:71]
	v_mfma_f32_16x16x32_bf16 v[72:75], v[166:169], v[206:209], v[72:75]
	s_mov_b32 s6, s2
	s_waitcnt vmcnt(0) lgkmcnt(0)
	s_barrier
	s_cmp_lt_u32 s6, 16
	s_cbranch_scc1 .LBB0_528
	s_setprio 0
	s_waitcnt vmcnt(5)
	v_add_u32_e32 v15, s44, v173
	v_or_b32_e32 v181, v15, v148
	v_or_b32_e32 v160, s0, v234
	s_add_i32 s0, s44, 0xfffff000
	v_lshlrev_b32_e32 v0, 2, v181
	s_ashr_i32 s0, s0, 10
	global_load_dword v14, v0, s[28:29]
	global_load_dword v30, v0, s[28:29] offset:64
	global_load_dword v31, v0, s[28:29] offset:128
	global_load_dword v44, v0, s[28:29] offset:192
	s_add_i32 s2, s0, 6
	s_and_b64 s[0:1], s[24:25], exec
	s_cselect_b32 s0, 5, s2
	s_mul_hi_u32 s1, s0, 0x4200
	s_mulk_i32 s0, 0x4200
	s_add_u32 s0, s4, s0
	s_addc_u32 s1, s5, s1
	v_mov_b32_e32 v135, v161
	v_lshl_add_u64 v[0:1], v[160:161], 2, s[0:1]
	v_lshl_add_u64 v[4:5], v[0:1], 0, v[134:135]
	global_load_dwordx4 v[22:25], v[4:5], off
	global_load_dwordx4 v[0:3], v[4:5], off offset:64
	global_load_dwordx4 v[92:95], v[4:5], off offset:128
	s_nop 0
	global_load_dwordx4 v[4:7], v[4:5], off offset:192
	v_mov_b32_e32 v12, v26
	v_mov_b32_e32 v13, v9
	v_mov_b32_e32 v9, v27
	s_waitcnt vmcnt(11)
	v_mov_b32_e32 v20, v54
	v_mov_b32_e32 v21, v37
	v_mov_b32_e32 v37, v55
	s_cmpk_lt_u32 s43, 0x80
	s_waitcnt vmcnt(7)
	v_fmamk_f32 v14, v14, 0x3a800000, v179
	s_waitcnt vmcnt(6)
	v_fmamk_f32 v26, v30, 0x3a800000, v179
	v_cmp_gt_f32_e64 s[6:7], s41, v26
	s_waitcnt vmcnt(4)
	v_fmamk_f32 v30, v44, 0x3a800000, v179
	v_mul_f32_e32 v44, 0x4b800000, v26
	v_fmamk_f32 v27, v31, 0x3a800000, v179
	v_mul_f32_e32 v46, 0x4b800000, v30
	v_cndmask_b32_e64 v26, v26, v44, s[6:7]
	v_cmp_gt_f32_e64 s[10:11], s41, v30
	v_mul_f32_e32 v31, 0x4b800000, v14
	v_mul_f32_e32 v45, 0x4b800000, v27
	v_cmp_gt_f32_e32 vcc, s41, v14
	v_cmp_gt_f32_e64 s[8:9], s41, v27
	v_cndmask_b32_e64 v30, v30, v46, s[10:11]
	v_rsq_f32_e32 v26, v26
	v_cndmask_b32_e32 v14, v14, v31, vcc
	v_cndmask_b32_e64 v27, v27, v45, s[8:9]
	v_rsq_f32_e32 v30, v30
	v_rsq_f32_e32 v14, v14
	v_rsq_f32_e32 v27, v27
	s_waitcnt vmcnt(2)
	v_mov_b32_e32 v97, v3
	v_mul_f32_e32 v3, 0x45800000, v26
	v_mov_b32_e32 v96, v25
	v_mul_f32_e32 v25, 0x45800000, v30
	v_cndmask_b32_e64 v102, v26, v3, s[6:7]
	v_mul_f32_e32 v31, 0x45800000, v14
	s_waitcnt vmcnt(0)
	v_mov_b32_e32 v99, v7
	v_mul_f32_e32 v7, 0x45800000, v27
	v_cndmask_b32_e64 v106, v30, v25, s[10:11]
	v_fma_f32 v30, v56, v102, v2
	v_mov_b32_e32 v56, v39
	v_mov_b32_e32 v53, v1
	v_mov_b32_e32 v1, v23
	v_cndmask_b32_e32 v100, v14, v31, vcc
	v_cndmask_b32_e64 v104, v27, v7, s[8:9]
	v_pk_fma_f32 v[140:141], v[56:57], v[102:103], v[96:97] op_sel_hi:[1,0,1]
	v_mov_b32_e32 v56, v88
	v_mov_b32_e32 v57, v41
	v_mov_b32_e32 v98, v95
	v_mov_b32_e32 v52, v22
	v_fma_f32 v14, v28, v100, v2
	v_mov_b32_e32 v28, v11
	v_fma_f32 v26, v38, v102, v24
	v_fma_f32 v38, v66, v102, v6
	v_mov_b32_e32 v66, v35
	v_mov_b32_e32 v41, v89
	v_pk_fma_f32 v[162:163], v[56:57], v[104:105], v[0:1] op_sel_hi:[1,0,1]
	v_mov_b32_e32 v56, v80
	v_mov_b32_e32 v57, v85
	v_mov_b32_e32 v85, v81
	v_fma_f32 v10, v10, v100, v24
	v_fma_f32 v42, v42, v104, v24
	v_fma_f32 v58, v82, v106, v24
	v_pk_fma_f32 v[8:9], v[8:9], v[100:101], v[52:53] op_sel_hi:[1,0,1]
	v_pk_fma_f32 v[136:137], v[12:13], v[100:101], v[0:1] op_sel_hi:[1,0,1]
	v_pk_fma_f32 v[24:25], v[36:37], v[102:103], v[52:53] op_sel_hi:[1,0,1]
	v_pk_fma_f32 v[20:21], v[20:21], v[102:103], v[0:1] op_sel_hi:[1,0,1]
	v_pk_fma_f32 v[138:139], v[28:29], v[100:101], v[96:97] op_sel_hi:[1,0,1]
	v_pk_fma_f32 v[28:29], v[66:67], v[102:103], v[98:99] op_sel_hi:[1,0,1]
	v_pk_fma_f32 v[40:41], v[40:41], v[104:105], v[52:53] op_sel_hi:[1,0,1]
	v_pk_fma_f32 v[56:57], v[56:57], v[106:107], v[52:53] op_sel_hi:[1,0,1]
	v_pk_fma_f32 v[52:53], v[84:85], v[106:107], v[0:1] op_sel_hi:[1,0,1]
	v_mov_b32_e32 v0, v60
	v_mov_b32_e32 v1, v17
	v_mov_b32_e32 v66, v4
	v_mov_b32_e32 v67, v93
	v_pk_fma_f32 v[142:143], v[0:1], v[100:101], v[66:67] op_sel_hi:[1,0,1]
	v_mov_b32_e32 v0, v64
	v_mov_b32_e32 v1, v33
	v_pk_fma_f32 v[164:165], v[0:1], v[102:103], v[66:67] op_sel_hi:[1,0,1]
	v_mov_b32_e32 v0, v76
	v_mov_b32_e32 v1, v49
	v_fma_f32 v22, v62, v100, v6
	v_mov_b32_e32 v62, v19
	v_fma_f32 v46, v90, v104, v2
	v_mov_b32_e32 v90, v43
	v_fma_f32 v54, v78, v104, v6
	v_mov_b32_e32 v78, v51
	v_fmac_f32_e32 v2, v86, v106
	v_mov_b32_e32 v86, v83
	v_mov_b32_e32 v17, v61
	v_mov_b32_e32 v93, v5
	v_mov_b32_e32 v33, v65
	v_pk_fma_f32 v[168:169], v[0:1], v[104:105], v[66:67] op_sel_hi:[1,0,1]
	v_mov_b32_e32 v49, v77
	v_mov_b32_e32 v0, v68
	v_mov_b32_e32 v1, v73
	v_mov_b32_e32 v73, v69
	v_fmac_f32_e32 v6, v74, v106
	v_mov_b32_e32 v74, v71
	s_cselect_b64 s[8:9], -1, 0
	s_and_b32 s0, s43, 0x7fffffc0
	v_fma_f32 v18, v18, v100, v94
	v_fma_f32 v34, v34, v102, v94
	v_fma_f32 v50, v50, v104, v94
	v_pk_fma_f32 v[12:13], v[62:63], v[100:101], v[98:99] op_sel_hi:[1,0,1]
	v_pk_fma_f32 v[36:37], v[90:91], v[104:105], v[96:97] op_sel_hi:[1,0,1]
	v_pk_fma_f32 v[44:45], v[78:79], v[104:105], v[98:99] op_sel_hi:[1,0,1]
	v_pk_fma_f32 v[166:167], v[86:87], v[106:107], v[96:97] op_sel_hi:[1,0,1]
	v_fma_f32 v62, v70, v106, v94
	v_pk_fma_f32 v[16:17], v[16:17], v[100:101], v[92:93] op_sel_hi:[1,0,1]
	v_pk_fma_f32 v[32:33], v[32:33], v[102:103], v[92:93] op_sel_hi:[1,0,1]
	v_pk_fma_f32 v[48:49], v[48:49], v[104:105], v[92:93] op_sel_hi:[1,0,1]
	v_pk_fma_f32 v[60:61], v[0:1], v[106:107], v[92:93] op_sel_hi:[1,0,1]
	v_pk_fma_f32 v[0:1], v[72:73], v[106:107], v[66:67] op_sel_hi:[1,0,1]
	v_pk_fma_f32 v[170:171], v[74:75], v[106:107], v[98:99] op_sel_hi:[1,0,1]
	s_cmpk_lg_i32 s0, 0x80
	s_mov_b64 s[6:7], -1
	s_cbranch_scc0 .LBB0_543
	v_lshlrev_b32_e32 v3, 1, v15
	s_and_b64 s[0:1], s[26:27], s[8:9]
	v_and_b32_e32 v4, 0x780, v3
	v_mov_b32_e32 v5, v161
	v_cndmask_b32_e64 v3, 0, 1, s[0:1]
	v_cmp_ne_u32_e64 s[6:7], 1, v3
	s_andn2_b64 vcc, exec, s[0:1]
	v_lshl_add_u64 v[112:113], v[130:131], 0, v[4:5]
	s_cbranch_vccnz .LBB0_532
	v_lshlrev_b32_e32 v3, 7, v181
	global_load_dwordx4 v[64:67], v[112:113], off
	global_load_dwordx4 v[68:71], v[112:113], off offset:16
	v_mov_b32_e32 v5, v161
	v_and_b32_e32 v4, 0x780, v3
	v_lshl_add_u64 v[4:5], v[130:131], 0, v[4:5]
	global_load_dwordx4 v[72:75], v[4:5], off
	global_load_dwordx4 v[76:79], v[4:5], off offset:16
	v_mov_b32_e32 v4, v136
	v_mov_b32_e32 v5, v9
	v_mov_b32_e32 v80, v8
	v_mov_b32_e32 v81, v137
	v_mov_b32_e32 v82, v142
	v_mov_b32_e32 v83, v17
	v_mov_b32_e32 v84, v16
	v_mov_b32_e32 v85, v143
	s_waitcnt vmcnt(3)
	v_mov_b32_e32 v86, v65
	v_mov_b32_e32 v87, v66
	v_mov_b32_e32 v88, v64
	v_mov_b32_e32 v89, v67
	v_mov_b32_e32 v90, v65
	v_mov_b32_e32 v91, v67
	v_mov_b32_e32 v65, v66
	s_waitcnt vmcnt(2)
	v_mul_f32_e32 v66, v10, v68
	v_mul_f32_e32 v92, v14, v69
	v_mul_f32_e32 v94, v14, v68
	v_mul_f32_e32 v96, v10, v69
	v_pk_mul_f32 v[68:69], v[138:139], v[70:71]
	v_pk_mul_f32 v[88:89], v[136:137], v[88:89]
	v_pk_mul_f32 v[4:5], v[4:5], v[90:91]
	v_mov_b32_e32 v67, v68
	v_mov_b32_e32 v93, v69
	v_pk_mul_f32 v[70:71], v[138:139], v[70:71] op_sel:[1,0] op_sel_hi:[0,1]
	v_pk_fma_f32 v[64:65], v[80:81], v[64:65], v[4:5] neg_lo:[0,0,1] neg_hi:[0,0,1]
	v_pk_add_f32 v[66:67], v[66:67], v[92:93] neg_lo:[0,1] neg_hi:[0,1]
	v_pk_fma_f32 v[68:69], v[8:9], v[86:87], v[88:89]
	s_waitcnt vmcnt(1)
	v_mov_b32_e32 v4, v73
	v_mov_b32_e32 v5, v74
	v_mov_b32_e32 v80, v72
	v_mov_b32_e32 v81, v75
	v_mov_b32_e32 v86, v73
	v_mov_b32_e32 v87, v75
	v_mov_b32_e32 v73, v74
	s_waitcnt vmcnt(0)
	v_mul_f32_e32 v74, v18, v76
	v_mul_f32_e32 v88, v22, v77
	v_mul_f32_e32 v90, v22, v76
	v_mul_f32_e32 v92, v18, v77
	v_pk_mul_f32 v[76:77], v[12:13], v[78:79]
	v_pk_mul_f32 v[78:79], v[12:13], v[78:79] op_sel:[1,0] op_sel_hi:[0,1]
	v_mov_b32_e32 v95, v70
	v_mov_b32_e32 v97, v71
	v_pk_mul_f32 v[80:81], v[142:143], v[80:81]
	v_pk_mul_f32 v[82:83], v[82:83], v[86:87]
	v_mov_b32_e32 v75, v76
	v_mov_b32_e32 v89, v77
	v_mov_b32_e32 v91, v78
	v_mov_b32_e32 v93, v79
	v_pk_add_f32 v[70:71], v[94:95], v[96:97]
	v_pk_fma_f32 v[72:73], v[84:85], v[72:73], v[82:83] neg_lo:[0,0,1] neg_hi:[0,0,1]
	v_pk_add_f32 v[74:75], v[74:75], v[88:89] neg_lo:[0,1] neg_hi:[0,1]
	v_pk_fma_f32 v[76:77], v[16:17], v[4:5], v[80:81]
	v_pk_add_f32 v[78:79], v[90:91], v[92:93]
	s_branch .LBB0_533

.LBB0_675:
	s_and_b32 s0, s9, 7
	s_or_b32 s0, s0, s3
	s_lshl_b32 s1, s0, 7
	v_or_b32_e32 v0, s1, v149
	v_lshl_or_b32 v96, v0, 11, v116
	s_waitcnt vmcnt(1)
	v_lshl_add_u64 v[100:101], s[18:19], 0, v[96:97]
	v_add_co_u32_e32 v12, vcc, 0x10000, v100
	s_lshl_b32 s2, s9, 4
	s_nop 0
	v_addc_co_u32_e32 v13, vcc, 0, v101, vcc
	s_and_b32 s0, s2, 0x7fffff80
	v_add_co_u32_e32 v26, vcc, 0x20000, v100
	v_or_b32_e32 v0, s0, v149
	s_nop 0
	v_addc_co_u32_e32 v27, vcc, 0, v101, vcc
	v_lshl_or_b32 v98, v0, 11, v116
	v_add_co_u32_e32 v28, vcc, 0x30000, v100
	v_mov_b32_e32 v99, v97
	s_nop 0
	v_addc_co_u32_e32 v29, vcc, 0, v101, vcc
	v_lshl_add_u64 v[102:103], s[16:17], 0, v[98:99]
	v_add_co_u32_e32 v30, vcc, s6, v102
	s_waitcnt lgkmcnt(0)
	v_addc_co_u32_e32 v31, vcc, 0, v103, vcc
	v_add_co_u32_e32 v42, vcc, s7, v102
	s_nop 0
	v_addc_co_u32_e32 v43, vcc, 0, v103, vcc
	v_add_co_u32_e32 v44, vcc, s8, v102
	s_nop 0
	v_addc_co_u32_e32 v45, vcc, 0, v103, vcc
	s_movk_i32 s2, 0x100
	s_mov_b32 s42, s29
	v_mov_b32_e32 v64, 0
	v_mov_b32_e32 v65, v97
	v_mov_b32_e32 v66, v97
	v_mov_b32_e32 v67, v97
	v_mov_b32_e32 v40, 0
	v_mov_b32_e32 v41, v97
	v_mov_b32_e32 v42, v97
	v_mov_b32_e32 v43, v97
	v_mov_b32_e32 v28, 0
	v_mov_b32_e32 v29, v97
	v_mov_b32_e32 v30, v97
	v_mov_b32_e32 v31, v97
	v_mov_b32_e32 v12, 0
	v_mov_b32_e32 v13, v97
	v_lshl_add_u64 v[104:105], v[102:103], 0, s[30:31]
	v_lshl_add_u64 v[106:107], v[102:103], 0, s[34:35]
	v_lshl_add_u64 v[108:109], v[102:103], 0, s[36:37]
	v_lshl_add_u64 v[110:111], v[100:101], 0, s[30:31]
	v_lshl_add_u64 v[112:113], v[100:101], 0, s[34:35]
	v_lshl_add_u64 v[114:115], v[100:101], 0, s[36:37]
	s_waitcnt lgkmcnt(0)
	s_barrier
	v_mov_b32_e32 v60, 0
	v_mov_b32_e32 v61, v97
	v_mov_b32_e32 v62, v97
	v_mov_b32_e32 v63, v97
	v_mov_b32_e32 v44, 0
	v_mov_b32_e32 v45, v97
	v_mov_b32_e32 v46, v97
	v_mov_b32_e32 v47, v97
	v_mov_b32_e32 v26, v97
	v_mov_b32_e32 v27, v97
	v_mov_b32_e32 v52, 0
	v_mov_b32_e32 v53, v97
	v_mov_b32_e32 v54, v97
	v_mov_b32_e32 v55, v97
	v_mov_b32_e32 v48, 0
	v_mov_b32_e32 v49, v97
	v_mov_b32_e32 v50, v97
	v_mov_b32_e32 v51, v97
	v_mov_b32_e32 v14, v97
	v_mov_b32_e32 v15, v97
	v_mov_b32_e32 v24, 0
	v_mov_b32_e32 v25, v97
	v_mov_b32_e32 v8, 0
	v_mov_b32_e32 v9, v97
	v_mov_b32_e32 v10, v97
	v_mov_b32_e32 v11, v97
	v_mov_b32_e32 v36, 0
	v_mov_b32_e32 v37, v97
	v_mov_b32_e32 v38, v97
	v_mov_b32_e32 v39, v97
	v_mov_b32_e32 v20, 0
	v_mov_b32_e32 v21, v97
	v_mov_b32_e32 v22, v97
	v_mov_b32_e32 v23, v97
	v_mov_b32_e32 v4, 0
	v_mov_b32_e32 v5, v97
	v_mov_b32_e32 v6, v97
	v_mov_b32_e32 v7, v97
	v_mov_b32_e32 v32, 0
	v_mov_b32_e32 v33, v97
	v_mov_b32_e32 v34, v97
	v_mov_b32_e32 v35, v97
	v_mov_b32_e32 v16, 0
	v_mov_b32_e32 v17, v97
	v_mov_b32_e32 v18, v97
	v_mov_b32_e32 v19, v97
	v_mov_b32_e32 v0, 0
	v_mov_b32_e32 v1, v97
	v_mov_b32_e32 v2, v97
	v_mov_b32_e32 v3, v97
	v_readlane_b32 s100, v253, 0
	v_readlane_b32 s101, v253, 1
	s_load_dwordx2 s[100:101], s[100:101], 0x160
	v_lshrrev_b32_e32 v71, 6, v146
	s_nop 0
	v_readfirstlane_b32 s44, v71
	v_lshrrev_b32_e32 v69, 3, v146
	v_and_b32_e32 v70, 7, v146
	v_xor_b32_e32 v70, v69, v70
	v_and_b32_e32 v70, 7, v70
	v_lshlrev_b32_e32 v70, 4, v70
	v_lshl_or_b32 v68, v69, 11, v70
	v_add_u32_e32 v69, 0x10000, v68
	v_add_u32_e32 v70, 0x20000, v68
	v_add_u32_e32 v71, 0x30000, v68
	s_and_b32 s98, s9, 7
	s_and_b32 s99, s69, 7
	s_lshl_b32 s99, s99, 3
	s_or_b32 s98, s98, s99
	s_lshl_b32 s98, s98, 18
	s_add_u32 s98, s98, 0x2000000
	s_lshr_b32 s99, s9, 3
	s_lshl_b32 s99, s99, 18
	s_add_u32 s99, s99, 0x8e40000
	s_lshl_b32 s44, s44, 10
	s_waitcnt lgkmcnt(0)
	s_mov_b32 m0, s99
	s_add_u32 s98, s100, s98
	s_addc_u32 s99, s101, 0
	s_add_u32 s100, s100, m0
	s_addc_u32 s101, s101, 0
	s_add_u32 m0, s44, 0x0
	s_nop 0
	global_load_lds_dwordx4 v68, s[98:99]
	s_add_u32 m0, s44, 0x1000
	s_nop 0
	global_load_lds_dwordx4 v69, s[98:99]
	s_add_u32 m0, s44, 0x2000
	s_nop 0
	global_load_lds_dwordx4 v70, s[98:99]
	s_add_u32 m0, s44, 0x3000
	s_nop 0
	global_load_lds_dwordx4 v71, s[98:99]
	s_add_u32 m0, s44, 0x8000
	s_nop 0
	global_load_lds_dwordx4 v68, s[100:101]
	s_add_u32 m0, s44, 0x9000
	s_nop 0
	global_load_lds_dwordx4 v69, s[100:101]
	s_add_u32 m0, s44, 0xa000
	s_nop 0
	global_load_lds_dwordx4 v70, s[100:101]
	s_add_u32 m0, s44, 0xb000
	s_nop 0
	global_load_lds_dwordx4 v71, s[100:101]
	s_add_u32 s98, s98, 0x80
	s_addc_u32 s99, s99, 0
	s_add_u32 s100, s100, 0x80
	s_addc_u32 s101, s101, 0
	s_waitcnt vmcnt(0)
	s_waitcnt lgkmcnt(0)
	s_barrier
	s_bitcmp1_b32 s69, 8
	s_cbranch_scc1 .Lprio_h676
	s_setprio 0
	s_branch .Lprio_j676

.Lprio_j676:
.LBB0_676:
	s_add_i32 s33, s42, 2
	ds_read_b128 v[126:129], v119 offset:32768
	ds_read_b128 v[134:137], v119 offset:34816
	ds_read_b128 v[130:133], v118
	ds_read_b128 v[138:141], v118 offset:2048
	ds_read_b128 v[162:165], v118 offset:4096
	ds_read_b128 v[166:169], v118 offset:6144
	s_waitcnt lgkmcnt(3)
	v_mfma_f32_16x16x32_bf16 v[64:67], v[126:129], v[130:133], v[64:67]
	ds_read_b128 v[170:173], v119 offset:36864
	v_mfma_f32_16x16x32_bf16 v[40:43], v[134:137], v[130:133], v[40:43]
	ds_read_b128 v[174:177], v119 offset:38912
	s_waitcnt lgkmcnt(1)
	v_mfma_f32_16x16x32_bf16 v[28:31], v[170:173], v[130:133], v[28:31]
	s_waitcnt lgkmcnt(0)
	v_mfma_f32_16x16x32_bf16 v[12:15], v[174:177], v[130:133], v[12:15]
	s_add_u32 m0, s44, 0x4000
	s_nop 0
	global_load_lds_dwordx4 v68, s[98:99]
	ds_read_b128 v[178:181], v120
	v_mfma_f32_16x16x32_bf16 v[60:63], v[126:129], v[138:141], v[60:63]
	v_mfma_f32_16x16x32_bf16 v[44:47], v[134:137], v[138:141], v[44:47]
	s_add_u32 m0, s44, 0x5000
	s_nop 0
	global_load_lds_dwordx4 v69, s[98:99]
	ds_read_b128 v[186:189], v120 offset:2048
	v_mfma_f32_16x16x32_bf16 v[24:27], v[170:173], v[138:141], v[24:27]
	v_mfma_f32_16x16x32_bf16 v[8:11], v[174:177], v[138:141], v[8:11]
	s_add_u32 m0, s44, 0x6000
	s_nop 0
	global_load_lds_dwordx4 v70, s[98:99]
	ds_read_b128 v[190:193], v120 offset:4096
	v_mfma_f32_16x16x32_bf16 v[52:55], v[126:129], v[162:165], v[52:55]
	v_mfma_f32_16x16x32_bf16 v[36:39], v[134:137], v[162:165], v[36:39]
	s_add_u32 m0, s44, 0x7000
	s_nop 0
	global_load_lds_dwordx4 v71, s[98:99]
	ds_read_b128 v[198:201], v120 offset:6144
	v_mfma_f32_16x16x32_bf16 v[20:23], v[170:173], v[162:165], v[20:23]
	v_mfma_f32_16x16x32_bf16 v[4:7], v[174:177], v[162:165], v[4:7]
	s_add_u32 m0, s44, 0xc000
	s_nop 0
	global_load_lds_dwordx4 v68, s[100:101]
	ds_read_b128 v[202:205], v121 offset:32768
	v_mfma_f32_16x16x32_bf16 v[48:51], v[126:129], v[166:169], v[48:51]
	v_mfma_f32_16x16x32_bf16 v[32:35], v[134:137], v[166:169], v[32:35]
	s_add_u32 m0, s44, 0xd000
	s_nop 0
	global_load_lds_dwordx4 v69, s[100:101]
	ds_read_b128 v[134:137], v121 offset:34816
	v_mfma_f32_16x16x32_bf16 v[16:19], v[170:173], v[166:169], v[16:19]
	v_mfma_f32_16x16x32_bf16 v[0:3], v[174:177], v[166:169], v[0:3]
	s_add_u32 m0, s44, 0xe000
	s_nop 0
	global_load_lds_dwordx4 v70, s[100:101]
	ds_read_b128 v[170:173], v121 offset:36864
	s_waitcnt lgkmcnt(2)
	v_mfma_f32_16x16x32_bf16 v[64:67], v[202:205], v[178:181], v[64:67]
	s_waitcnt lgkmcnt(1)
	v_mfma_f32_16x16x32_bf16 v[40:43], v[134:137], v[178:181], v[40:43]
	s_add_u32 m0, s44, 0xf000
	s_nop 0
	global_load_lds_dwordx4 v71, s[100:101]
	s_add_u32 s98, s98, 0x80
	s_addc_u32 s99, s99, 0
	s_add_u32 s100, s100, 0x80
	s_addc_u32 s101, s101, 0
	ds_read_b128 v[206:209], v121 offset:38912
	s_waitcnt lgkmcnt(1)
	v_mfma_f32_16x16x32_bf16 v[28:31], v[170:173], v[178:181], v[28:31]
	s_waitcnt lgkmcnt(0)
	v_mfma_f32_16x16x32_bf16 v[12:15], v[206:209], v[178:181], v[12:15]
	v_mfma_f32_16x16x32_bf16 v[60:63], v[202:205], v[186:189], v[60:63]
	v_mfma_f32_16x16x32_bf16 v[44:47], v[134:137], v[186:189], v[44:47]
	v_mfma_f32_16x16x32_bf16 v[24:27], v[170:173], v[186:189], v[24:27]
	v_mfma_f32_16x16x32_bf16 v[8:11], v[206:209], v[186:189], v[8:11]
	v_mfma_f32_16x16x32_bf16 v[52:55], v[202:205], v[190:193], v[52:55]
	v_mfma_f32_16x16x32_bf16 v[36:39], v[134:137], v[190:193], v[36:39]
	v_mfma_f32_16x16x32_bf16 v[20:23], v[170:173], v[190:193], v[20:23]
	v_mfma_f32_16x16x32_bf16 v[4:7], v[206:209], v[190:193], v[4:7]
	v_mfma_f32_16x16x32_bf16 v[48:51], v[202:205], v[198:201], v[48:51]
	v_mfma_f32_16x16x32_bf16 v[32:35], v[134:137], v[198:201], v[32:35]
	v_mfma_f32_16x16x32_bf16 v[16:19], v[170:173], v[198:201], v[16:19]
	v_mfma_f32_16x16x32_bf16 v[0:3], v[206:209], v[198:201], v[0:3]
	s_waitcnt vmcnt(0) lgkmcnt(0)
	s_barrier
	ds_read_b128 v[84:87], v119 offset:49152
	ds_read_b128 v[88:91], v119 offset:51200
	ds_read_b128 v[56:59], v118 offset:16384
	ds_read_b128 v[72:75], v118 offset:18432
	ds_read_b128 v[76:79], v118 offset:20480
	ds_read_b128 v[92:95], v118 offset:22528
	s_waitcnt lgkmcnt(3)
	v_mfma_f32_16x16x32_bf16 v[64:67], v[84:87], v[56:59], v[64:67]
	ds_read_b128 v[134:137], v119 offset:53248
	v_mfma_f32_16x16x32_bf16 v[40:43], v[88:91], v[56:59], v[40:43]
	ds_read_b128 v[170:173], v119 offset:55296
	s_waitcnt lgkmcnt(1)
	v_mfma_f32_16x16x32_bf16 v[28:31], v[134:137], v[56:59], v[28:31]
	s_waitcnt lgkmcnt(0)
	v_mfma_f32_16x16x32_bf16 v[12:15], v[170:173], v[56:59], v[12:15]
	s_add_u32 m0, s44, 0x0
	s_nop 0
	global_load_lds_dwordx4 v68, s[98:99]
	ds_read_b128 v[178:181], v120 offset:16384
	v_mfma_f32_16x16x32_bf16 v[60:63], v[84:87], v[72:75], v[60:63]
	v_mfma_f32_16x16x32_bf16 v[44:47], v[88:91], v[72:75], v[44:47]
	s_add_u32 m0, s44, 0x1000
	s_nop 0
	global_load_lds_dwordx4 v69, s[98:99]
	ds_read_b128 v[186:189], v120 offset:18432
	v_mfma_f32_16x16x32_bf16 v[24:27], v[134:137], v[72:75], v[24:27]
	v_mfma_f32_16x16x32_bf16 v[8:11], v[170:173], v[72:75], v[8:11]
	s_add_u32 m0, s44, 0x2000
	s_nop 0
	global_load_lds_dwordx4 v70, s[98:99]
	ds_read_b128 v[190:193], v120 offset:20480
	v_mfma_f32_16x16x32_bf16 v[52:55], v[84:87], v[76:79], v[52:55]
	v_mfma_f32_16x16x32_bf16 v[36:39], v[88:91], v[76:79], v[36:39]
	s_add_u32 m0, s44, 0x3000
	s_nop 0
	global_load_lds_dwordx4 v71, s[98:99]
	ds_read_b128 v[198:201], v120 offset:22528
	v_mfma_f32_16x16x32_bf16 v[20:23], v[134:137], v[76:79], v[20:23]
	v_mfma_f32_16x16x32_bf16 v[4:7], v[170:173], v[76:79], v[4:7]
	s_add_u32 m0, s44, 0x8000
	s_nop 0
	global_load_lds_dwordx4 v68, s[100:101]
	ds_read_b128 v[202:205], v121 offset:49152
	v_mfma_f32_16x16x32_bf16 v[48:51], v[84:87], v[92:95], v[48:51]
	v_mfma_f32_16x16x32_bf16 v[32:35], v[88:91], v[92:95], v[32:35]
	s_add_u32 m0, s44, 0x9000
	s_nop 0
	global_load_lds_dwordx4 v69, s[100:101]
	ds_read_b128 v[206:209], v121 offset:51200
	v_mfma_f32_16x16x32_bf16 v[16:19], v[134:137], v[92:95], v[16:19]
	v_mfma_f32_16x16x32_bf16 v[0:3], v[170:173], v[92:95], v[0:3]
	s_add_u32 m0, s44, 0xa000
	s_nop 0
	global_load_lds_dwordx4 v70, s[100:101]
	ds_read_b128 v[134:137], v121 offset:53248
	s_waitcnt lgkmcnt(2)
	v_mfma_f32_16x16x32_bf16 v[64:67], v[202:205], v[178:181], v[64:67]
	s_waitcnt lgkmcnt(1)
	v_mfma_f32_16x16x32_bf16 v[40:43], v[206:209], v[178:181], v[40:43]
	s_add_u32 m0, s44, 0xb000
	s_nop 0
	global_load_lds_dwordx4 v71, s[100:101]
	s_add_u32 s98, s98, 0x80
	s_addc_u32 s99, s99, 0
	s_add_u32 s100, s100, 0x80
	s_addc_u32 s101, s101, 0
	ds_read_b128 v[170:173], v121 offset:55296
	s_waitcnt lgkmcnt(1)
	v_mfma_f32_16x16x32_bf16 v[28:31], v[134:137], v[178:181], v[28:31]
	s_waitcnt lgkmcnt(0)
	v_mfma_f32_16x16x32_bf16 v[12:15], v[170:173], v[178:181], v[12:15]
	v_mfma_f32_16x16x32_bf16 v[60:63], v[202:205], v[186:189], v[60:63]
	v_mfma_f32_16x16x32_bf16 v[44:47], v[206:209], v[186:189], v[44:47]
	v_mfma_f32_16x16x32_bf16 v[24:27], v[134:137], v[186:189], v[24:27]
	v_mfma_f32_16x16x32_bf16 v[8:11], v[170:173], v[186:189], v[8:11]
	v_mfma_f32_16x16x32_bf16 v[52:55], v[202:205], v[190:193], v[52:55]
	v_mfma_f32_16x16x32_bf16 v[36:39], v[206:209], v[190:193], v[36:39]
	v_mfma_f32_16x16x32_bf16 v[20:23], v[134:137], v[190:193], v[20:23]
	v_mfma_f32_16x16x32_bf16 v[4:7], v[170:173], v[190:193], v[4:7]
	v_mfma_f32_16x16x32_bf16 v[48:51], v[202:205], v[198:201], v[48:51]
	v_mfma_f32_16x16x32_bf16 v[32:35], v[206:209], v[198:201], v[32:35]
	v_mfma_f32_16x16x32_bf16 v[16:19], v[134:137], v[198:201], v[16:19]
	v_mfma_f32_16x16x32_bf16 v[0:3], v[170:173], v[198:201], v[0:3]
	s_mov_b32 s42, s33
	s_waitcnt vmcnt(0) lgkmcnt(0)
	s_barrier
	s_cmp_lt_u32 s42, 16
	s_cbranch_scc1 .LBB0_676
	s_setprio 0
	s_waitcnt vmcnt(0)
	s_and_b32 s2, s9, 7
	s_and_b32 s28, s69, 7
	s_lshl_b32 s28, s28, 3
	s_or_b32 s2, s2, s28
	s_lshl_b32 s2, s2, 7
	s_lshr_b32 s28, s9, 3
	s_lshl_b32 s28, s28, 7
	v_readlane_b32 s44, v253, 0
	v_readlane_b32 s45, v253, 1
	s_load_dwordx2 s[98:99], s[44:45], 0x160
	s_load_dwordx2 s[100:101], s[44:45], 0xd8
	v_and_b32_e32 v227, 15, v146
	v_bfe_u32 v228, v146, 7, 1
	v_lshl_add_u32 v227, v228, 6, v227
	v_add_u32_e32 v227, s2, v227
	v_bfe_u32 v228, v146, 4, 2
	v_lshlrev_b32_e32 v228, 2, v228
	v_bfe_u32 v218, v146, 6, 1
	v_lshl_add_u32 v228, v218, 6, v228
	v_add_u32_e32 v228, s28, v228
	v_lshlrev_b32_e32 v218, 2, v228
	v_lshl_add_u32 v96, v227, 12, v218
	v_add_u32_e32 v114, 0x10000, v96
	v_add_u32_e32 v115, 0x20000, v96
	v_add_u32_e32 v142, 0x30000, v96
	v_lshrrev_b32_e32 v214, 1, v96
	v_add_u32_e32 v214, 0xdc40000, v214
	v_lshrrev_b32_e32 v215, 1, v114
	v_add_u32_e32 v215, 0xdc40000, v215
	v_lshrrev_b32_e32 v216, 1, v115
	v_add_u32_e32 v216, 0xdc40000, v216
	v_lshrrev_b32_e32 v217, 1, v142
	v_add_u32_e32 v217, 0xdc40000, v217
	v_lshlrev_b32_e32 v222, 2, v227
	v_add_u32_e32 v222, 0xfa92100, v222
	s_sub_u32 s33, s2, 0x1000
	s_lshr_b32 s33, s33, 10
	s_add_u32 s33, s33, 1
	s_cmp_lt_u32 s2, 0x1000
	s_cselect_b32 s33, 0, s33
	s_mul_i32 s33, s33, 0x3000
	v_add_u32_e32 v219, s33, v218
	v_add_u32_e32 v221, 0xf45f000, v219
	v_add_u32_e32 v219, 0xf451000, v219
	v_mbcnt_lo_u32_b32 v229, -1, 0
	v_mbcnt_hi_u32_b32 v229, -1, v229
	v_xor_b32_e32 v244, 32, v229
	v_xor_b32_e32 v229, 16, v229
	v_lshlrev_b32_e32 v244, 2, v244
	v_lshlrev_b32_e32 v229, 2, v229
	s_waitcnt lgkmcnt(0)
	s_mov_b64 s[44:45], s[98:99]
	global_load_dwordx4 v[162:165], v219, s[98:99]
	global_load_dwordx4 v[166:169], v219, s[98:99] offset:64
	global_load_dwordx4 v[170:173], v219, s[98:99] offset:128
	global_load_dwordx4 v[174:177], v219, s[98:99] offset:192
	global_load_dwordx4 v[178:181], v218, s[100:101]
	global_load_dwordx4 v[182:185], v218, s[100:101] offset:64
	global_load_dwordx4 v[186:189], v218, s[100:101] offset:128
	global_load_dwordx4 v[190:193], v218, s[100:101] offset:192
	global_load_dwordx4 v[194:197], v221, s[98:99]
	global_load_dwordx4 v[198:201], v221, s[98:99] offset:64
	global_load_dwordx4 v[202:205], v221, s[98:99] offset:128
	global_load_dwordx4 v[206:209], v221, s[98:99] offset:192
	global_load_dwordx4 v[56:59], v96, s[44:45]
	global_load_dwordx4 v[80:83], v114, s[44:45]
	global_load_dwordx4 v[98:101], v115, s[44:45]
	global_load_dwordx4 v[126:129], v142, s[44:45]
	global_load_dwordx4 v[68:71], v96, s[44:45] offset:64
	global_load_dwordx4 v[84:87], v114, s[44:45] offset:64
	global_load_dwordx4 v[102:105], v115, s[44:45] offset:64
	global_load_dwordx4 v[130:133], v142, s[44:45] offset:64
	global_load_dwordx4 v[72:75], v96, s[44:45] offset:128
	global_load_dwordx4 v[88:91], v114, s[44:45] offset:128
	global_load_dwordx4 v[106:109], v115, s[44:45] offset:128
	global_load_dwordx4 v[134:137], v142, s[44:45] offset:128
	global_load_dwordx4 v[76:79], v96, s[44:45] offset:192
	global_load_dwordx4 v[92:95], v114, s[44:45] offset:192
	global_load_dwordx4 v[110:113], v115, s[44:45] offset:192
	global_load_dwordx4 v[138:141], v142, s[44:45] offset:192
	v_mov_b32_e32 v223, 0
	v_mov_b32_e32 v224, 0
	v_mov_b32_e32 v225, 0
	v_mov_b32_e32 v226, 0
	s_waitcnt vmcnt(16)
	v_pk_add_f32 v[194:195], v[194:195], 1.0 op_sel_hi:[1,0]
	v_pk_add_f32 v[196:197], v[196:197], 1.0 op_sel_hi:[1,0]
	v_pk_mul_f32 v[194:195], v[178:179], v[194:195]
	v_pk_mul_f32 v[196:197], v[180:181], v[196:197]
	v_pk_add_f32 v[198:199], v[198:199], 1.0 op_sel_hi:[1,0]
	v_pk_add_f32 v[200:201], v[200:201], 1.0 op_sel_hi:[1,0]
	v_pk_mul_f32 v[198:199], v[182:183], v[198:199]
	v_pk_mul_f32 v[200:201], v[184:185], v[200:201]
	v_pk_add_f32 v[202:203], v[202:203], 1.0 op_sel_hi:[1,0]
	v_pk_add_f32 v[204:205], v[204:205], 1.0 op_sel_hi:[1,0]
	v_pk_mul_f32 v[202:203], v[186:187], v[202:203]
	v_pk_mul_f32 v[204:205], v[188:189], v[204:205]
	v_pk_add_f32 v[206:207], v[206:207], 1.0 op_sel_hi:[1,0]
	v_pk_add_f32 v[208:209], v[208:209], 1.0 op_sel_hi:[1,0]
	v_pk_mul_f32 v[206:207], v[190:191], v[206:207]
	v_pk_mul_f32 v[208:209], v[192:193], v[208:209]
	s_waitcnt vmcnt(15)
	v_pk_fma_f32 v[64:65], v[64:65], v[162:163], v[56:57]
	v_pk_fma_f32 v[66:67], v[66:67], v[164:165], v[58:59]
	global_store_dwordx4 v96, v[64:67], s[98:99]
	v_pk_mul_f32 v[56:57], v[194:195], v[64:65]
	v_pk_mul_f32 v[58:59], v[196:197], v[66:67]
	v_cvt_pk_bf16_f32 v56, v56, v57
	v_cvt_pk_bf16_f32 v57, v58, v59
	global_store_dwordx2 v214, v[56:57], s[98:99]
	v_pk_mul_f32 v[58:59], v[64:65], v[64:65]
	v_pk_fma_f32 v[58:59], v[66:67], v[66:67], v[58:59]
	v_add_f32_e32 v227, v58, v59
	v_add_f32_e32 v223, v223, v227
	s_waitcnt vmcnt(16)
	v_pk_fma_f32 v[60:61], v[60:61], v[162:163], v[80:81]
	v_pk_fma_f32 v[62:63], v[62:63], v[164:165], v[82:83]
	global_store_dwordx4 v114, v[60:63], s[98:99]
	v_pk_mul_f32 v[80:81], v[194:195], v[60:61]
	v_pk_mul_f32 v[82:83], v[196:197], v[62:63]
	v_cvt_pk_bf16_f32 v80, v80, v81
	v_cvt_pk_bf16_f32 v81, v82, v83
	global_store_dwordx2 v215, v[80:81], s[98:99]
	v_pk_mul_f32 v[82:83], v[60:61], v[60:61]
	v_pk_fma_f32 v[82:83], v[62:63], v[62:63], v[82:83]
	v_add_f32_e32 v227, v82, v83
	v_add_f32_e32 v224, v224, v227
	s_waitcnt vmcnt(17)
	v_pk_fma_f32 v[52:53], v[52:53], v[162:163], v[98:99]
	v_pk_fma_f32 v[54:55], v[54:55], v[164:165], v[100:101]
	global_store_dwordx4 v115, v[52:55], s[98:99]
	v_pk_mul_f32 v[98:99], v[194:195], v[52:53]
	v_pk_mul_f32 v[100:101], v[196:197], v[54:55]
	v_cvt_pk_bf16_f32 v98, v98, v99
	v_cvt_pk_bf16_f32 v99, v100, v101
	global_store_dwordx2 v216, v[98:99], s[98:99]
	v_pk_mul_f32 v[100:101], v[52:53], v[52:53]
	v_pk_fma_f32 v[100:101], v[54:55], v[54:55], v[100:101]
	v_add_f32_e32 v227, v100, v101
	v_add_f32_e32 v225, v225, v227
	s_waitcnt vmcnt(18)
	v_pk_fma_f32 v[48:49], v[48:49], v[162:163], v[126:127]
	v_pk_fma_f32 v[50:51], v[50:51], v[164:165], v[128:129]
	global_store_dwordx4 v142, v[48:51], s[98:99]
	v_pk_mul_f32 v[126:127], v[194:195], v[48:49]
	v_pk_mul_f32 v[128:129], v[196:197], v[50:51]
	v_cvt_pk_bf16_f32 v126, v126, v127
	v_cvt_pk_bf16_f32 v127, v128, v129
	global_store_dwordx2 v217, v[126:127], s[98:99]
	v_pk_mul_f32 v[128:129], v[48:49], v[48:49]
	v_pk_fma_f32 v[128:129], v[50:51], v[50:51], v[128:129]
	v_add_f32_e32 v227, v128, v129
	v_add_f32_e32 v226, v226, v227
	s_waitcnt vmcnt(19)
	v_pk_fma_f32 v[40:41], v[40:41], v[166:167], v[68:69]
	v_pk_fma_f32 v[42:43], v[42:43], v[168:169], v[70:71]
	global_store_dwordx4 v96, v[40:43], s[98:99] offset:64
	v_pk_mul_f32 v[68:69], v[198:199], v[40:41]
	v_pk_mul_f32 v[70:71], v[200:201], v[42:43]
	v_cvt_pk_bf16_f32 v68, v68, v69
	v_cvt_pk_bf16_f32 v69, v70, v71
	global_store_dwordx2 v214, v[68:69], s[98:99] offset:32
	v_pk_mul_f32 v[70:71], v[40:41], v[40:41]
	v_pk_fma_f32 v[70:71], v[42:43], v[42:43], v[70:71]
	v_add_f32_e32 v227, v70, v71
	v_add_f32_e32 v223, v223, v227
	s_waitcnt vmcnt(20)
	v_pk_fma_f32 v[44:45], v[44:45], v[166:167], v[84:85]
	v_pk_fma_f32 v[46:47], v[46:47], v[168:169], v[86:87]
	global_store_dwordx4 v114, v[44:47], s[98:99] offset:64
	v_pk_mul_f32 v[84:85], v[198:199], v[44:45]
	v_pk_mul_f32 v[86:87], v[200:201], v[46:47]
	v_cvt_pk_bf16_f32 v84, v84, v85
	v_cvt_pk_bf16_f32 v85, v86, v87
	global_store_dwordx2 v215, v[84:85], s[98:99] offset:32
	v_pk_mul_f32 v[86:87], v[44:45], v[44:45]
	v_pk_fma_f32 v[86:87], v[46:47], v[46:47], v[86:87]
	v_add_f32_e32 v227, v86, v87
	v_add_f32_e32 v224, v224, v227
	s_waitcnt vmcnt(21)
	v_pk_fma_f32 v[36:37], v[36:37], v[166:167], v[102:103]
	v_pk_fma_f32 v[38:39], v[38:39], v[168:169], v[104:105]
	global_store_dwordx4 v115, v[36:39], s[98:99] offset:64
	v_pk_mul_f32 v[102:103], v[198:199], v[36:37]
	v_pk_mul_f32 v[104:105], v[200:201], v[38:39]
	v_cvt_pk_bf16_f32 v102, v102, v103
	v_cvt_pk_bf16_f32 v103, v104, v105
	global_store_dwordx2 v216, v[102:103], s[98:99] offset:32
	v_pk_mul_f32 v[104:105], v[36:37], v[36:37]
	v_pk_fma_f32 v[104:105], v[38:39], v[38:39], v[104:105]
	v_add_f32_e32 v227, v104, v105
	v_add_f32_e32 v225, v225, v227
	s_waitcnt vmcnt(22)
	v_pk_fma_f32 v[32:33], v[32:33], v[166:167], v[130:131]
	v_pk_fma_f32 v[34:35], v[34:35], v[168:169], v[132:133]
	global_store_dwordx4 v142, v[32:35], s[98:99] offset:64
	v_pk_mul_f32 v[130:131], v[198:199], v[32:33]
	v_pk_mul_f32 v[132:133], v[200:201], v[34:35]
	v_cvt_pk_bf16_f32 v130, v130, v131
	v_cvt_pk_bf16_f32 v131, v132, v133
	global_store_dwordx2 v217, v[130:131], s[98:99] offset:32
	v_pk_mul_f32 v[132:133], v[32:33], v[32:33]
	v_pk_fma_f32 v[132:133], v[34:35], v[34:35], v[132:133]
	v_add_f32_e32 v227, v132, v133
	v_add_f32_e32 v226, v226, v227
	s_waitcnt vmcnt(23)
	v_pk_fma_f32 v[28:29], v[28:29], v[170:171], v[72:73]
	v_pk_fma_f32 v[30:31], v[30:31], v[172:173], v[74:75]
	global_store_dwordx4 v96, v[28:31], s[98:99] offset:128
	v_pk_mul_f32 v[72:73], v[202:203], v[28:29]
	v_pk_mul_f32 v[74:75], v[204:205], v[30:31]
	v_cvt_pk_bf16_f32 v72, v72, v73
	v_cvt_pk_bf16_f32 v73, v74, v75
	global_store_dwordx2 v214, v[72:73], s[98:99] offset:64
	v_pk_mul_f32 v[74:75], v[28:29], v[28:29]
	v_pk_fma_f32 v[74:75], v[30:31], v[30:31], v[74:75]
	v_add_f32_e32 v227, v74, v75
	v_add_f32_e32 v223, v223, v227
	s_waitcnt vmcnt(24)
	v_pk_fma_f32 v[24:25], v[24:25], v[170:171], v[88:89]
	v_pk_fma_f32 v[26:27], v[26:27], v[172:173], v[90:91]
	global_store_dwordx4 v114, v[24:27], s[98:99] offset:128
	v_pk_mul_f32 v[88:89], v[202:203], v[24:25]
	v_pk_mul_f32 v[90:91], v[204:205], v[26:27]
	v_cvt_pk_bf16_f32 v88, v88, v89
	v_cvt_pk_bf16_f32 v89, v90, v91
	global_store_dwordx2 v215, v[88:89], s[98:99] offset:64
	v_pk_mul_f32 v[90:91], v[24:25], v[24:25]
	v_pk_fma_f32 v[90:91], v[26:27], v[26:27], v[90:91]
	v_add_f32_e32 v227, v90, v91
	v_add_f32_e32 v224, v224, v227
	s_waitcnt vmcnt(25)
	v_pk_fma_f32 v[20:21], v[20:21], v[170:171], v[106:107]
	v_pk_fma_f32 v[22:23], v[22:23], v[172:173], v[108:109]
	global_store_dwordx4 v115, v[20:23], s[98:99] offset:128
	v_pk_mul_f32 v[106:107], v[202:203], v[20:21]
	v_pk_mul_f32 v[108:109], v[204:205], v[22:23]
	v_cvt_pk_bf16_f32 v106, v106, v107
	v_cvt_pk_bf16_f32 v107, v108, v109
	global_store_dwordx2 v216, v[106:107], s[98:99] offset:64
	v_pk_mul_f32 v[108:109], v[20:21], v[20:21]
	v_pk_fma_f32 v[108:109], v[22:23], v[22:23], v[108:109]
	v_add_f32_e32 v227, v108, v109
	v_add_f32_e32 v225, v225, v227
	s_waitcnt vmcnt(26)
	v_pk_fma_f32 v[16:17], v[16:17], v[170:171], v[134:135]
	v_pk_fma_f32 v[18:19], v[18:19], v[172:173], v[136:137]
	global_store_dwordx4 v142, v[16:19], s[98:99] offset:128
	v_pk_mul_f32 v[134:135], v[202:203], v[16:17]
	v_pk_mul_f32 v[136:137], v[204:205], v[18:19]
	v_cvt_pk_bf16_f32 v134, v134, v135
	v_cvt_pk_bf16_f32 v135, v136, v137
	global_store_dwordx2 v217, v[134:135], s[98:99] offset:64
	v_pk_mul_f32 v[136:137], v[16:17], v[16:17]
	v_pk_fma_f32 v[136:137], v[18:19], v[18:19], v[136:137]
	v_add_f32_e32 v227, v136, v137
	v_add_f32_e32 v226, v226, v227
	s_waitcnt vmcnt(27)
	v_pk_fma_f32 v[12:13], v[12:13], v[174:175], v[76:77]
	v_pk_fma_f32 v[14:15], v[14:15], v[176:177], v[78:79]
	global_store_dwordx4 v96, v[12:15], s[98:99] offset:192
	v_pk_mul_f32 v[76:77], v[206:207], v[12:13]
	v_pk_mul_f32 v[78:79], v[208:209], v[14:15]
	v_cvt_pk_bf16_f32 v76, v76, v77
	v_cvt_pk_bf16_f32 v77, v78, v79
	global_store_dwordx2 v214, v[76:77], s[98:99] offset:96
	v_pk_mul_f32 v[78:79], v[12:13], v[12:13]
	v_pk_fma_f32 v[78:79], v[14:15], v[14:15], v[78:79]
	v_add_f32_e32 v227, v78, v79
	v_add_f32_e32 v223, v223, v227
	s_waitcnt vmcnt(28)
	v_pk_fma_f32 v[8:9], v[8:9], v[174:175], v[92:93]
	v_pk_fma_f32 v[10:11], v[10:11], v[176:177], v[94:95]
	global_store_dwordx4 v114, v[8:11], s[98:99] offset:192
	v_pk_mul_f32 v[92:93], v[206:207], v[8:9]
	v_pk_mul_f32 v[94:95], v[208:209], v[10:11]
	v_cvt_pk_bf16_f32 v92, v92, v93
	v_cvt_pk_bf16_f32 v93, v94, v95
	global_store_dwordx2 v215, v[92:93], s[98:99] offset:96
	v_pk_mul_f32 v[94:95], v[8:9], v[8:9]
	v_pk_fma_f32 v[94:95], v[10:11], v[10:11], v[94:95]
	v_add_f32_e32 v227, v94, v95
	v_add_f32_e32 v224, v224, v227
	s_waitcnt vmcnt(29)
	v_pk_fma_f32 v[4:5], v[4:5], v[174:175], v[110:111]
	v_pk_fma_f32 v[6:7], v[6:7], v[176:177], v[112:113]
	global_store_dwordx4 v115, v[4:7], s[98:99] offset:192
	v_pk_mul_f32 v[110:111], v[206:207], v[4:5]
	v_pk_mul_f32 v[112:113], v[208:209], v[6:7]
	v_cvt_pk_bf16_f32 v110, v110, v111
	v_cvt_pk_bf16_f32 v111, v112, v113
	global_store_dwordx2 v216, v[110:111], s[98:99] offset:96
	v_pk_mul_f32 v[112:113], v[4:5], v[4:5]
	v_pk_fma_f32 v[112:113], v[6:7], v[6:7], v[112:113]
	v_add_f32_e32 v227, v112, v113
	v_add_f32_e32 v225, v225, v227
	s_waitcnt vmcnt(30)
	v_pk_fma_f32 v[0:1], v[0:1], v[174:175], v[138:139]
	v_pk_fma_f32 v[2:3], v[2:3], v[176:177], v[140:141]
	global_store_dwordx4 v142, v[0:3], s[98:99] offset:192
	v_pk_mul_f32 v[138:139], v[206:207], v[0:1]
	v_pk_mul_f32 v[140:141], v[208:209], v[2:3]
	v_cvt_pk_bf16_f32 v138, v138, v139
	v_cvt_pk_bf16_f32 v139, v140, v141
	global_store_dwordx2 v217, v[138:139], s[98:99] offset:96
	v_pk_mul_f32 v[140:141], v[0:1], v[0:1]
	v_pk_fma_f32 v[140:141], v[2:3], v[2:3], v[140:141]
	v_add_f32_e32 v227, v140, v141
	v_add_f32_e32 v226, v226, v227
	ds_bpermute_b32 v56, v229, v223
	ds_bpermute_b32 v80, v229, v224
	ds_bpermute_b32 v98, v229, v225
	ds_bpermute_b32 v126, v229, v226
	s_waitcnt lgkmcnt(0)
	v_add_f32_e32 v223, v223, v56
	v_add_f32_e32 v224, v224, v80
	v_add_f32_e32 v225, v225, v98
	v_add_f32_e32 v226, v226, v126
	ds_bpermute_b32 v56, v244, v223
	ds_bpermute_b32 v80, v244, v224
	ds_bpermute_b32 v98, v244, v225
	ds_bpermute_b32 v126, v244, v226
	s_waitcnt lgkmcnt(0)
	v_add_f32_e32 v223, v223, v56
	v_add_f32_e32 v224, v224, v80
	v_add_f32_e32 v225, v225, v98
	v_add_f32_e32 v226, v226, v126
	s_mov_b64 exec, 0xffff
	global_atomic_add_f32 v222, v223, s[98:99]
	global_atomic_add_f32 v222, v224, s[98:99] offset:64
	global_atomic_add_f32 v222, v225, s[98:99] offset:128
	global_atomic_add_f32 v222, v226, s[98:99] offset:192
	s_mov_b64 exec, -1
	s_mov_b32 s98, 0
	s_branch .LBB0_674

.LBB0_739:
	s_and_b32 s8, s7, 7
	s_or_b32 s8, s8, s0
	s_lshl_b32 s8, s8, 7
	v_or_b32_e32 v0, s8, v149
	v_lshl_or_b32 v96, v0, 11, v116
	s_waitcnt vmcnt(1)
	v_lshl_add_u64 v[100:101], s[18:19], 0, v[96:97]
	v_add_co_u32_e32 v2, vcc, 0x10000, v100
	s_lshl_b32 s9, s7, 4
	s_nop 0
	v_addc_co_u32_e32 v3, vcc, 0, v101, vcc
	s_and_b32 s9, s9, 0x7fffff80
	v_add_co_u32_e32 v4, vcc, 0x20000, v100
	v_or_b32_e32 v0, s9, v149
	s_nop 0
	v_addc_co_u32_e32 v5, vcc, 0, v101, vcc
	v_lshl_or_b32 v98, v0, 11, v116
	v_add_co_u32_e32 v6, vcc, 0x30000, v100
	v_mov_b32_e32 v99, v97
	s_nop 0
	v_addc_co_u32_e32 v7, vcc, 0, v101, vcc
	v_lshl_add_u64 v[102:103], s[16:17], 0, v[98:99]
	v_add_co_u32_e32 v12, vcc, s3, v102
	s_nop 0
	v_addc_co_u32_e32 v13, vcc, 0, v103, vcc
	v_add_co_u32_e32 v14, vcc, s4, v102
	s_nop 0
	v_addc_co_u32_e32 v15, vcc, 0, v103, vcc
	v_add_co_u32_e32 v48, vcc, s5, v102
	s_nop 0
	v_addc_co_u32_e32 v49, vcc, 0, v103, vcc
	s_movk_i32 s10, 0x100
	s_mov_b32 s12, s35
	v_mov_b32_e32 v8, 0
	v_mov_b32_e32 v9, v97
	v_mov_b32_e32 v10, v97
	v_mov_b32_e32 v11, v97
	v_mov_b32_e32 v0, 0
	v_mov_b32_e32 v1, v97
	v_mov_b32_e32 v2, v97
	v_mov_b32_e32 v3, v97
	v_mov_b32_e32 v12, 0
	v_mov_b32_e32 v13, v97
	v_mov_b32_e32 v14, v97
	v_mov_b32_e32 v15, v97
	v_mov_b32_e32 v4, 0
	v_mov_b32_e32 v5, v97
	v_lshl_add_u64 v[104:105], v[102:103], 0, s[26:27]
	v_lshl_add_u64 v[106:107], v[102:103], 0, s[28:29]
	v_lshl_add_u64 v[108:109], v[102:103], 0, s[30:31]
	v_lshl_add_u64 v[110:111], v[100:101], 0, s[26:27]
	v_lshl_add_u64 v[112:113], v[100:101], 0, s[28:29]
	v_lshl_add_u64 v[114:115], v[100:101], 0, s[30:31]
	s_barrier
	v_mov_b32_e32 v6, v97
	v_mov_b32_e32 v7, v97
	v_mov_b32_e32 v48, 0
	v_mov_b32_e32 v49, v97
	v_mov_b32_e32 v50, v97
	v_mov_b32_e32 v51, v97
	v_mov_b32_e32 v60, 0
	v_mov_b32_e32 v61, v97
	v_mov_b32_e32 v62, v97
	v_mov_b32_e32 v63, v97
	v_mov_b32_e32 v56, 0
	v_mov_b32_e32 v57, v97
	v_mov_b32_e32 v58, v97
	v_mov_b32_e32 v59, v97
	v_mov_b32_e32 v52, 0
	v_mov_b32_e32 v53, v97
	v_mov_b32_e32 v54, v97
	v_mov_b32_e32 v55, v97
	v_mov_b32_e32 v32, 0
	v_mov_b32_e32 v33, v97
	v_mov_b32_e32 v34, v97
	v_mov_b32_e32 v35, v97
	v_mov_b32_e32 v24, 0
	v_mov_b32_e32 v25, v97
	v_mov_b32_e32 v26, v97
	v_mov_b32_e32 v27, v97
	v_mov_b32_e32 v20, 0
	v_mov_b32_e32 v21, v97
	v_mov_b32_e32 v22, v97
	v_mov_b32_e32 v23, v97
	v_mov_b32_e32 v16, 0
	v_mov_b32_e32 v17, v97
	v_mov_b32_e32 v18, v97
	v_mov_b32_e32 v19, v97
	v_mov_b32_e32 v40, 0
	v_mov_b32_e32 v41, v97
	v_mov_b32_e32 v42, v97
	v_mov_b32_e32 v43, v97
	v_mov_b32_e32 v36, 0
	v_mov_b32_e32 v37, v97
	v_mov_b32_e32 v38, v97
	v_mov_b32_e32 v39, v97
	v_mov_b32_e32 v28, 0
	v_mov_b32_e32 v29, v97
	v_mov_b32_e32 v30, v97
	v_mov_b32_e32 v31, v97
	v_mov_b32_e32 v44, 0
	v_mov_b32_e32 v45, v97
	v_mov_b32_e32 v46, v97
	v_mov_b32_e32 v47, v97
	v_readlane_b32 s100, v253, 0
	v_readlane_b32 s101, v253, 1
	s_load_dwordx2 s[100:101], s[100:101], 0x160
	v_lshrrev_b32_e32 v71, 6, v146
	s_nop 0
	v_readfirstlane_b32 s14, v71
	v_lshrrev_b32_e32 v69, 3, v146
	v_and_b32_e32 v70, 7, v146
	v_xor_b32_e32 v70, v69, v70
	v_and_b32_e32 v70, 7, v70
	v_lshlrev_b32_e32 v70, 4, v70
	v_lshl_or_b32 v68, v69, 11, v70
	v_add_u32_e32 v69, 0x10000, v68
	v_add_u32_e32 v70, 0x20000, v68
	v_add_u32_e32 v71, 0x30000, v68
	s_and_b32 s98, s7, 7
	s_and_b32 s99, s69, 7
	s_lshl_b32 s99, s99, 3
	s_or_b32 s98, s98, s99
	s_lshl_b32 s98, s98, 18
	s_add_u32 s98, s98, 0xdc40000
	s_lshr_b32 s99, s7, 3
	s_lshl_b32 s99, s99, 18
	s_add_u32 s99, s99, 0x7f00000
	s_lshl_b32 s14, s14, 10
	s_waitcnt lgkmcnt(0)
	s_mov_b32 m0, s99
	s_add_u32 s98, s100, s98
	s_addc_u32 s99, s101, 0
	s_add_u32 s100, s100, m0
	s_addc_u32 s101, s101, 0
	s_add_u32 m0, s14, 0x0
	s_nop 0
	global_load_lds_dwordx4 v68, s[98:99]
	s_add_u32 m0, s14, 0x1000
	s_nop 0
	global_load_lds_dwordx4 v69, s[98:99]
	s_add_u32 m0, s14, 0x2000
	s_nop 0
	global_load_lds_dwordx4 v70, s[98:99]
	s_add_u32 m0, s14, 0x3000
	s_nop 0
	global_load_lds_dwordx4 v71, s[98:99]
	s_add_u32 m0, s14, 0x8000
	s_nop 0
	global_load_lds_dwordx4 v68, s[100:101]
	s_add_u32 m0, s14, 0x9000
	s_nop 0
	global_load_lds_dwordx4 v69, s[100:101]
	s_add_u32 m0, s14, 0xa000
	s_nop 0
	global_load_lds_dwordx4 v70, s[100:101]
	s_add_u32 m0, s14, 0xb000
	s_nop 0
	global_load_lds_dwordx4 v71, s[100:101]
	s_add_u32 s98, s98, 0x80
	s_addc_u32 s99, s99, 0
	s_add_u32 s100, s100, 0x80
	s_addc_u32 s101, s101, 0
	s_waitcnt vmcnt(0)
	s_waitcnt lgkmcnt(0)
	s_barrier
	s_bitcmp1_b32 s69, 8
	s_cbranch_scc1 .Lprio_h740
	s_setprio 0
	s_branch .Lprio_j740

.Lprio_j740:
.LBB0_740:
	s_add_i32 s11, s12, 2
	ds_read_b128 v[124:127], v119 offset:32768
	ds_read_b128 v[132:135], v119 offset:34816
	ds_read_b128 v[128:131], v118
	ds_read_b128 v[136:139], v118 offset:2048
	ds_read_b128 v[140:143], v118 offset:4096
	ds_read_b128 v[162:165], v118 offset:6144
	s_waitcnt lgkmcnt(3)
	v_mfma_f32_16x16x32_bf16 v[8:11], v[124:127], v[128:131], v[8:11]
	ds_read_b128 v[166:169], v119 offset:36864
	v_mfma_f32_16x16x32_bf16 v[0:3], v[132:135], v[128:131], v[0:3]
	ds_read_b128 v[170:173], v119 offset:38912
	s_waitcnt lgkmcnt(1)
	v_mfma_f32_16x16x32_bf16 v[12:15], v[166:169], v[128:131], v[12:15]
	s_waitcnt lgkmcnt(0)
	v_mfma_f32_16x16x32_bf16 v[4:7], v[170:173], v[128:131], v[4:7]
	s_add_u32 m0, s14, 0x4000
	s_nop 0
	global_load_lds_dwordx4 v68, s[98:99]
	ds_read_b128 v[174:177], v120
	v_mfma_f32_16x16x32_bf16 v[32:35], v[124:127], v[136:139], v[32:35]
	v_mfma_f32_16x16x32_bf16 v[24:27], v[132:135], v[136:139], v[24:27]
	s_add_u32 m0, s14, 0x5000
	s_nop 0
	global_load_lds_dwordx4 v69, s[98:99]
	ds_read_b128 v[182:185], v120 offset:2048
	v_mfma_f32_16x16x32_bf16 v[20:23], v[166:169], v[136:139], v[20:23]
	v_mfma_f32_16x16x32_bf16 v[16:19], v[170:173], v[136:139], v[16:19]
	s_add_u32 m0, s14, 0x6000
	s_nop 0
	global_load_lds_dwordx4 v70, s[98:99]
	ds_read_b128 v[186:189], v120 offset:4096
	v_mfma_f32_16x16x32_bf16 v[48:51], v[124:127], v[140:143], v[48:51]
	v_mfma_f32_16x16x32_bf16 v[40:43], v[132:135], v[140:143], v[40:43]
	s_add_u32 m0, s14, 0x7000
	s_nop 0
	global_load_lds_dwordx4 v71, s[98:99]
	ds_read_b128 v[194:197], v120 offset:6144
	v_mfma_f32_16x16x32_bf16 v[36:39], v[166:169], v[140:143], v[36:39]
	v_mfma_f32_16x16x32_bf16 v[28:31], v[170:173], v[140:143], v[28:31]
	s_add_u32 m0, s14, 0xc000
	s_nop 0
	global_load_lds_dwordx4 v68, s[100:101]
	ds_read_b128 v[198:201], v121 offset:32768
	v_mfma_f32_16x16x32_bf16 v[60:63], v[124:127], v[162:165], v[60:63]
	v_mfma_f32_16x16x32_bf16 v[56:59], v[132:135], v[162:165], v[56:59]
	s_add_u32 m0, s14, 0xd000
	s_nop 0
	global_load_lds_dwordx4 v69, s[100:101]
	ds_read_b128 v[132:135], v121 offset:34816
	v_mfma_f32_16x16x32_bf16 v[52:55], v[166:169], v[162:165], v[52:55]
	v_mfma_f32_16x16x32_bf16 v[44:47], v[170:173], v[162:165], v[44:47]
	s_add_u32 m0, s14, 0xe000
	s_nop 0
	global_load_lds_dwordx4 v70, s[100:101]
	ds_read_b128 v[166:169], v121 offset:36864
	s_waitcnt lgkmcnt(2)
	v_mfma_f32_16x16x32_bf16 v[8:11], v[198:201], v[174:177], v[8:11]
	s_waitcnt lgkmcnt(1)
	v_mfma_f32_16x16x32_bf16 v[0:3], v[132:135], v[174:177], v[0:3]
	s_add_u32 m0, s14, 0xf000
	s_nop 0
	global_load_lds_dwordx4 v71, s[100:101]
	s_add_u32 s98, s98, 0x80
	s_addc_u32 s99, s99, 0
	s_add_u32 s100, s100, 0x80
	s_addc_u32 s101, s101, 0
	ds_read_b128 v[202:205], v121 offset:38912
	s_waitcnt lgkmcnt(1)
	v_mfma_f32_16x16x32_bf16 v[12:15], v[166:169], v[174:177], v[12:15]
	s_waitcnt lgkmcnt(0)
	v_mfma_f32_16x16x32_bf16 v[4:7], v[202:205], v[174:177], v[4:7]
	v_mfma_f32_16x16x32_bf16 v[32:35], v[198:201], v[182:185], v[32:35]
	v_mfma_f32_16x16x32_bf16 v[24:27], v[132:135], v[182:185], v[24:27]
	v_mfma_f32_16x16x32_bf16 v[20:23], v[166:169], v[182:185], v[20:23]
	v_mfma_f32_16x16x32_bf16 v[16:19], v[202:205], v[182:185], v[16:19]
	v_mfma_f32_16x16x32_bf16 v[48:51], v[198:201], v[186:189], v[48:51]
	v_mfma_f32_16x16x32_bf16 v[40:43], v[132:135], v[186:189], v[40:43]
	v_mfma_f32_16x16x32_bf16 v[36:39], v[166:169], v[186:189], v[36:39]
	v_mfma_f32_16x16x32_bf16 v[28:31], v[202:205], v[186:189], v[28:31]
	v_mfma_f32_16x16x32_bf16 v[60:63], v[198:201], v[194:197], v[60:63]
	v_mfma_f32_16x16x32_bf16 v[56:59], v[132:135], v[194:197], v[56:59]
	v_mfma_f32_16x16x32_bf16 v[52:55], v[166:169], v[194:197], v[52:55]
	v_mfma_f32_16x16x32_bf16 v[44:47], v[202:205], v[194:197], v[44:47]
	s_waitcnt vmcnt(0) lgkmcnt(0)
	s_barrier
	ds_read_b128 v[84:87], v119 offset:49152
	ds_read_b128 v[88:91], v119 offset:51200
	ds_read_b128 v[64:67], v118 offset:16384
	ds_read_b128 v[72:75], v118 offset:18432
	ds_read_b128 v[76:79], v118 offset:20480
	ds_read_b128 v[92:95], v118 offset:22528
	s_waitcnt lgkmcnt(3)
	v_mfma_f32_16x16x32_bf16 v[8:11], v[84:87], v[64:67], v[8:11]
	ds_read_b128 v[132:135], v119 offset:53248
	v_mfma_f32_16x16x32_bf16 v[0:3], v[88:91], v[64:67], v[0:3]
	ds_read_b128 v[166:169], v119 offset:55296
	s_waitcnt lgkmcnt(1)
	v_mfma_f32_16x16x32_bf16 v[12:15], v[132:135], v[64:67], v[12:15]
	s_waitcnt lgkmcnt(0)
	v_mfma_f32_16x16x32_bf16 v[4:7], v[166:169], v[64:67], v[4:7]
	s_add_u32 m0, s14, 0x0
	s_nop 0
	global_load_lds_dwordx4 v68, s[98:99]
	ds_read_b128 v[174:177], v120 offset:16384
	v_mfma_f32_16x16x32_bf16 v[32:35], v[84:87], v[72:75], v[32:35]
	v_mfma_f32_16x16x32_bf16 v[24:27], v[88:91], v[72:75], v[24:27]
	s_add_u32 m0, s14, 0x1000
	s_nop 0
	global_load_lds_dwordx4 v69, s[98:99]
	ds_read_b128 v[182:185], v120 offset:18432
	v_mfma_f32_16x16x32_bf16 v[20:23], v[132:135], v[72:75], v[20:23]
	v_mfma_f32_16x16x32_bf16 v[16:19], v[166:169], v[72:75], v[16:19]
	s_add_u32 m0, s14, 0x2000
	s_nop 0
	global_load_lds_dwordx4 v70, s[98:99]
	ds_read_b128 v[186:189], v120 offset:20480
	v_mfma_f32_16x16x32_bf16 v[48:51], v[84:87], v[76:79], v[48:51]
	v_mfma_f32_16x16x32_bf16 v[40:43], v[88:91], v[76:79], v[40:43]
	s_add_u32 m0, s14, 0x3000
	s_nop 0
	global_load_lds_dwordx4 v71, s[98:99]
	ds_read_b128 v[194:197], v120 offset:22528
	v_mfma_f32_16x16x32_bf16 v[36:39], v[132:135], v[76:79], v[36:39]
	v_mfma_f32_16x16x32_bf16 v[28:31], v[166:169], v[76:79], v[28:31]
	s_add_u32 m0, s14, 0x8000
	s_nop 0
	global_load_lds_dwordx4 v68, s[100:101]
	ds_read_b128 v[198:201], v121 offset:49152
	v_mfma_f32_16x16x32_bf16 v[60:63], v[84:87], v[92:95], v[60:63]
	v_mfma_f32_16x16x32_bf16 v[56:59], v[88:91], v[92:95], v[56:59]
	s_add_u32 m0, s14, 0x9000
	s_nop 0
	global_load_lds_dwordx4 v69, s[100:101]
	ds_read_b128 v[202:205], v121 offset:51200
	v_mfma_f32_16x16x32_bf16 v[52:55], v[132:135], v[92:95], v[52:55]
	v_mfma_f32_16x16x32_bf16 v[44:47], v[166:169], v[92:95], v[44:47]
	s_add_u32 m0, s14, 0xa000
	s_nop 0
	global_load_lds_dwordx4 v70, s[100:101]
	ds_read_b128 v[132:135], v121 offset:53248
	s_waitcnt lgkmcnt(2)
	v_mfma_f32_16x16x32_bf16 v[8:11], v[198:201], v[174:177], v[8:11]
	s_waitcnt lgkmcnt(1)
	v_mfma_f32_16x16x32_bf16 v[0:3], v[202:205], v[174:177], v[0:3]
	s_add_u32 m0, s14, 0xb000
	s_nop 0
	global_load_lds_dwordx4 v71, s[100:101]
	s_add_u32 s98, s98, 0x80
	s_addc_u32 s99, s99, 0
	s_add_u32 s100, s100, 0x80
	s_addc_u32 s101, s101, 0
	ds_read_b128 v[166:169], v121 offset:55296
	s_waitcnt lgkmcnt(1)
	v_mfma_f32_16x16x32_bf16 v[12:15], v[132:135], v[174:177], v[12:15]
	s_waitcnt lgkmcnt(0)
	v_mfma_f32_16x16x32_bf16 v[4:7], v[166:169], v[174:177], v[4:7]
	v_mfma_f32_16x16x32_bf16 v[32:35], v[198:201], v[182:185], v[32:35]
	v_mfma_f32_16x16x32_bf16 v[24:27], v[202:205], v[182:185], v[24:27]
	v_mfma_f32_16x16x32_bf16 v[20:23], v[132:135], v[182:185], v[20:23]
	v_mfma_f32_16x16x32_bf16 v[16:19], v[166:169], v[182:185], v[16:19]
	v_mfma_f32_16x16x32_bf16 v[48:51], v[198:201], v[186:189], v[48:51]
	v_mfma_f32_16x16x32_bf16 v[40:43], v[202:205], v[186:189], v[40:43]
	v_mfma_f32_16x16x32_bf16 v[36:39], v[132:135], v[186:189], v[36:39]
	v_mfma_f32_16x16x32_bf16 v[28:31], v[166:169], v[186:189], v[28:31]
	v_mfma_f32_16x16x32_bf16 v[60:63], v[198:201], v[194:197], v[60:63]
	v_mfma_f32_16x16x32_bf16 v[56:59], v[202:205], v[194:197], v[56:59]
	v_mfma_f32_16x16x32_bf16 v[52:55], v[132:135], v[194:197], v[52:55]
	v_mfma_f32_16x16x32_bf16 v[44:47], v[166:169], v[194:197], v[44:47]
	s_mov_b32 s12, s11
	s_waitcnt vmcnt(0) lgkmcnt(0)
	s_barrier
	s_cmp_lt_u32 s12, 16
	s_cbranch_scc1 .LBB0_740
	s_setprio 0
	s_waitcnt vmcnt(4)
	v_add_u32_e32 v80, s8, v122
	s_addk_i32 s8, 0xf000
	v_lshlrev_b32_e32 v64, 2, v80
	s_ashr_i32 s8, s8, 10
	global_load_dword v84, v64, s[24:25]
	global_load_dword v85, v64, s[24:25] offset:64
	global_load_dword v86, v64, s[24:25] offset:128
	global_load_dword v87, v64, s[24:25] offset:192
	s_add_i32 s10, s8, 11
	v_or_b32_e32 v96, s9, v234
	s_and_b64 s[8:9], s[22:23], exec
	s_cselect_b32 s8, 10, s10
	s_mul_hi_u32 s9, s8, 0x4200
	s_mulk_i32 s8, 0x4200
	s_add_u32 s8, s1, s8
	s_addc_u32 s9, s2, s9
	v_lshlrev_b32_e32 v64, 2, v154
	v_mov_b32_e32 v65, v97
	v_lshl_add_u64 v[66:67], v[96:97], 2, s[8:9]
	s_waitcnt vmcnt(7)
	v_lshl_add_u64 v[76:77], v[66:67], 0, v[64:65]
	global_load_dwordx4 v[64:67], v[76:77], off
	global_load_dwordx4 v[68:71], v[76:77], off offset:64
	global_load_dwordx4 v[72:75], v[76:77], off offset:128
	s_nop 0
	global_load_dwordx4 v[76:79], v[76:77], off offset:192
	v_mul_u32_u24_e32 v80, 0x1080, v80
	v_or_b32_e32 v82, v96, v154
	v_lshlrev_b32_e32 v96, 1, v80
	v_lshl_add_u64 v[80:81], s[20:21], 0, v[96:97]
	v_lshlrev_b32_e32 v96, 1, v82
	v_lshl_add_u64 v[82:83], v[80:81], 0, v[96:97]
	s_add_i32 s7, s7, s96
	s_cmpk_gt_u32 s7, 0xff
	s_waitcnt vmcnt(7)
	v_fmamk_f32 v84, v84, 0x3a800000, v123
	v_mul_f32_e32 v88, 0x4b800000, v84
	v_cmp_gt_f32_e32 vcc, s6, v84
	s_waitcnt vmcnt(6)
	v_fmamk_f32 v85, v85, 0x3a800000, v123
	v_mul_f32_e32 v89, 0x4b800000, v85
	v_cndmask_b32_e32 v84, v84, v88, vcc
	v_cmp_gt_f32_e64 s[10:11], s6, v85
	v_rsq_f32_e32 v84, v84
	s_waitcnt vmcnt(5)
	v_fmamk_f32 v86, v86, 0x3a800000, v123
	v_cndmask_b32_e64 v85, v85, v89, s[10:11]
	v_mul_f32_e32 v90, 0x4b800000, v86
	v_cmp_gt_f32_e64 s[12:13], s6, v86
	v_rsq_f32_e32 v85, v85
	s_waitcnt vmcnt(4)
	v_fmamk_f32 v87, v87, 0x3a800000, v123
	v_cndmask_b32_e64 v86, v86, v90, s[12:13]
	v_mul_f32_e32 v91, 0x4b800000, v87
	v_cmp_gt_f32_e64 s[14:15], s6, v87
	v_rsq_f32_e32 v88, v86
	v_mul_f32_e32 v86, 0x45800000, v84
	v_cndmask_b32_e64 v87, v87, v91, s[14:15]
	v_cndmask_b32_e32 v84, v84, v86, vcc
	v_rsq_f32_e32 v87, v87
	s_waitcnt vmcnt(2)
	v_pk_fma_f32 v[0:1], v[0:1], v[84:85], v[68:69] op_sel_hi:[1,0,1]
	v_pk_fma_f32 v[2:3], v[2:3], v[84:85], v[70:71] op_sel_hi:[1,0,1]
	s_waitcnt vmcnt(1)
	v_pk_fma_f32 v[12:13], v[12:13], v[84:85], v[72:73] op_sel_hi:[1,0,1]
	v_pk_fma_f32 v[14:15], v[14:15], v[84:85], v[74:75] op_sel_hi:[1,0,1]
	v_cvt_pk_bf16_f32 v0, v0, v1
	v_cvt_pk_bf16_f32 v1, v2, v3
	v_mul_f32_e32 v89, 0x45800000, v85
	s_waitcnt vmcnt(0)
	v_pk_fma_f32 v[4:5], v[4:5], v[84:85], v[76:77] op_sel_hi:[1,0,1]
	v_pk_fma_f32 v[6:7], v[6:7], v[84:85], v[78:79] op_sel_hi:[1,0,1]
	global_store_dwordx2 v[82:83], v[0:1], off offset:32
	v_cvt_pk_bf16_f32 v0, v12, v13
	v_cvt_pk_bf16_f32 v1, v14, v15
	v_cndmask_b32_e64 v86, v85, v89, s[10:11]
	global_store_dwordx2 v[82:83], v[0:1], off offset:64
	v_cvt_pk_bf16_f32 v0, v4, v5
	v_cvt_pk_bf16_f32 v1, v6, v7
	v_pk_fma_f32 v[32:33], v[32:33], v[86:87], v[64:65] op_sel_hi:[1,0,1]
	v_pk_fma_f32 v[34:35], v[34:35], v[86:87], v[66:67] op_sel_hi:[1,0,1]
	global_store_dwordx2 v[82:83], v[0:1], off offset:96
	v_lshl_add_u64 v[0:1], v[80:81], 0, s[36:37]
	v_cvt_pk_bf16_f32 v2, v32, v33
	v_cvt_pk_bf16_f32 v3, v34, v35
	v_lshl_add_u64 v[4:5], v[0:1], 0, v[96:97]
	v_pk_fma_f32 v[24:25], v[24:25], v[86:87], v[68:69] op_sel_hi:[1,0,1]
	v_pk_fma_f32 v[26:27], v[26:27], v[86:87], v[70:71] op_sel_hi:[1,0,1]
	global_store_dwordx2 v[4:5], v[2:3], off
	v_or_b32_e32 v4, 32, v96
	v_mov_b32_e32 v5, v97
	v_pk_fma_f32 v[8:9], v[8:9], v[84:85], v[64:65] op_sel_hi:[1,0,1]
	v_pk_fma_f32 v[10:11], v[10:11], v[84:85], v[66:67] op_sel_hi:[1,0,1]
	v_cvt_pk_bf16_f32 v2, v24, v25
	v_cvt_pk_bf16_f32 v3, v26, v27
	v_lshl_add_u64 v[6:7], v[0:1], 0, v[4:5]
	v_pk_fma_f32 v[20:21], v[20:21], v[86:87], v[72:73] op_sel_hi:[1,0,1]
	v_pk_fma_f32 v[22:23], v[22:23], v[86:87], v[74:75] op_sel_hi:[1,0,1]
	v_cvt_pk_bf16_f32 v8, v8, v9
	v_cvt_pk_bf16_f32 v9, v10, v11
	global_store_dwordx2 v[6:7], v[2:3], off
	v_or_b32_e32 v6, 64, v96
	v_mov_b32_e32 v7, v97
	global_store_dwordx2 v[82:83], v[8:9], off
	v_cvt_pk_bf16_f32 v2, v20, v21
	v_cvt_pk_bf16_f32 v3, v22, v23
	v_lshl_add_u64 v[8:9], v[0:1], 0, v[6:7]
	v_mul_f32_e32 v90, 0x45800000, v88
	v_pk_fma_f32 v[16:17], v[16:17], v[86:87], v[76:77] op_sel_hi:[1,0,1]
	v_pk_fma_f32 v[18:19], v[18:19], v[86:87], v[78:79] op_sel_hi:[1,0,1]
	global_store_dwordx2 v[8:9], v[2:3], off
	v_or_b32_e32 v8, 0x60, v96
	v_mov_b32_e32 v9, v97
	v_cndmask_b32_e64 v88, v88, v90, s[12:13]
	v_cvt_pk_bf16_f32 v2, v16, v17
	v_cvt_pk_bf16_f32 v3, v18, v19
	v_lshl_add_u64 v[0:1], v[0:1], 0, v[8:9]
	v_pk_fma_f32 v[48:49], v[48:49], v[88:89], v[64:65] op_sel_hi:[1,0,1]
	v_pk_fma_f32 v[50:51], v[50:51], v[88:89], v[66:67] op_sel_hi:[1,0,1]
	global_store_dwordx2 v[0:1], v[2:3], off
	v_lshl_add_u64 v[0:1], v[80:81], 0, s[38:39]
	v_pk_fma_f32 v[40:41], v[40:41], v[88:89], v[68:69] op_sel_hi:[1,0,1]
	v_pk_fma_f32 v[42:43], v[42:43], v[88:89], v[70:71] op_sel_hi:[1,0,1]
	v_cvt_pk_bf16_f32 v2, v48, v49
	v_cvt_pk_bf16_f32 v3, v50, v51
	v_lshl_add_u64 v[10:11], v[0:1], 0, v[96:97]
	v_pk_fma_f32 v[36:37], v[36:37], v[88:89], v[72:73] op_sel_hi:[1,0,1]
	v_pk_fma_f32 v[38:39], v[38:39], v[88:89], v[74:75] op_sel_hi:[1,0,1]
	global_store_dwordx2 v[10:11], v[2:3], off
	v_cvt_pk_bf16_f32 v2, v40, v41
	v_cvt_pk_bf16_f32 v3, v42, v43
	v_lshl_add_u64 v[10:11], v[0:1], 0, v[4:5]
	v_mul_f32_e32 v91, 0x45800000, v87
	v_pk_fma_f32 v[28:29], v[28:29], v[88:89], v[76:77] op_sel_hi:[1,0,1]
	v_pk_fma_f32 v[30:31], v[30:31], v[88:89], v[78:79] op_sel_hi:[1,0,1]
	global_store_dwordx2 v[10:11], v[2:3], off
	v_cvt_pk_bf16_f32 v2, v36, v37
	v_cvt_pk_bf16_f32 v3, v38, v39
	v_lshl_add_u64 v[10:11], v[0:1], 0, v[6:7]
	v_cndmask_b32_e64 v90, v87, v91, s[14:15]
	global_store_dwordx2 v[10:11], v[2:3], off
	v_cvt_pk_bf16_f32 v2, v28, v29
	v_cvt_pk_bf16_f32 v3, v30, v31
	v_lshl_add_u64 v[0:1], v[0:1], 0, v[8:9]
	v_pk_fma_f32 v[60:61], v[60:61], v[90:91], v[64:65] op_sel_hi:[1,0,1]
	v_pk_fma_f32 v[62:63], v[62:63], v[90:91], v[66:67] op_sel_hi:[1,0,1]
	global_store_dwordx2 v[0:1], v[2:3], off
	v_lshl_add_u64 v[0:1], v[80:81], 0, s[40:41]
	v_pk_fma_f32 v[56:57], v[56:57], v[90:91], v[68:69] op_sel_hi:[1,0,1]
	v_pk_fma_f32 v[58:59], v[58:59], v[90:91], v[70:71] op_sel_hi:[1,0,1]
	v_cvt_pk_bf16_f32 v2, v60, v61
	v_cvt_pk_bf16_f32 v3, v62, v63
	v_lshl_add_u64 v[10:11], v[0:1], 0, v[96:97]
	v_pk_fma_f32 v[52:53], v[52:53], v[90:91], v[72:73] op_sel_hi:[1,0,1]
	v_pk_fma_f32 v[54:55], v[54:55], v[90:91], v[74:75] op_sel_hi:[1,0,1]
	global_store_dwordx2 v[10:11], v[2:3], off
	v_cvt_pk_bf16_f32 v2, v56, v57
	v_cvt_pk_bf16_f32 v3, v58, v59
	v_lshl_add_u64 v[4:5], v[0:1], 0, v[4:5]
	v_pk_fma_f32 v[44:45], v[44:45], v[90:91], v[76:77] op_sel_hi:[1,0,1]
	v_pk_fma_f32 v[46:47], v[46:47], v[90:91], v[78:79] op_sel_hi:[1,0,1]
	global_store_dwordx2 v[4:5], v[2:3], off
	v_cvt_pk_bf16_f32 v2, v52, v53
	v_cvt_pk_bf16_f32 v3, v54, v55
	v_lshl_add_u64 v[4:5], v[0:1], 0, v[6:7]
	global_store_dwordx2 v[4:5], v[2:3], off
	v_cvt_pk_bf16_f32 v2, v44, v45
	v_cvt_pk_bf16_f32 v3, v46, v47
	v_lshl_add_u64 v[0:1], v[0:1], 0, v[8:9]
	global_store_dwordx2 v[0:1], v[2:3], off
	s_cbranch_scc0 .LBB0_739

.LBB0_1100:
	s_and_b32 s0, s9, 7
	s_or_b32 s0, s0, s3
	s_lshl_b32 s1, s0, 7
	v_or_b32_e32 v0, s1, v149
	v_lshl_or_b32 v96, v0, 11, v116
	s_waitcnt vmcnt(1)
	v_lshl_add_u64 v[100:101], s[18:19], 0, v[96:97]
	v_add_co_u32_e32 v12, vcc, 0x10000, v100
	s_lshl_b32 s2, s9, 4
	s_nop 0
	v_addc_co_u32_e32 v13, vcc, 0, v101, vcc
	s_and_b32 s0, s2, 0x7fffff80
	v_add_co_u32_e32 v26, vcc, 0x20000, v100
	v_or_b32_e32 v0, s0, v149
	s_nop 0
	v_addc_co_u32_e32 v27, vcc, 0, v101, vcc
	v_lshl_or_b32 v98, v0, 11, v116
	v_add_co_u32_e32 v28, vcc, 0x30000, v100
	v_mov_b32_e32 v99, v97
	s_nop 0
	v_addc_co_u32_e32 v29, vcc, 0, v101, vcc
	v_lshl_add_u64 v[102:103], s[16:17], 0, v[98:99]
	v_add_co_u32_e32 v30, vcc, s6, v102
	s_waitcnt lgkmcnt(0)
	v_addc_co_u32_e32 v31, vcc, 0, v103, vcc
	v_add_co_u32_e32 v42, vcc, s7, v102
	s_nop 0
	v_addc_co_u32_e32 v43, vcc, 0, v103, vcc
	v_add_co_u32_e32 v44, vcc, s8, v102
	s_nop 0
	v_addc_co_u32_e32 v45, vcc, 0, v103, vcc
	s_movk_i32 s2, 0x100
	s_mov_b32 s40, s27
	v_mov_b32_e32 v64, 0
	v_mov_b32_e32 v65, v97
	v_mov_b32_e32 v66, v97
	v_mov_b32_e32 v67, v97
	v_mov_b32_e32 v40, 0
	v_mov_b32_e32 v41, v97
	v_mov_b32_e32 v42, v97
	v_mov_b32_e32 v43, v97
	v_mov_b32_e32 v28, 0
	v_mov_b32_e32 v29, v97
	v_mov_b32_e32 v30, v97
	v_mov_b32_e32 v31, v97
	v_mov_b32_e32 v12, 0
	v_mov_b32_e32 v13, v97
	v_lshl_add_u64 v[104:105], v[102:103], 0, s[28:29]
	v_lshl_add_u64 v[106:107], v[102:103], 0, s[30:31]
	v_lshl_add_u64 v[108:109], v[102:103], 0, s[34:35]
	v_lshl_add_u64 v[110:111], v[100:101], 0, s[28:29]
	v_lshl_add_u64 v[112:113], v[100:101], 0, s[30:31]
	v_lshl_add_u64 v[114:115], v[100:101], 0, s[34:35]
	s_waitcnt lgkmcnt(0)
	s_barrier
	v_mov_b32_e32 v60, 0
	v_mov_b32_e32 v61, v97
	v_mov_b32_e32 v62, v97
	v_mov_b32_e32 v63, v97
	v_mov_b32_e32 v44, 0
	v_mov_b32_e32 v45, v97
	v_mov_b32_e32 v46, v97
	v_mov_b32_e32 v47, v97
	v_mov_b32_e32 v26, v97
	v_mov_b32_e32 v27, v97
	v_mov_b32_e32 v52, 0
	v_mov_b32_e32 v53, v97
	v_mov_b32_e32 v54, v97
	v_mov_b32_e32 v55, v97
	v_mov_b32_e32 v48, 0
	v_mov_b32_e32 v49, v97
	v_mov_b32_e32 v50, v97
	v_mov_b32_e32 v51, v97
	v_mov_b32_e32 v14, v97
	v_mov_b32_e32 v15, v97
	v_mov_b32_e32 v24, 0
	v_mov_b32_e32 v25, v97
	v_mov_b32_e32 v8, 0
	v_mov_b32_e32 v9, v97
	v_mov_b32_e32 v10, v97
	v_mov_b32_e32 v11, v97
	v_mov_b32_e32 v36, 0
	v_mov_b32_e32 v37, v97
	v_mov_b32_e32 v38, v97
	v_mov_b32_e32 v39, v97
	v_mov_b32_e32 v20, 0
	v_mov_b32_e32 v21, v97
	v_mov_b32_e32 v22, v97
	v_mov_b32_e32 v23, v97
	v_mov_b32_e32 v4, 0
	v_mov_b32_e32 v5, v97
	v_mov_b32_e32 v6, v97
	v_mov_b32_e32 v7, v97
	v_mov_b32_e32 v32, 0
	v_mov_b32_e32 v33, v97
	v_mov_b32_e32 v34, v97
	v_mov_b32_e32 v35, v97
	v_mov_b32_e32 v16, 0
	v_mov_b32_e32 v17, v97
	v_mov_b32_e32 v18, v97
	v_mov_b32_e32 v19, v97
	v_mov_b32_e32 v0, 0
	v_mov_b32_e32 v1, v97
	v_mov_b32_e32 v2, v97
	v_mov_b32_e32 v3, v97
	v_readlane_b32 s100, v253, 0
	v_readlane_b32 s101, v253, 1
	s_load_dwordx2 s[100:101], s[100:101], 0x160
	v_lshrrev_b32_e32 v71, 6, v146
	s_nop 0
	v_readfirstlane_b32 s42, v71
	v_lshrrev_b32_e32 v69, 3, v146
	v_and_b32_e32 v70, 7, v146
	v_xor_b32_e32 v70, v69, v70
	v_and_b32_e32 v70, 7, v70
	v_lshlrev_b32_e32 v70, 4, v70
	v_lshl_or_b32 v68, v69, 11, v70
	v_add_u32_e32 v69, 0x10000, v68
	v_add_u32_e32 v70, 0x20000, v68
	v_add_u32_e32 v71, 0x30000, v68
	s_and_b32 s98, s9, 7
	s_and_b32 s99, s69, 7
	s_lshl_b32 s99, s99, 3
	s_or_b32 s98, s98, s99
	s_lshl_b32 s98, s98, 18
	s_add_u32 s98, s98, 0x2000000
	s_lshr_b32 s99, s9, 3
	s_lshl_b32 s99, s99, 18
	s_add_u32 s99, s99, 0x9040000
	s_lshl_b32 s42, s42, 10
	s_waitcnt lgkmcnt(0)
	s_mov_b32 m0, s99
	s_add_u32 s98, s100, s98
	s_addc_u32 s99, s101, 0
	s_add_u32 s100, s100, m0
	s_addc_u32 s101, s101, 0
	s_add_u32 m0, s42, 0x0
	s_nop 0
	global_load_lds_dwordx4 v68, s[98:99]
	s_add_u32 m0, s42, 0x1000
	s_nop 0
	global_load_lds_dwordx4 v69, s[98:99]
	s_add_u32 m0, s42, 0x2000
	s_nop 0
	global_load_lds_dwordx4 v70, s[98:99]
	s_add_u32 m0, s42, 0x3000
	s_nop 0
	global_load_lds_dwordx4 v71, s[98:99]
	s_add_u32 m0, s42, 0x8000
	s_nop 0
	global_load_lds_dwordx4 v68, s[100:101]
	s_add_u32 m0, s42, 0x9000
	s_nop 0
	global_load_lds_dwordx4 v69, s[100:101]
	s_add_u32 m0, s42, 0xa000
	s_nop 0
	global_load_lds_dwordx4 v70, s[100:101]
	s_add_u32 m0, s42, 0xb000
	s_nop 0
	global_load_lds_dwordx4 v71, s[100:101]
	s_add_u32 s98, s98, 0x80
	s_addc_u32 s99, s99, 0
	s_add_u32 s100, s100, 0x80
	s_addc_u32 s101, s101, 0
	s_waitcnt vmcnt(0)
	s_waitcnt lgkmcnt(0)
	s_barrier
	s_bitcmp1_b32 s69, 8
	s_cbranch_scc1 .Lprio_h1101
	s_setprio 0
	s_branch .Lprio_j1101

.Lprio_j1101:
.LBB0_1101:
	s_add_i32 s33, s40, 2
	ds_read_b128 v[126:129], v119 offset:32768
	ds_read_b128 v[134:137], v119 offset:34816
	ds_read_b128 v[130:133], v118
	ds_read_b128 v[138:141], v118 offset:2048
	ds_read_b128 v[160:163], v118 offset:4096
	ds_read_b128 v[164:167], v118 offset:6144
	s_waitcnt lgkmcnt(3)
	v_mfma_f32_16x16x32_bf16 v[64:67], v[126:129], v[130:133], v[64:67]
	ds_read_b128 v[168:171], v119 offset:36864
	v_mfma_f32_16x16x32_bf16 v[40:43], v[134:137], v[130:133], v[40:43]
	ds_read_b128 v[172:175], v119 offset:38912
	s_waitcnt lgkmcnt(1)
	v_mfma_f32_16x16x32_bf16 v[28:31], v[168:171], v[130:133], v[28:31]
	s_waitcnt lgkmcnt(0)
	v_mfma_f32_16x16x32_bf16 v[12:15], v[172:175], v[130:133], v[12:15]
	s_add_u32 m0, s42, 0x4000
	s_nop 0
	global_load_lds_dwordx4 v68, s[98:99]
	ds_read_b128 v[176:179], v120
	v_mfma_f32_16x16x32_bf16 v[60:63], v[126:129], v[138:141], v[60:63]
	v_mfma_f32_16x16x32_bf16 v[44:47], v[134:137], v[138:141], v[44:47]
	s_add_u32 m0, s42, 0x5000
	s_nop 0
	global_load_lds_dwordx4 v69, s[98:99]
	ds_read_b128 v[184:187], v120 offset:2048
	v_mfma_f32_16x16x32_bf16 v[24:27], v[168:171], v[138:141], v[24:27]
	v_mfma_f32_16x16x32_bf16 v[8:11], v[172:175], v[138:141], v[8:11]
	s_add_u32 m0, s42, 0x6000
	s_nop 0
	global_load_lds_dwordx4 v70, s[98:99]
	ds_read_b128 v[188:191], v120 offset:4096
	v_mfma_f32_16x16x32_bf16 v[52:55], v[126:129], v[160:163], v[52:55]
	v_mfma_f32_16x16x32_bf16 v[36:39], v[134:137], v[160:163], v[36:39]
	s_add_u32 m0, s42, 0x7000
	s_nop 0
	global_load_lds_dwordx4 v71, s[98:99]
	ds_read_b128 v[196:199], v120 offset:6144
	v_mfma_f32_16x16x32_bf16 v[20:23], v[168:171], v[160:163], v[20:23]
	v_mfma_f32_16x16x32_bf16 v[4:7], v[172:175], v[160:163], v[4:7]
	s_add_u32 m0, s42, 0xc000
	s_nop 0
	global_load_lds_dwordx4 v68, s[100:101]
	ds_read_b128 v[200:203], v121 offset:32768
	v_mfma_f32_16x16x32_bf16 v[48:51], v[126:129], v[164:167], v[48:51]
	v_mfma_f32_16x16x32_bf16 v[32:35], v[134:137], v[164:167], v[32:35]
	s_add_u32 m0, s42, 0xd000
	s_nop 0
	global_load_lds_dwordx4 v69, s[100:101]
	ds_read_b128 v[134:137], v121 offset:34816
	v_mfma_f32_16x16x32_bf16 v[16:19], v[168:171], v[164:167], v[16:19]
	v_mfma_f32_16x16x32_bf16 v[0:3], v[172:175], v[164:167], v[0:3]
	s_add_u32 m0, s42, 0xe000
	s_nop 0
	global_load_lds_dwordx4 v70, s[100:101]
	ds_read_b128 v[168:171], v121 offset:36864
	s_waitcnt lgkmcnt(2)
	v_mfma_f32_16x16x32_bf16 v[64:67], v[200:203], v[176:179], v[64:67]
	s_waitcnt lgkmcnt(1)
	v_mfma_f32_16x16x32_bf16 v[40:43], v[134:137], v[176:179], v[40:43]
	s_add_u32 m0, s42, 0xf000
	s_nop 0
	global_load_lds_dwordx4 v71, s[100:101]
	s_add_u32 s98, s98, 0x80
	s_addc_u32 s99, s99, 0
	s_add_u32 s100, s100, 0x80
	s_addc_u32 s101, s101, 0
	ds_read_b128 v[204:207], v121 offset:38912
	s_waitcnt lgkmcnt(1)
	v_mfma_f32_16x16x32_bf16 v[28:31], v[168:171], v[176:179], v[28:31]
	s_waitcnt lgkmcnt(0)
	v_mfma_f32_16x16x32_bf16 v[12:15], v[204:207], v[176:179], v[12:15]
	v_mfma_f32_16x16x32_bf16 v[60:63], v[200:203], v[184:187], v[60:63]
	v_mfma_f32_16x16x32_bf16 v[44:47], v[134:137], v[184:187], v[44:47]
	v_mfma_f32_16x16x32_bf16 v[24:27], v[168:171], v[184:187], v[24:27]
	v_mfma_f32_16x16x32_bf16 v[8:11], v[204:207], v[184:187], v[8:11]
	v_mfma_f32_16x16x32_bf16 v[52:55], v[200:203], v[188:191], v[52:55]
	v_mfma_f32_16x16x32_bf16 v[36:39], v[134:137], v[188:191], v[36:39]
	v_mfma_f32_16x16x32_bf16 v[20:23], v[168:171], v[188:191], v[20:23]
	v_mfma_f32_16x16x32_bf16 v[4:7], v[204:207], v[188:191], v[4:7]
	v_mfma_f32_16x16x32_bf16 v[48:51], v[200:203], v[196:199], v[48:51]
	v_mfma_f32_16x16x32_bf16 v[32:35], v[134:137], v[196:199], v[32:35]
	v_mfma_f32_16x16x32_bf16 v[16:19], v[168:171], v[196:199], v[16:19]
	v_mfma_f32_16x16x32_bf16 v[0:3], v[204:207], v[196:199], v[0:3]
	s_waitcnt vmcnt(0) lgkmcnt(0)
	s_barrier
	ds_read_b128 v[84:87], v119 offset:49152
	ds_read_b128 v[88:91], v119 offset:51200
	ds_read_b128 v[56:59], v118 offset:16384
	ds_read_b128 v[72:75], v118 offset:18432
	ds_read_b128 v[76:79], v118 offset:20480
	ds_read_b128 v[92:95], v118 offset:22528
	s_waitcnt lgkmcnt(3)
	v_mfma_f32_16x16x32_bf16 v[64:67], v[84:87], v[56:59], v[64:67]
	ds_read_b128 v[134:137], v119 offset:53248
	v_mfma_f32_16x16x32_bf16 v[40:43], v[88:91], v[56:59], v[40:43]
	ds_read_b128 v[168:171], v119 offset:55296
	s_waitcnt lgkmcnt(1)
	v_mfma_f32_16x16x32_bf16 v[28:31], v[134:137], v[56:59], v[28:31]
	s_waitcnt lgkmcnt(0)
	v_mfma_f32_16x16x32_bf16 v[12:15], v[168:171], v[56:59], v[12:15]
	s_add_u32 m0, s42, 0x0
	s_nop 0
	global_load_lds_dwordx4 v68, s[98:99]
	ds_read_b128 v[176:179], v120 offset:16384
	v_mfma_f32_16x16x32_bf16 v[60:63], v[84:87], v[72:75], v[60:63]
	v_mfma_f32_16x16x32_bf16 v[44:47], v[88:91], v[72:75], v[44:47]
	s_add_u32 m0, s42, 0x1000
	s_nop 0
	global_load_lds_dwordx4 v69, s[98:99]
	ds_read_b128 v[184:187], v120 offset:18432
	v_mfma_f32_16x16x32_bf16 v[24:27], v[134:137], v[72:75], v[24:27]
	v_mfma_f32_16x16x32_bf16 v[8:11], v[168:171], v[72:75], v[8:11]
	s_add_u32 m0, s42, 0x2000
	s_nop 0
	global_load_lds_dwordx4 v70, s[98:99]
	ds_read_b128 v[188:191], v120 offset:20480
	v_mfma_f32_16x16x32_bf16 v[52:55], v[84:87], v[76:79], v[52:55]
	v_mfma_f32_16x16x32_bf16 v[36:39], v[88:91], v[76:79], v[36:39]
	s_add_u32 m0, s42, 0x3000
	s_nop 0
	global_load_lds_dwordx4 v71, s[98:99]
	ds_read_b128 v[196:199], v120 offset:22528
	v_mfma_f32_16x16x32_bf16 v[20:23], v[134:137], v[76:79], v[20:23]
	v_mfma_f32_16x16x32_bf16 v[4:7], v[168:171], v[76:79], v[4:7]
	s_add_u32 m0, s42, 0x8000
	s_nop 0
	global_load_lds_dwordx4 v68, s[100:101]
	ds_read_b128 v[200:203], v121 offset:49152
	v_mfma_f32_16x16x32_bf16 v[48:51], v[84:87], v[92:95], v[48:51]
	v_mfma_f32_16x16x32_bf16 v[32:35], v[88:91], v[92:95], v[32:35]
	s_add_u32 m0, s42, 0x9000
	s_nop 0
	global_load_lds_dwordx4 v69, s[100:101]
	ds_read_b128 v[204:207], v121 offset:51200
	v_mfma_f32_16x16x32_bf16 v[16:19], v[134:137], v[92:95], v[16:19]
	v_mfma_f32_16x16x32_bf16 v[0:3], v[168:171], v[92:95], v[0:3]
	s_add_u32 m0, s42, 0xa000
	s_nop 0
	global_load_lds_dwordx4 v70, s[100:101]
	ds_read_b128 v[134:137], v121 offset:53248
	s_waitcnt lgkmcnt(2)
	v_mfma_f32_16x16x32_bf16 v[64:67], v[200:203], v[176:179], v[64:67]
	s_waitcnt lgkmcnt(1)
	v_mfma_f32_16x16x32_bf16 v[40:43], v[204:207], v[176:179], v[40:43]
	s_add_u32 m0, s42, 0xb000
	s_nop 0
	global_load_lds_dwordx4 v71, s[100:101]
	s_add_u32 s98, s98, 0x80
	s_addc_u32 s99, s99, 0
	s_add_u32 s100, s100, 0x80
	s_addc_u32 s101, s101, 0
	ds_read_b128 v[168:171], v121 offset:55296
	s_waitcnt lgkmcnt(1)
	v_mfma_f32_16x16x32_bf16 v[28:31], v[134:137], v[176:179], v[28:31]
	s_waitcnt lgkmcnt(0)
	v_mfma_f32_16x16x32_bf16 v[12:15], v[168:171], v[176:179], v[12:15]
	v_mfma_f32_16x16x32_bf16 v[60:63], v[200:203], v[184:187], v[60:63]
	v_mfma_f32_16x16x32_bf16 v[44:47], v[204:207], v[184:187], v[44:47]
	v_mfma_f32_16x16x32_bf16 v[24:27], v[134:137], v[184:187], v[24:27]
	v_mfma_f32_16x16x32_bf16 v[8:11], v[168:171], v[184:187], v[8:11]
	v_mfma_f32_16x16x32_bf16 v[52:55], v[200:203], v[188:191], v[52:55]
	v_mfma_f32_16x16x32_bf16 v[36:39], v[204:207], v[188:191], v[36:39]
	v_mfma_f32_16x16x32_bf16 v[20:23], v[134:137], v[188:191], v[20:23]
	v_mfma_f32_16x16x32_bf16 v[4:7], v[168:171], v[188:191], v[4:7]
	v_mfma_f32_16x16x32_bf16 v[48:51], v[200:203], v[196:199], v[48:51]
	v_mfma_f32_16x16x32_bf16 v[32:35], v[204:207], v[196:199], v[32:35]
	v_mfma_f32_16x16x32_bf16 v[16:19], v[134:137], v[196:199], v[16:19]
	v_mfma_f32_16x16x32_bf16 v[0:3], v[168:171], v[196:199], v[0:3]
	s_mov_b32 s40, s33
	s_waitcnt vmcnt(0) lgkmcnt(0)
	s_barrier
	s_cmp_lt_u32 s40, 16
	s_cbranch_scc1 .LBB0_1101
	s_setprio 0
	s_waitcnt vmcnt(0)
	s_and_b32 s2, s9, 7
	s_and_b32 s26, s69, 7
	s_lshl_b32 s26, s26, 3
	s_or_b32 s2, s2, s26
	s_lshl_b32 s2, s2, 7
	s_lshr_b32 s26, s9, 3
	s_lshl_b32 s26, s26, 7
	v_readlane_b32 s42, v253, 0
	v_readlane_b32 s43, v253, 1
	s_load_dwordx2 s[98:99], s[42:43], 0x160
	s_load_dwordx2 s[100:101], s[42:43], 0x120
	v_and_b32_e32 v227, 15, v146
	v_bfe_u32 v228, v146, 7, 1
	v_lshl_add_u32 v227, v228, 6, v227
	v_add_u32_e32 v227, s2, v227
	v_bfe_u32 v228, v146, 4, 2
	v_lshlrev_b32_e32 v228, 2, v228
	v_bfe_u32 v218, v146, 6, 1
	v_lshl_add_u32 v228, v218, 6, v228
	v_add_u32_e32 v228, s26, v228
	v_lshlrev_b32_e32 v218, 2, v228
	v_lshl_add_u32 v96, v227, 12, v218
	v_add_u32_e32 v114, 0x10000, v96
	v_add_u32_e32 v115, 0x20000, v96
	v_add_u32_e32 v142, 0x30000, v96
	v_lshrrev_b32_e32 v214, 1, v96
	v_add_u32_e32 v214, 0xdc40000, v214
	v_lshrrev_b32_e32 v215, 1, v114
	v_add_u32_e32 v215, 0xdc40000, v215
	v_lshrrev_b32_e32 v216, 1, v115
	v_add_u32_e32 v216, 0xdc40000, v216
	v_lshrrev_b32_e32 v217, 1, v142
	v_add_u32_e32 v217, 0xdc40000, v217
	v_lshlrev_b32_e32 v222, 2, v227
	v_add_u32_e32 v222, 0xfa9a100, v222
	s_sub_u32 s33, s2, 0x1000
	s_lshr_b32 s33, s33, 10
	s_add_u32 s33, s33, 1
	s_cmp_lt_u32 s2, 0x1000
	s_cselect_b32 s33, 0, s33
	s_mul_i32 s33, s33, 0x3000
	v_add_u32_e32 v219, s33, v218
	v_add_u32_e32 v221, 0xf46e000, v219
	v_add_u32_e32 v219, 0xf460000, v219
	v_mbcnt_lo_u32_b32 v229, -1, 0
	v_mbcnt_hi_u32_b32 v229, -1, v229
	v_xor_b32_e32 v244, 32, v229
	v_xor_b32_e32 v229, 16, v229
	v_lshlrev_b32_e32 v244, 2, v244
	v_lshlrev_b32_e32 v229, 2, v229
	s_waitcnt lgkmcnt(0)
	s_mov_b64 s[42:43], s[98:99]
	global_load_dwordx4 v[160:163], v219, s[98:99]
	global_load_dwordx4 v[164:167], v219, s[98:99] offset:64
	global_load_dwordx4 v[168:171], v219, s[98:99] offset:128
	global_load_dwordx4 v[172:175], v219, s[98:99] offset:192
	global_load_dwordx4 v[176:179], v218, s[100:101]
	global_load_dwordx4 v[180:183], v218, s[100:101] offset:64
	global_load_dwordx4 v[184:187], v218, s[100:101] offset:128
	global_load_dwordx4 v[188:191], v218, s[100:101] offset:192
	global_load_dwordx4 v[192:195], v221, s[98:99]
	global_load_dwordx4 v[196:199], v221, s[98:99] offset:64
	global_load_dwordx4 v[200:203], v221, s[98:99] offset:128
	global_load_dwordx4 v[204:207], v221, s[98:99] offset:192
	global_load_dwordx4 v[56:59], v96, s[42:43]
	global_load_dwordx4 v[80:83], v114, s[42:43]
	global_load_dwordx4 v[98:101], v115, s[42:43]
	global_load_dwordx4 v[126:129], v142, s[42:43]
	global_load_dwordx4 v[68:71], v96, s[42:43] offset:64
	global_load_dwordx4 v[84:87], v114, s[42:43] offset:64
	global_load_dwordx4 v[102:105], v115, s[42:43] offset:64
	global_load_dwordx4 v[130:133], v142, s[42:43] offset:64
	global_load_dwordx4 v[72:75], v96, s[42:43] offset:128
	global_load_dwordx4 v[88:91], v114, s[42:43] offset:128
	global_load_dwordx4 v[106:109], v115, s[42:43] offset:128
	global_load_dwordx4 v[134:137], v142, s[42:43] offset:128
	global_load_dwordx4 v[76:79], v96, s[42:43] offset:192
	global_load_dwordx4 v[92:95], v114, s[42:43] offset:192
	global_load_dwordx4 v[110:113], v115, s[42:43] offset:192
	global_load_dwordx4 v[138:141], v142, s[42:43] offset:192
	v_mov_b32_e32 v223, 0
	v_mov_b32_e32 v224, 0
	v_mov_b32_e32 v225, 0
	v_mov_b32_e32 v226, 0
	s_waitcnt vmcnt(16)
	v_pk_add_f32 v[192:193], v[192:193], 1.0 op_sel_hi:[1,0]
	v_pk_add_f32 v[194:195], v[194:195], 1.0 op_sel_hi:[1,0]
	v_pk_mul_f32 v[192:193], v[176:177], v[192:193]
	v_pk_mul_f32 v[194:195], v[178:179], v[194:195]
	v_pk_add_f32 v[196:197], v[196:197], 1.0 op_sel_hi:[1,0]
	v_pk_add_f32 v[198:199], v[198:199], 1.0 op_sel_hi:[1,0]
	v_pk_mul_f32 v[196:197], v[180:181], v[196:197]
	v_pk_mul_f32 v[198:199], v[182:183], v[198:199]
	v_pk_add_f32 v[200:201], v[200:201], 1.0 op_sel_hi:[1,0]
	v_pk_add_f32 v[202:203], v[202:203], 1.0 op_sel_hi:[1,0]
	v_pk_mul_f32 v[200:201], v[184:185], v[200:201]
	v_pk_mul_f32 v[202:203], v[186:187], v[202:203]
	v_pk_add_f32 v[204:205], v[204:205], 1.0 op_sel_hi:[1,0]
	v_pk_add_f32 v[206:207], v[206:207], 1.0 op_sel_hi:[1,0]
	v_pk_mul_f32 v[204:205], v[188:189], v[204:205]
	v_pk_mul_f32 v[206:207], v[190:191], v[206:207]
	s_waitcnt vmcnt(15)
	v_pk_fma_f32 v[64:65], v[64:65], v[160:161], v[56:57]
	v_pk_fma_f32 v[66:67], v[66:67], v[162:163], v[58:59]
	global_store_dwordx4 v96, v[64:67], s[98:99]
	v_pk_mul_f32 v[56:57], v[192:193], v[64:65]
	v_pk_mul_f32 v[58:59], v[194:195], v[66:67]
	v_cvt_pk_bf16_f32 v56, v56, v57
	v_cvt_pk_bf16_f32 v57, v58, v59
	global_store_dwordx2 v214, v[56:57], s[98:99]
	v_pk_mul_f32 v[58:59], v[64:65], v[64:65]
	v_pk_fma_f32 v[58:59], v[66:67], v[66:67], v[58:59]
	v_add_f32_e32 v227, v58, v59
	v_add_f32_e32 v223, v223, v227
	s_waitcnt vmcnt(16)
	v_pk_fma_f32 v[60:61], v[60:61], v[160:161], v[80:81]
	v_pk_fma_f32 v[62:63], v[62:63], v[162:163], v[82:83]
	global_store_dwordx4 v114, v[60:63], s[98:99]
	v_pk_mul_f32 v[80:81], v[192:193], v[60:61]
	v_pk_mul_f32 v[82:83], v[194:195], v[62:63]
	v_cvt_pk_bf16_f32 v80, v80, v81
	v_cvt_pk_bf16_f32 v81, v82, v83
	global_store_dwordx2 v215, v[80:81], s[98:99]
	v_pk_mul_f32 v[82:83], v[60:61], v[60:61]
	v_pk_fma_f32 v[82:83], v[62:63], v[62:63], v[82:83]
	v_add_f32_e32 v227, v82, v83
	v_add_f32_e32 v224, v224, v227
	s_waitcnt vmcnt(17)
	v_pk_fma_f32 v[52:53], v[52:53], v[160:161], v[98:99]
	v_pk_fma_f32 v[54:55], v[54:55], v[162:163], v[100:101]
	global_store_dwordx4 v115, v[52:55], s[98:99]
	v_pk_mul_f32 v[98:99], v[192:193], v[52:53]
	v_pk_mul_f32 v[100:101], v[194:195], v[54:55]
	v_cvt_pk_bf16_f32 v98, v98, v99
	v_cvt_pk_bf16_f32 v99, v100, v101
	global_store_dwordx2 v216, v[98:99], s[98:99]
	v_pk_mul_f32 v[100:101], v[52:53], v[52:53]
	v_pk_fma_f32 v[100:101], v[54:55], v[54:55], v[100:101]
	v_add_f32_e32 v227, v100, v101
	v_add_f32_e32 v225, v225, v227
	s_waitcnt vmcnt(18)
	v_pk_fma_f32 v[48:49], v[48:49], v[160:161], v[126:127]
	v_pk_fma_f32 v[50:51], v[50:51], v[162:163], v[128:129]
	global_store_dwordx4 v142, v[48:51], s[98:99]
	v_pk_mul_f32 v[126:127], v[192:193], v[48:49]
	v_pk_mul_f32 v[128:129], v[194:195], v[50:51]
	v_cvt_pk_bf16_f32 v126, v126, v127
	v_cvt_pk_bf16_f32 v127, v128, v129
	global_store_dwordx2 v217, v[126:127], s[98:99]
	v_pk_mul_f32 v[128:129], v[48:49], v[48:49]
	v_pk_fma_f32 v[128:129], v[50:51], v[50:51], v[128:129]
	v_add_f32_e32 v227, v128, v129
	v_add_f32_e32 v226, v226, v227
	s_waitcnt vmcnt(19)
	v_pk_fma_f32 v[40:41], v[40:41], v[164:165], v[68:69]
	v_pk_fma_f32 v[42:43], v[42:43], v[166:167], v[70:71]
	global_store_dwordx4 v96, v[40:43], s[98:99] offset:64
	v_pk_mul_f32 v[68:69], v[196:197], v[40:41]
	v_pk_mul_f32 v[70:71], v[198:199], v[42:43]
	v_cvt_pk_bf16_f32 v68, v68, v69
	v_cvt_pk_bf16_f32 v69, v70, v71
	global_store_dwordx2 v214, v[68:69], s[98:99] offset:32
	v_pk_mul_f32 v[70:71], v[40:41], v[40:41]
	v_pk_fma_f32 v[70:71], v[42:43], v[42:43], v[70:71]
	v_add_f32_e32 v227, v70, v71
	v_add_f32_e32 v223, v223, v227
	s_waitcnt vmcnt(20)
	v_pk_fma_f32 v[44:45], v[44:45], v[164:165], v[84:85]
	v_pk_fma_f32 v[46:47], v[46:47], v[166:167], v[86:87]
	global_store_dwordx4 v114, v[44:47], s[98:99] offset:64
	v_pk_mul_f32 v[84:85], v[196:197], v[44:45]
	v_pk_mul_f32 v[86:87], v[198:199], v[46:47]
	v_cvt_pk_bf16_f32 v84, v84, v85
	v_cvt_pk_bf16_f32 v85, v86, v87
	global_store_dwordx2 v215, v[84:85], s[98:99] offset:32
	v_pk_mul_f32 v[86:87], v[44:45], v[44:45]
	v_pk_fma_f32 v[86:87], v[46:47], v[46:47], v[86:87]
	v_add_f32_e32 v227, v86, v87
	v_add_f32_e32 v224, v224, v227
	s_waitcnt vmcnt(21)
	v_pk_fma_f32 v[36:37], v[36:37], v[164:165], v[102:103]
	v_pk_fma_f32 v[38:39], v[38:39], v[166:167], v[104:105]
	global_store_dwordx4 v115, v[36:39], s[98:99] offset:64
	v_pk_mul_f32 v[102:103], v[196:197], v[36:37]
	v_pk_mul_f32 v[104:105], v[198:199], v[38:39]
	v_cvt_pk_bf16_f32 v102, v102, v103
	v_cvt_pk_bf16_f32 v103, v104, v105
	global_store_dwordx2 v216, v[102:103], s[98:99] offset:32
	v_pk_mul_f32 v[104:105], v[36:37], v[36:37]
	v_pk_fma_f32 v[104:105], v[38:39], v[38:39], v[104:105]
	v_add_f32_e32 v227, v104, v105
	v_add_f32_e32 v225, v225, v227
	s_waitcnt vmcnt(22)
	v_pk_fma_f32 v[32:33], v[32:33], v[164:165], v[130:131]
	v_pk_fma_f32 v[34:35], v[34:35], v[166:167], v[132:133]
	global_store_dwordx4 v142, v[32:35], s[98:99] offset:64
	v_pk_mul_f32 v[130:131], v[196:197], v[32:33]
	v_pk_mul_f32 v[132:133], v[198:199], v[34:35]
	v_cvt_pk_bf16_f32 v130, v130, v131
	v_cvt_pk_bf16_f32 v131, v132, v133
	global_store_dwordx2 v217, v[130:131], s[98:99] offset:32
	v_pk_mul_f32 v[132:133], v[32:33], v[32:33]
	v_pk_fma_f32 v[132:133], v[34:35], v[34:35], v[132:133]
	v_add_f32_e32 v227, v132, v133
	v_add_f32_e32 v226, v226, v227
	s_waitcnt vmcnt(23)
	v_pk_fma_f32 v[28:29], v[28:29], v[168:169], v[72:73]
	v_pk_fma_f32 v[30:31], v[30:31], v[170:171], v[74:75]
	global_store_dwordx4 v96, v[28:31], s[98:99] offset:128
	v_pk_mul_f32 v[72:73], v[200:201], v[28:29]
	v_pk_mul_f32 v[74:75], v[202:203], v[30:31]
	v_cvt_pk_bf16_f32 v72, v72, v73
	v_cvt_pk_bf16_f32 v73, v74, v75
	global_store_dwordx2 v214, v[72:73], s[98:99] offset:64
	v_pk_mul_f32 v[74:75], v[28:29], v[28:29]
	v_pk_fma_f32 v[74:75], v[30:31], v[30:31], v[74:75]
	v_add_f32_e32 v227, v74, v75
	v_add_f32_e32 v223, v223, v227
	s_waitcnt vmcnt(24)
	v_pk_fma_f32 v[24:25], v[24:25], v[168:169], v[88:89]
	v_pk_fma_f32 v[26:27], v[26:27], v[170:171], v[90:91]
	global_store_dwordx4 v114, v[24:27], s[98:99] offset:128
	v_pk_mul_f32 v[88:89], v[200:201], v[24:25]
	v_pk_mul_f32 v[90:91], v[202:203], v[26:27]
	v_cvt_pk_bf16_f32 v88, v88, v89
	v_cvt_pk_bf16_f32 v89, v90, v91
	global_store_dwordx2 v215, v[88:89], s[98:99] offset:64
	v_pk_mul_f32 v[90:91], v[24:25], v[24:25]
	v_pk_fma_f32 v[90:91], v[26:27], v[26:27], v[90:91]
	v_add_f32_e32 v227, v90, v91
	v_add_f32_e32 v224, v224, v227
	s_waitcnt vmcnt(25)
	v_pk_fma_f32 v[20:21], v[20:21], v[168:169], v[106:107]
	v_pk_fma_f32 v[22:23], v[22:23], v[170:171], v[108:109]
	global_store_dwordx4 v115, v[20:23], s[98:99] offset:128
	v_pk_mul_f32 v[106:107], v[200:201], v[20:21]
	v_pk_mul_f32 v[108:109], v[202:203], v[22:23]
	v_cvt_pk_bf16_f32 v106, v106, v107
	v_cvt_pk_bf16_f32 v107, v108, v109
	global_store_dwordx2 v216, v[106:107], s[98:99] offset:64
	v_pk_mul_f32 v[108:109], v[20:21], v[20:21]
	v_pk_fma_f32 v[108:109], v[22:23], v[22:23], v[108:109]
	v_add_f32_e32 v227, v108, v109
	v_add_f32_e32 v225, v225, v227
	s_waitcnt vmcnt(26)
	v_pk_fma_f32 v[16:17], v[16:17], v[168:169], v[134:135]
	v_pk_fma_f32 v[18:19], v[18:19], v[170:171], v[136:137]
	global_store_dwordx4 v142, v[16:19], s[98:99] offset:128
	v_pk_mul_f32 v[134:135], v[200:201], v[16:17]
	v_pk_mul_f32 v[136:137], v[202:203], v[18:19]
	v_cvt_pk_bf16_f32 v134, v134, v135
	v_cvt_pk_bf16_f32 v135, v136, v137
	global_store_dwordx2 v217, v[134:135], s[98:99] offset:64
	v_pk_mul_f32 v[136:137], v[16:17], v[16:17]
	v_pk_fma_f32 v[136:137], v[18:19], v[18:19], v[136:137]
	v_add_f32_e32 v227, v136, v137
	v_add_f32_e32 v226, v226, v227
	s_waitcnt vmcnt(27)
	v_pk_fma_f32 v[12:13], v[12:13], v[172:173], v[76:77]
	v_pk_fma_f32 v[14:15], v[14:15], v[174:175], v[78:79]
	global_store_dwordx4 v96, v[12:15], s[98:99] offset:192
	v_pk_mul_f32 v[76:77], v[204:205], v[12:13]
	v_pk_mul_f32 v[78:79], v[206:207], v[14:15]
	v_cvt_pk_bf16_f32 v76, v76, v77
	v_cvt_pk_bf16_f32 v77, v78, v79
	global_store_dwordx2 v214, v[76:77], s[98:99] offset:96
	v_pk_mul_f32 v[78:79], v[12:13], v[12:13]
	v_pk_fma_f32 v[78:79], v[14:15], v[14:15], v[78:79]
	v_add_f32_e32 v227, v78, v79
	v_add_f32_e32 v223, v223, v227
	s_waitcnt vmcnt(28)
	v_pk_fma_f32 v[8:9], v[8:9], v[172:173], v[92:93]
	v_pk_fma_f32 v[10:11], v[10:11], v[174:175], v[94:95]
	global_store_dwordx4 v114, v[8:11], s[98:99] offset:192
	v_pk_mul_f32 v[92:93], v[204:205], v[8:9]
	v_pk_mul_f32 v[94:95], v[206:207], v[10:11]
	v_cvt_pk_bf16_f32 v92, v92, v93
	v_cvt_pk_bf16_f32 v93, v94, v95
	global_store_dwordx2 v215, v[92:93], s[98:99] offset:96
	v_pk_mul_f32 v[94:95], v[8:9], v[8:9]
	v_pk_fma_f32 v[94:95], v[10:11], v[10:11], v[94:95]
	v_add_f32_e32 v227, v94, v95
	v_add_f32_e32 v224, v224, v227
	s_waitcnt vmcnt(29)
	v_pk_fma_f32 v[4:5], v[4:5], v[172:173], v[110:111]
	v_pk_fma_f32 v[6:7], v[6:7], v[174:175], v[112:113]
	global_store_dwordx4 v115, v[4:7], s[98:99] offset:192
	v_pk_mul_f32 v[110:111], v[204:205], v[4:5]
	v_pk_mul_f32 v[112:113], v[206:207], v[6:7]
	v_cvt_pk_bf16_f32 v110, v110, v111
	v_cvt_pk_bf16_f32 v111, v112, v113
	global_store_dwordx2 v216, v[110:111], s[98:99] offset:96
	v_pk_mul_f32 v[112:113], v[4:5], v[4:5]
	v_pk_fma_f32 v[112:113], v[6:7], v[6:7], v[112:113]
	v_add_f32_e32 v227, v112, v113
	v_add_f32_e32 v225, v225, v227
	s_waitcnt vmcnt(30)
	v_pk_fma_f32 v[0:1], v[0:1], v[172:173], v[138:139]
	v_pk_fma_f32 v[2:3], v[2:3], v[174:175], v[140:141]
	global_store_dwordx4 v142, v[0:3], s[98:99] offset:192
	v_pk_mul_f32 v[138:139], v[204:205], v[0:1]
	v_pk_mul_f32 v[140:141], v[206:207], v[2:3]
	v_cvt_pk_bf16_f32 v138, v138, v139
	v_cvt_pk_bf16_f32 v139, v140, v141
	global_store_dwordx2 v217, v[138:139], s[98:99] offset:96
	v_pk_mul_f32 v[140:141], v[0:1], v[0:1]
	v_pk_fma_f32 v[140:141], v[2:3], v[2:3], v[140:141]
	v_add_f32_e32 v227, v140, v141
	v_add_f32_e32 v226, v226, v227
	ds_bpermute_b32 v56, v229, v223
	ds_bpermute_b32 v80, v229, v224
	ds_bpermute_b32 v98, v229, v225
	ds_bpermute_b32 v126, v229, v226
	s_waitcnt lgkmcnt(0)
	v_add_f32_e32 v223, v223, v56
	v_add_f32_e32 v224, v224, v80
	v_add_f32_e32 v225, v225, v98
	v_add_f32_e32 v226, v226, v126
	ds_bpermute_b32 v56, v244, v223
	ds_bpermute_b32 v80, v244, v224
	ds_bpermute_b32 v98, v244, v225
	ds_bpermute_b32 v126, v244, v226
	s_waitcnt lgkmcnt(0)
	v_add_f32_e32 v223, v223, v56
	v_add_f32_e32 v224, v224, v80
	v_add_f32_e32 v225, v225, v98
	v_add_f32_e32 v226, v226, v126
	s_mov_b64 exec, 0xffff
	global_atomic_add_f32 v222, v223, s[98:99]
	global_atomic_add_f32 v222, v224, s[98:99] offset:64
	global_atomic_add_f32 v222, v225, s[98:99] offset:128
	global_atomic_add_f32 v222, v226, s[98:99] offset:192
	s_mov_b64 exec, -1
	s_mov_b32 s98, 0
	s_branch .LBB0_1099

.LBB0_1165:
	s_and_b32 s0, s45, 7
	s_lshl_b32 s0, s0, 3
	s_lshr_b32 s1, s3, 3
	s_or_b32 s0, s0, s1
	s_lshl_b32 s46, s0, 7
	v_or_b32_e32 v0, s46, v149
	v_lshl_or_b32 v130, v0, 11, v129
	v_lshl_add_u64 v[30:31], s[22:23], 0, v[130:131]
	v_add_co_u32_e32 v4, vcc, 0x10000, v30
	s_lshl_b32 s1, s45, 4
	s_nop 0
	v_addc_co_u32_e32 v5, vcc, 0, v31, vcc
	s_and_b32 s0, s1, 0x7fffff80
	v_add_co_u32_e32 v12, vcc, 0x20000, v30
	v_or_b32_e32 v0, s0, v149
	s_nop 0
	v_addc_co_u32_e32 v13, vcc, 0, v31, vcc
	v_lshl_or_b32 v24, v0, 11, v129
	v_add_co_u32_e32 v16, vcc, 0x30000, v30
	v_mov_b32_e32 v25, v131
	s_nop 0
	v_addc_co_u32_e32 v17, vcc, 0, v31, vcc
	v_lshl_add_u64 v[52:53], s[20:21], 0, v[24:25]
	v_add_co_u32_e32 v18, vcc, s8, v52
	s_nop 0
	v_addc_co_u32_e32 v19, vcc, 0, v53, vcc
	v_add_co_u32_e32 v28, vcc, s9, v52
	s_nop 0
	v_addc_co_u32_e32 v29, vcc, 0, v53, vcc
	v_add_co_u32_e32 v58, vcc, s38, v52
	s_nop 0
	v_addc_co_u32_e32 v59, vcc, 0, v53, vcc
	s_nop 0
	s_nop 0
	s_nop 0
	s_movk_i32 s1, 0x100
	s_mov_b32 s6, s37
	v_mov_b32_e32 v8, 0
	v_mov_b32_e32 v9, v131
	v_mov_b32_e32 v10, v131
	v_mov_b32_e32 v11, v131
	v_mov_b32_e32 v26, 0
	v_mov_b32_e32 v27, v131
	v_mov_b32_e32 v28, v131
	v_mov_b32_e32 v29, v131
	v_mov_b32_e32 v16, 0
	v_mov_b32_e32 v17, v131
	v_mov_b32_e32 v18, v131
	v_mov_b32_e32 v19, v131
	v_mov_b32_e32 v60, 0
	v_mov_b32_e32 v61, v131
	v_lshl_add_u64 v[58:59], v[52:53], 0, s[18:19]
	v_lshl_add_u64 v[104:105], v[52:53], 0, s[30:31]
	v_lshl_add_u64 v[106:107], v[52:53], 0, s[34:35]
	v_lshl_add_u64 v[108:109], v[30:31], 0, s[18:19]
	v_lshl_add_u64 v[110:111], v[30:31], 0, s[30:31]
	v_lshl_add_u64 v[112:113], v[30:31], 0, s[34:35]
	s_barrier
	v_mov_b32_e32 v88, 0
	v_mov_b32_e32 v89, v131
	v_mov_b32_e32 v90, v131
	v_mov_b32_e32 v91, v131
	v_mov_b32_e32 v76, 0
	v_mov_b32_e32 v77, v131
	v_mov_b32_e32 v78, v131
	v_mov_b32_e32 v79, v131
	v_mov_b32_e32 v80, 0
	v_mov_b32_e32 v81, v131
	v_mov_b32_e32 v82, v131
	v_mov_b32_e32 v83, v131
	v_mov_b32_e32 v84, 0
	v_mov_b32_e32 v85, v131
	v_mov_b32_e32 v86, v131
	v_mov_b32_e32 v87, v131
	v_mov_b32_e32 v74, v131
	v_mov_b32_e32 v75, v131
	v_mov_b32_e32 v62, v131
	v_mov_b32_e32 v63, v131
	v_mov_b32_e32 v36, 0
	v_mov_b32_e32 v37, v131
	v_mov_b32_e32 v38, v131
	v_mov_b32_e32 v39, v131
	v_mov_b32_e32 v54, 0
	v_mov_b32_e32 v55, v131
	v_mov_b32_e32 v56, v131
	v_mov_b32_e32 v57, v131
	v_mov_b32_e32 v32, 0
	v_mov_b32_e32 v33, v131
	v_mov_b32_e32 v34, v131
	v_mov_b32_e32 v35, v131
	v_mov_b32_e32 v64, 0
	v_mov_b32_e32 v65, v131
	v_mov_b32_e32 v66, v131
	v_mov_b32_e32 v67, v131
	v_mov_b32_e32 v40, 0
	v_mov_b32_e32 v41, v131
	v_mov_b32_e32 v42, v131
	v_mov_b32_e32 v43, v131
	v_mov_b32_e32 v48, 0
	v_mov_b32_e32 v49, v131
	v_mov_b32_e32 v50, v131
	v_mov_b32_e32 v51, v131
	v_mov_b32_e32 v68, 0
	v_mov_b32_e32 v69, v131
	v_mov_b32_e32 v70, v131
	v_mov_b32_e32 v71, v131
	v_mov_b32_e32 v72, 0
	v_mov_b32_e32 v73, v131
	v_readlane_b32 s100, v253, 0
	v_readlane_b32 s101, v253, 1
	s_load_dwordx2 s[100:101], s[100:101], 0x160
	v_lshrrev_b32_e32 v7, 6, v146
	s_nop 0
	v_readfirstlane_b32 s10, v7
	v_lshrrev_b32_e32 v5, 3, v146
	v_and_b32_e32 v6, 7, v146
	v_xor_b32_e32 v6, v5, v6
	v_and_b32_e32 v6, 7, v6
	v_lshlrev_b32_e32 v6, 4, v6
	v_lshl_or_b32 v4, v5, 11, v6
	v_add_u32_e32 v5, 0x10000, v4
	v_add_u32_e32 v6, 0x20000, v4
	v_add_u32_e32 v7, 0x30000, v4
	s_and_b32 s98, s45, 7
	s_lshl_b32 s98, s98, 3
	s_and_b32 s99, s69, 7
	s_or_b32 s98, s98, s99
	s_lshl_b32 s98, s98, 18
	s_add_u32 s98, s98, 0xdc40000
	s_lshr_b32 s99, s45, 3
	s_lshl_b32 s99, s99, 18
	s_add_u32 s99, s99, 0x8740000
	s_lshl_b32 s10, s10, 10
	s_waitcnt lgkmcnt(0)
	s_mov_b32 m0, s99
	s_add_u32 s98, s100, s98
	s_addc_u32 s99, s101, 0
	s_add_u32 s100, s100, m0
	s_addc_u32 s101, s101, 0
	s_add_u32 m0, s10, 0x0
	s_nop 0
	global_load_lds_dwordx4 v4, s[98:99]
	s_add_u32 m0, s10, 0x1000
	s_nop 0
	global_load_lds_dwordx4 v5, s[98:99]
	s_add_u32 m0, s10, 0x2000
	s_nop 0
	global_load_lds_dwordx4 v6, s[98:99]
	s_add_u32 m0, s10, 0x3000
	s_nop 0
	global_load_lds_dwordx4 v7, s[98:99]
	s_add_u32 m0, s10, 0x8000
	s_nop 0
	global_load_lds_dwordx4 v4, s[100:101]
	s_add_u32 m0, s10, 0x9000
	s_nop 0
	global_load_lds_dwordx4 v5, s[100:101]
	s_add_u32 m0, s10, 0xa000
	s_nop 0
	global_load_lds_dwordx4 v6, s[100:101]
	s_add_u32 m0, s10, 0xb000
	s_nop 0
	global_load_lds_dwordx4 v7, s[100:101]
	s_add_u32 s98, s98, 0x80
	s_addc_u32 s99, s99, 0
	s_add_u32 s100, s100, 0x80
	s_addc_u32 s101, s101, 0
	s_waitcnt vmcnt(0)
	s_waitcnt lgkmcnt(0)
	s_barrier
	s_bitcmp1_b32 s69, 8
	s_cbranch_scc1 .Lprio_h1166
	s_setprio 0
	s_branch .Lprio_j1166

.Lprio_j1166:
.LBB0_1166:
	s_add_i32 s2, s6, 2
	ds_read_b128 v[114:117], v171 offset:32768
	ds_read_b128 v[122:125], v171 offset:34816
	ds_read_b128 v[118:121], v155
	ds_read_b128 v[140:143], v155 offset:2048
	ds_read_b128 v[160:163], v155 offset:4096
	ds_read_b128 v[164:167], v155 offset:6144
	s_waitcnt lgkmcnt(3)
	v_mfma_f32_16x16x32_bf16 v[8:11], v[114:117], v[118:121], v[8:11]
	ds_read_b128 v[188:191], v171 offset:36864
	v_mfma_f32_16x16x32_bf16 v[26:29], v[122:125], v[118:121], v[26:29]
	ds_read_b128 v[192:195], v171 offset:38912
	s_waitcnt lgkmcnt(1)
	v_mfma_f32_16x16x32_bf16 v[16:19], v[188:191], v[118:121], v[16:19]
	s_waitcnt lgkmcnt(0)
	v_mfma_f32_16x16x32_bf16 v[60:63], v[192:195], v[118:121], v[60:63]
	s_add_u32 m0, s10, 0x4000
	s_nop 0
	global_load_lds_dwordx4 v4, s[98:99]
	ds_read_b128 v[196:199], v172
	v_mfma_f32_16x16x32_bf16 v[36:39], v[114:117], v[140:143], v[36:39]
	v_mfma_f32_16x16x32_bf16 v[54:57], v[122:125], v[140:143], v[54:57]
	s_add_u32 m0, s10, 0x5000
	s_nop 0
	global_load_lds_dwordx4 v5, s[98:99]
	ds_read_b128 v[204:207], v172 offset:2048
	v_mfma_f32_16x16x32_bf16 v[32:35], v[188:191], v[140:143], v[32:35]
	v_mfma_f32_16x16x32_bf16 v[64:67], v[192:195], v[140:143], v[64:67]
	s_add_u32 m0, s10, 0x6000
	s_nop 0
	global_load_lds_dwordx4 v6, s[98:99]
	ds_read_b128 v[208:211], v172 offset:4096
	v_mfma_f32_16x16x32_bf16 v[40:43], v[114:117], v[160:163], v[40:43]
	v_mfma_f32_16x16x32_bf16 v[88:91], v[122:125], v[160:163], v[88:91]
	s_add_u32 m0, s10, 0x7000
	s_nop 0
	global_load_lds_dwordx4 v7, s[98:99]
	ds_read_b128 v[216:219], v172 offset:6144
	v_mfma_f32_16x16x32_bf16 v[48:51], v[188:191], v[160:163], v[48:51]
	v_mfma_f32_16x16x32_bf16 v[76:79], v[192:195], v[160:163], v[76:79]
	s_add_u32 m0, s10, 0xc000
	s_nop 0
	global_load_lds_dwordx4 v4, s[100:101]
	ds_read_b128 v[222:225], v173 offset:32768
	v_mfma_f32_16x16x32_bf16 v[80:83], v[114:117], v[164:167], v[80:83]
	v_mfma_f32_16x16x32_bf16 v[84:87], v[122:125], v[164:167], v[84:87]
	s_add_u32 m0, s10, 0xd000
	s_nop 0
	global_load_lds_dwordx4 v5, s[100:101]
	ds_read_b128 v[122:125], v173 offset:34816
	v_mfma_f32_16x16x32_bf16 v[68:71], v[188:191], v[164:167], v[68:71]
	v_mfma_f32_16x16x32_bf16 v[72:75], v[192:195], v[164:167], v[72:75]
	s_add_u32 m0, s10, 0xe000
	s_nop 0
	global_load_lds_dwordx4 v6, s[100:101]
	ds_read_b128 v[188:191], v173 offset:36864
	s_waitcnt lgkmcnt(2)
	v_mfma_f32_16x16x32_bf16 v[8:11], v[222:225], v[196:199], v[8:11]
	s_waitcnt lgkmcnt(1)
	v_mfma_f32_16x16x32_bf16 v[26:29], v[122:125], v[196:199], v[26:29]
	s_add_u32 m0, s10, 0xf000
	s_nop 0
	global_load_lds_dwordx4 v7, s[100:101]
	s_add_u32 s98, s98, 0x80
	s_addc_u32 s99, s99, 0
	s_add_u32 s100, s100, 0x80
	s_addc_u32 s101, s101, 0
	ds_read_b128 v[226:229], v173 offset:38912
	s_waitcnt lgkmcnt(1)
	v_mfma_f32_16x16x32_bf16 v[16:19], v[188:191], v[196:199], v[16:19]
	s_waitcnt lgkmcnt(0)
	v_mfma_f32_16x16x32_bf16 v[60:63], v[226:229], v[196:199], v[60:63]
	v_mfma_f32_16x16x32_bf16 v[36:39], v[222:225], v[204:207], v[36:39]
	v_mfma_f32_16x16x32_bf16 v[54:57], v[122:125], v[204:207], v[54:57]
	v_mfma_f32_16x16x32_bf16 v[32:35], v[188:191], v[204:207], v[32:35]
	v_mfma_f32_16x16x32_bf16 v[64:67], v[226:229], v[204:207], v[64:67]
	v_mfma_f32_16x16x32_bf16 v[40:43], v[222:225], v[208:211], v[40:43]
	v_mfma_f32_16x16x32_bf16 v[88:91], v[122:125], v[208:211], v[88:91]
	v_mfma_f32_16x16x32_bf16 v[48:51], v[188:191], v[208:211], v[48:51]
	v_mfma_f32_16x16x32_bf16 v[76:79], v[226:229], v[208:211], v[76:79]
	v_mfma_f32_16x16x32_bf16 v[80:83], v[222:225], v[216:219], v[80:83]
	v_mfma_f32_16x16x32_bf16 v[84:87], v[122:125], v[216:219], v[84:87]
	v_mfma_f32_16x16x32_bf16 v[68:71], v[188:191], v[216:219], v[68:71]
	v_mfma_f32_16x16x32_bf16 v[72:75], v[226:229], v[216:219], v[72:75]
	s_waitcnt vmcnt(0) lgkmcnt(0)
	s_barrier
	ds_read_b128 v[92:95], v171 offset:49152
	ds_read_b128 v[96:99], v171 offset:51200
	ds_read_b128 v[0:3], v155 offset:16384
	ds_read_b128 v[12:15], v155 offset:18432
	ds_read_b128 v[20:23], v155 offset:20480
	ds_read_b128 v[100:103], v155 offset:22528
	s_waitcnt lgkmcnt(3)
	v_mfma_f32_16x16x32_bf16 v[8:11], v[92:95], v[0:3], v[8:11]
	ds_read_b128 v[122:125], v171 offset:53248
	v_mfma_f32_16x16x32_bf16 v[26:29], v[96:99], v[0:3], v[26:29]
	ds_read_b128 v[188:191], v171 offset:55296
	s_waitcnt lgkmcnt(1)
	v_mfma_f32_16x16x32_bf16 v[16:19], v[122:125], v[0:3], v[16:19]
	s_waitcnt lgkmcnt(0)
	v_mfma_f32_16x16x32_bf16 v[60:63], v[188:191], v[0:3], v[60:63]
	s_add_u32 m0, s10, 0x0
	s_nop 0
	global_load_lds_dwordx4 v4, s[98:99]
	ds_read_b128 v[196:199], v172 offset:16384
	v_mfma_f32_16x16x32_bf16 v[36:39], v[92:95], v[12:15], v[36:39]
	v_mfma_f32_16x16x32_bf16 v[54:57], v[96:99], v[12:15], v[54:57]
	s_add_u32 m0, s10, 0x1000
	s_nop 0
	global_load_lds_dwordx4 v5, s[98:99]
	ds_read_b128 v[204:207], v172 offset:18432
	v_mfma_f32_16x16x32_bf16 v[32:35], v[122:125], v[12:15], v[32:35]
	v_mfma_f32_16x16x32_bf16 v[64:67], v[188:191], v[12:15], v[64:67]
	s_add_u32 m0, s10, 0x2000
	s_nop 0
	global_load_lds_dwordx4 v6, s[98:99]
	ds_read_b128 v[208:211], v172 offset:20480
	v_mfma_f32_16x16x32_bf16 v[40:43], v[92:95], v[20:23], v[40:43]
	v_mfma_f32_16x16x32_bf16 v[88:91], v[96:99], v[20:23], v[88:91]
	s_add_u32 m0, s10, 0x3000
	s_nop 0
	global_load_lds_dwordx4 v7, s[98:99]
	ds_read_b128 v[216:219], v172 offset:22528
	v_mfma_f32_16x16x32_bf16 v[48:51], v[122:125], v[20:23], v[48:51]
	v_mfma_f32_16x16x32_bf16 v[76:79], v[188:191], v[20:23], v[76:79]
	s_add_u32 m0, s10, 0x8000
	s_nop 0
	global_load_lds_dwordx4 v4, s[100:101]
	ds_read_b128 v[222:225], v173 offset:49152
	v_mfma_f32_16x16x32_bf16 v[80:83], v[92:95], v[100:103], v[80:83]
	v_mfma_f32_16x16x32_bf16 v[84:87], v[96:99], v[100:103], v[84:87]
	s_add_u32 m0, s10, 0x9000
	s_nop 0
	global_load_lds_dwordx4 v5, s[100:101]
	ds_read_b128 v[226:229], v173 offset:51200
	v_mfma_f32_16x16x32_bf16 v[68:71], v[122:125], v[100:103], v[68:71]
	v_mfma_f32_16x16x32_bf16 v[72:75], v[188:191], v[100:103], v[72:75]
	s_add_u32 m0, s10, 0xa000
	s_nop 0
	global_load_lds_dwordx4 v6, s[100:101]
	ds_read_b128 v[122:125], v173 offset:53248
	s_waitcnt lgkmcnt(2)
	v_mfma_f32_16x16x32_bf16 v[8:11], v[222:225], v[196:199], v[8:11]
	s_waitcnt lgkmcnt(1)
	v_mfma_f32_16x16x32_bf16 v[26:29], v[226:229], v[196:199], v[26:29]
	s_add_u32 m0, s10, 0xb000
	s_nop 0
	global_load_lds_dwordx4 v7, s[100:101]
	s_add_u32 s98, s98, 0x80
	s_addc_u32 s99, s99, 0
	s_add_u32 s100, s100, 0x80
	s_addc_u32 s101, s101, 0
	ds_read_b128 v[188:191], v173 offset:55296
	s_waitcnt lgkmcnt(1)
	v_mfma_f32_16x16x32_bf16 v[16:19], v[122:125], v[196:199], v[16:19]
	s_waitcnt lgkmcnt(0)
	v_mfma_f32_16x16x32_bf16 v[60:63], v[188:191], v[196:199], v[60:63]
	v_mfma_f32_16x16x32_bf16 v[36:39], v[222:225], v[204:207], v[36:39]
	v_mfma_f32_16x16x32_bf16 v[54:57], v[226:229], v[204:207], v[54:57]
	v_mfma_f32_16x16x32_bf16 v[32:35], v[122:125], v[204:207], v[32:35]
	v_mfma_f32_16x16x32_bf16 v[64:67], v[188:191], v[204:207], v[64:67]
	v_mfma_f32_16x16x32_bf16 v[40:43], v[222:225], v[208:211], v[40:43]
	v_mfma_f32_16x16x32_bf16 v[88:91], v[226:229], v[208:211], v[88:91]
	v_mfma_f32_16x16x32_bf16 v[48:51], v[122:125], v[208:211], v[48:51]
	v_mfma_f32_16x16x32_bf16 v[76:79], v[188:191], v[208:211], v[76:79]
	v_mfma_f32_16x16x32_bf16 v[80:83], v[222:225], v[216:219], v[80:83]
	v_mfma_f32_16x16x32_bf16 v[84:87], v[226:229], v[216:219], v[84:87]
	v_mfma_f32_16x16x32_bf16 v[68:71], v[122:125], v[216:219], v[68:71]
	v_mfma_f32_16x16x32_bf16 v[72:75], v[188:191], v[216:219], v[72:75]
	s_mov_b32 s6, s2
	s_waitcnt vmcnt(0) lgkmcnt(0)
	s_barrier
	s_cmp_lt_u32 s6, 16
	s_cbranch_scc1 .LBB0_1166
	s_setprio 0
	s_waitcnt vmcnt(5)
	v_add_u32_e32 v15, s46, v170
	v_or_b32_e32 v188, v15, v148
	v_or_b32_e32 v130, s0, v234
	s_add_i32 s0, s46, 0xfffff000
	v_lshlrev_b32_e32 v0, 2, v188
	s_ashr_i32 s0, s0, 10
	global_load_dword v14, v0, s[28:29]
	global_load_dword v30, v0, s[28:29] offset:64
	global_load_dword v31, v0, s[28:29] offset:128
	global_load_dword v44, v0, s[28:29] offset:192
	s_add_i32 s2, s0, 16
	s_and_b64 s[0:1], s[24:25], exec
	s_cselect_b32 s0, 15, s2
	s_mul_hi_u32 s1, s0, 0x4200
	s_mulk_i32 s0, 0x4200
	s_add_u32 s0, s4, s0
	s_addc_u32 s1, s5, s1
	v_mov_b32_e32 v139, v131
	v_lshl_add_u64 v[0:1], v[130:131], 2, s[0:1]
	v_lshl_add_u64 v[4:5], v[0:1], 0, v[138:139]
	global_load_dwordx4 v[22:25], v[4:5], off
	global_load_dwordx4 v[0:3], v[4:5], off offset:64
	global_load_dwordx4 v[92:95], v[4:5], off offset:128
	s_nop 0
	global_load_dwordx4 v[4:7], v[4:5], off offset:192
	v_mov_b32_e32 v12, v26
	v_mov_b32_e32 v13, v9
	v_mov_b32_e32 v9, v27
	s_waitcnt vmcnt(11)
	v_mov_b32_e32 v20, v54
	v_mov_b32_e32 v21, v37
	v_mov_b32_e32 v37, v55
	s_cmpk_lt_u32 s45, 0x50
	s_waitcnt vmcnt(7)
	v_fmamk_f32 v14, v14, 0x3a800000, v183
	s_waitcnt vmcnt(6)
	v_fmamk_f32 v26, v30, 0x3a800000, v183
	v_cmp_gt_f32_e64 s[10:11], s39, v26
	s_waitcnt vmcnt(4)
	v_fmamk_f32 v30, v44, 0x3a800000, v183
	v_mul_f32_e32 v44, 0x4b800000, v26
	v_fmamk_f32 v27, v31, 0x3a800000, v183
	v_mul_f32_e32 v46, 0x4b800000, v30
	v_cndmask_b32_e64 v26, v26, v44, s[10:11]
	v_cmp_gt_f32_e64 s[14:15], s39, v30
	v_mul_f32_e32 v31, 0x4b800000, v14
	v_mul_f32_e32 v45, 0x4b800000, v27
	v_cmp_gt_f32_e32 vcc, s39, v14
	v_cmp_gt_f32_e64 s[12:13], s39, v27
	v_cndmask_b32_e64 v30, v30, v46, s[14:15]
	v_rsq_f32_e32 v26, v26
	v_cndmask_b32_e32 v14, v14, v31, vcc
	v_cndmask_b32_e64 v27, v27, v45, s[12:13]
	v_rsq_f32_e32 v30, v30
	v_rsq_f32_e32 v14, v14
	v_rsq_f32_e32 v27, v27
	s_waitcnt vmcnt(2)
	v_mov_b32_e32 v97, v3
	v_mul_f32_e32 v3, 0x45800000, v26
	v_mov_b32_e32 v96, v25
	v_mul_f32_e32 v25, 0x45800000, v30
	v_cndmask_b32_e64 v102, v26, v3, s[10:11]
	v_mul_f32_e32 v31, 0x45800000, v14
	s_waitcnt vmcnt(0)
	v_mov_b32_e32 v99, v7
	v_mul_f32_e32 v7, 0x45800000, v27
	v_cndmask_b32_e64 v106, v30, v25, s[14:15]
	v_fma_f32 v30, v56, v102, v2
	v_mov_b32_e32 v56, v39
	v_mov_b32_e32 v53, v1
	v_mov_b32_e32 v1, v23
	v_cndmask_b32_e32 v100, v14, v31, vcc
	v_cndmask_b32_e64 v104, v27, v7, s[12:13]
	v_pk_fma_f32 v[152:153], v[56:57], v[102:103], v[96:97] op_sel_hi:[1,0,1]
	v_mov_b32_e32 v56, v88
	v_mov_b32_e32 v57, v41
	v_mov_b32_e32 v98, v95
	v_mov_b32_e32 v52, v22
	v_fma_f32 v14, v28, v100, v2
	v_mov_b32_e32 v28, v11
	v_fma_f32 v26, v38, v102, v24
	v_fma_f32 v38, v66, v102, v6
	v_mov_b32_e32 v66, v35
	v_mov_b32_e32 v41, v89
	v_pk_fma_f32 v[160:161], v[56:57], v[104:105], v[0:1] op_sel_hi:[1,0,1]
	v_mov_b32_e32 v56, v80
	v_mov_b32_e32 v57, v85
	v_mov_b32_e32 v85, v81
	v_fma_f32 v10, v10, v100, v24
	v_fma_f32 v42, v42, v104, v24
	v_fma_f32 v58, v82, v106, v24
	v_pk_fma_f32 v[8:9], v[8:9], v[100:101], v[52:53] op_sel_hi:[1,0,1]
	v_pk_fma_f32 v[140:141], v[12:13], v[100:101], v[0:1] op_sel_hi:[1,0,1]
	v_pk_fma_f32 v[24:25], v[36:37], v[102:103], v[52:53] op_sel_hi:[1,0,1]
	v_pk_fma_f32 v[20:21], v[20:21], v[102:103], v[0:1] op_sel_hi:[1,0,1]
	v_pk_fma_f32 v[142:143], v[28:29], v[100:101], v[96:97] op_sel_hi:[1,0,1]
	v_pk_fma_f32 v[28:29], v[66:67], v[102:103], v[98:99] op_sel_hi:[1,0,1]
	v_pk_fma_f32 v[40:41], v[40:41], v[104:105], v[52:53] op_sel_hi:[1,0,1]
	v_pk_fma_f32 v[56:57], v[56:57], v[106:107], v[52:53] op_sel_hi:[1,0,1]
	v_pk_fma_f32 v[52:53], v[84:85], v[106:107], v[0:1] op_sel_hi:[1,0,1]
	v_mov_b32_e32 v0, v60
	v_mov_b32_e32 v1, v17
	v_mov_b32_e32 v66, v4
	v_mov_b32_e32 v67, v93
	v_pk_fma_f32 v[156:157], v[0:1], v[100:101], v[66:67] op_sel_hi:[1,0,1]
	v_mov_b32_e32 v0, v64
	v_mov_b32_e32 v1, v33
	v_pk_fma_f32 v[162:163], v[0:1], v[102:103], v[66:67] op_sel_hi:[1,0,1]
	v_mov_b32_e32 v0, v76
	v_mov_b32_e32 v1, v49
	v_fma_f32 v22, v62, v100, v6
	v_mov_b32_e32 v62, v19
	v_fma_f32 v46, v90, v104, v2
	v_mov_b32_e32 v90, v43
	v_fma_f32 v54, v78, v104, v6
	v_mov_b32_e32 v78, v51
	v_fmac_f32_e32 v2, v86, v106
	v_mov_b32_e32 v86, v83
	v_mov_b32_e32 v17, v61
	v_mov_b32_e32 v93, v5
	v_mov_b32_e32 v33, v65
	v_pk_fma_f32 v[166:167], v[0:1], v[104:105], v[66:67] op_sel_hi:[1,0,1]
	v_mov_b32_e32 v49, v77
	v_mov_b32_e32 v0, v68
	v_mov_b32_e32 v1, v73
	v_mov_b32_e32 v73, v69
	v_fmac_f32_e32 v6, v74, v106
	v_mov_b32_e32 v74, v71
	s_cselect_b64 s[12:13], -1, 0
	s_and_b32 s0, s45, 0x7ffffff0
	v_fma_f32 v18, v18, v100, v94
	v_fma_f32 v34, v34, v102, v94
	v_fma_f32 v50, v50, v104, v94
	v_pk_fma_f32 v[12:13], v[62:63], v[100:101], v[98:99] op_sel_hi:[1,0,1]
	v_pk_fma_f32 v[36:37], v[90:91], v[104:105], v[96:97] op_sel_hi:[1,0,1]
	v_pk_fma_f32 v[44:45], v[78:79], v[104:105], v[98:99] op_sel_hi:[1,0,1]
	v_pk_fma_f32 v[164:165], v[86:87], v[106:107], v[96:97] op_sel_hi:[1,0,1]
	v_fma_f32 v62, v70, v106, v94
	v_pk_fma_f32 v[16:17], v[16:17], v[100:101], v[92:93] op_sel_hi:[1,0,1]
	v_pk_fma_f32 v[32:33], v[32:33], v[102:103], v[92:93] op_sel_hi:[1,0,1]
	v_pk_fma_f32 v[48:49], v[48:49], v[104:105], v[92:93] op_sel_hi:[1,0,1]
	v_pk_fma_f32 v[60:61], v[0:1], v[106:107], v[92:93] op_sel_hi:[1,0,1]
	v_pk_fma_f32 v[0:1], v[72:73], v[106:107], v[66:67] op_sel_hi:[1,0,1]
	v_pk_fma_f32 v[168:169], v[74:75], v[106:107], v[98:99] op_sel_hi:[1,0,1]
	s_cmpk_lg_i32 s0, 0x50
	s_mov_b64 s[10:11], -1
	s_cbranch_scc0 .LBB0_1181
	v_lshlrev_b32_e32 v3, 1, v15
	s_and_b64 s[0:1], s[26:27], s[12:13]
	v_and_b32_e32 v4, 0x780, v3
	v_mov_b32_e32 v5, v131
	v_cndmask_b32_e64 v3, 0, 1, s[0:1]
	v_lshl_add_u64 v[112:113], v[134:135], 0, v[4:5]
	v_cmp_ne_u32_e64 s[10:11], 1, v3
	s_andn2_b64 vcc, exec, s[0:1]
	v_lshlrev_b32_e32 v3, 7, v188
	s_cbranch_vccnz .LBB0_1170
	v_and_b32_e32 v4, 0x780, v3
	v_mov_b32_e32 v5, v131
	global_load_dwordx4 v[64:67], v[112:113], off
	global_load_dwordx4 v[68:71], v[112:113], off offset:16
	v_lshl_add_u64 v[4:5], v[134:135], 0, v[4:5]
	global_load_dwordx4 v[72:75], v[4:5], off
	global_load_dwordx4 v[76:79], v[4:5], off offset:16
	v_mov_b32_e32 v4, v140
	v_mov_b32_e32 v5, v9
	v_mov_b32_e32 v80, v8
	v_mov_b32_e32 v81, v141
	v_mov_b32_e32 v82, v156
	v_mov_b32_e32 v83, v17
	v_mov_b32_e32 v84, v16
	v_mov_b32_e32 v85, v157
	s_waitcnt vmcnt(3)
	v_mov_b32_e32 v90, v65
	v_mov_b32_e32 v91, v67
	v_mov_b32_e32 v86, v65
	v_mov_b32_e32 v65, v66
	v_pk_mul_f32 v[4:5], v[4:5], v[90:91]
	v_mov_b32_e32 v87, v66
	v_mov_b32_e32 v88, v64
	v_mov_b32_e32 v89, v67
	s_waitcnt vmcnt(2)
	v_mul_f32_e32 v66, v10, v68
	v_mul_f32_e32 v92, v14, v69
	v_mul_f32_e32 v94, v14, v68
	v_mul_f32_e32 v96, v10, v69
	v_pk_mul_f32 v[68:69], v[142:143], v[70:71]
	v_pk_mul_f32 v[70:71], v[142:143], v[70:71] op_sel:[1,0] op_sel_hi:[0,1]
	s_waitcnt vmcnt(1)
	v_mov_b32_e32 v90, v73
	v_mov_b32_e32 v91, v74
	v_mov_b32_e32 v98, v72
	v_mov_b32_e32 v99, v75
	v_mov_b32_e32 v100, v73
	v_mov_b32_e32 v101, v75
	v_mov_b32_e32 v73, v74
	s_waitcnt vmcnt(0)
	v_mul_f32_e32 v74, v18, v76
	v_mul_f32_e32 v102, v22, v77
	v_mul_f32_e32 v104, v22, v76
	v_mul_f32_e32 v106, v18, v77
	v_pk_fma_f32 v[64:65], v[80:81], v[64:65], v[4:5] neg_lo:[0,0,1] neg_hi:[0,0,1]
	v_pk_mul_f32 v[4:5], v[12:13], v[78:79]
	v_pk_mul_f32 v[76:77], v[12:13], v[78:79] op_sel:[1,0] op_sel_hi:[0,1]
	v_pk_mul_f32 v[88:89], v[140:141], v[88:89]
	v_mov_b32_e32 v67, v68
	v_mov_b32_e32 v93, v69
	v_mov_b32_e32 v95, v70
	v_mov_b32_e32 v97, v71
	v_pk_mul_f32 v[78:79], v[156:157], v[98:99]
	v_pk_mul_f32 v[80:81], v[82:83], v[100:101]
	v_mov_b32_e32 v75, v4
	v_mov_b32_e32 v103, v5
	v_mov_b32_e32 v105, v76
	v_mov_b32_e32 v107, v77
	v_pk_add_f32 v[66:67], v[66:67], v[92:93] neg_lo:[0,1] neg_hi:[0,1]
	v_pk_fma_f32 v[68:69], v[8:9], v[86:87], v[88:89]
	v_pk_add_f32 v[70:71], v[94:95], v[96:97]
	v_pk_fma_f32 v[72:73], v[84:85], v[72:73], v[80:81] neg_lo:[0,0,1] neg_hi:[0,0,1]
	v_pk_add_f32 v[74:75], v[74:75], v[102:103] neg_lo:[0,1] neg_hi:[0,1]
	v_pk_fma_f32 v[76:77], v[16:17], v[90:91], v[78:79]
	v_pk_add_f32 v[78:79], v[104:105], v[106:107]
	s_branch .LBB0_1171

.LBB0_1344:
	s_and_b32 s18, s97, 7
	s_or_b32 s18, s18, s0
	s_lshl_b32 s26, s18, 7
	s_lshl_b32 s24, s97, 4
	v_or_b32_e32 v0, s26, v149
	s_and_b32 s27, s24, 0x7fffff80
	v_lshl_or_b32 v96, v0, 11, v116
	v_or_b32_e32 v0, s27, v149
	s_waitcnt vmcnt(1)
	v_lshl_add_u64 v[100:101], s[10:11], 0, v[96:97]
	v_lshl_or_b32 v98, v0, 11, v116
	v_add_co_u32_e32 v0, vcc, 0x10000, v100
	v_mov_b32_e32 v99, v97
	s_nop 0
	v_addc_co_u32_e32 v1, vcc, 0, v101, vcc
	v_add_co_u32_e32 v2, vcc, 0x20000, v100
	v_lshl_add_u64 v[102:103], s[8:9], 0, v[98:99]
	s_nop 0
	v_addc_co_u32_e32 v3, vcc, 0, v101, vcc
	v_add_co_u32_e32 v6, vcc, 0x30000, v100
	s_nop 0
	v_addc_co_u32_e32 v7, vcc, 0, v101, vcc
	v_add_co_u32_e32 v12, vcc, s1, v102
	s_nop 0
	v_addc_co_u32_e32 v13, vcc, 0, v103, vcc
	v_add_co_u32_e32 v14, vcc, s4, v102
	s_nop 0
	v_addc_co_u32_e32 v15, vcc, 0, v103, vcc
	v_add_co_u32_e32 v48, vcc, s5, v102
	s_nop 0
	v_addc_co_u32_e32 v49, vcc, 0, v103, vcc
	s_movk_i32 s24, 0x100
	s_mov_b32 s28, s19
	v_mov_b32_e32 v8, 0
	v_mov_b32_e32 v9, v97
	v_mov_b32_e32 v10, v97
	v_mov_b32_e32 v11, v97
	v_mov_b32_e32 v4, 0
	v_mov_b32_e32 v5, v97
	v_mov_b32_e32 v6, v97
	v_mov_b32_e32 v7, v97
	v_mov_b32_e32 v12, 0
	v_mov_b32_e32 v13, v97
	v_mov_b32_e32 v14, v97
	v_mov_b32_e32 v15, v97
	v_mov_b32_e32 v0, 0
	v_mov_b32_e32 v1, v97
	v_lshl_add_u64 v[104:105], v[102:103], 0, s[12:13]
	v_lshl_add_u64 v[106:107], v[102:103], 0, s[14:15]
	v_lshl_add_u64 v[108:109], v[102:103], 0, s[16:17]
	v_lshl_add_u64 v[110:111], v[100:101], 0, s[12:13]
	v_lshl_add_u64 v[112:113], v[100:101], 0, s[14:15]
	v_lshl_add_u64 v[114:115], v[100:101], 0, s[16:17]
	s_barrier
	v_mov_b32_e32 v2, v97
	v_mov_b32_e32 v3, v97
	v_mov_b32_e32 v52, 0
	v_mov_b32_e32 v53, v97
	v_mov_b32_e32 v54, v97
	v_mov_b32_e32 v55, v97
	v_mov_b32_e32 v48, 0
	v_mov_b32_e32 v49, v97
	v_mov_b32_e32 v50, v97
	v_mov_b32_e32 v51, v97
	v_mov_b32_e32 v60, 0
	v_mov_b32_e32 v61, v97
	v_mov_b32_e32 v62, v97
	v_mov_b32_e32 v63, v97
	v_mov_b32_e32 v56, 0
	v_mov_b32_e32 v57, v97
	v_mov_b32_e32 v58, v97
	v_mov_b32_e32 v59, v97
	v_mov_b32_e32 v44, 0
	v_mov_b32_e32 v45, v97
	v_mov_b32_e32 v46, v97
	v_mov_b32_e32 v47, v97
	v_mov_b32_e32 v36, 0
	v_mov_b32_e32 v37, v97
	v_mov_b32_e32 v38, v97
	v_mov_b32_e32 v39, v97
	v_mov_b32_e32 v20, 0
	v_mov_b32_e32 v21, v97
	v_mov_b32_e32 v22, v97
	v_mov_b32_e32 v23, v97
	v_mov_b32_e32 v16, 0
	v_mov_b32_e32 v17, v97
	v_mov_b32_e32 v18, v97
	v_mov_b32_e32 v19, v97
	v_mov_b32_e32 v32, 0
	v_mov_b32_e32 v33, v97
	v_mov_b32_e32 v34, v97
	v_mov_b32_e32 v35, v97
	v_mov_b32_e32 v24, 0
	v_mov_b32_e32 v25, v97
	v_mov_b32_e32 v26, v97
	v_mov_b32_e32 v27, v97
	v_mov_b32_e32 v40, 0
	v_mov_b32_e32 v41, v97
	v_mov_b32_e32 v42, v97
	v_mov_b32_e32 v43, v97
	v_mov_b32_e32 v28, 0
	v_mov_b32_e32 v29, v97
	v_mov_b32_e32 v30, v97
	v_mov_b32_e32 v31, v97
	v_readlane_b32 s100, v253, 0
	v_readlane_b32 s101, v253, 1
	s_load_dwordx2 s[100:101], s[100:101], 0x160
	v_lshrrev_b32_e32 v71, 6, v146
	s_nop 0
	v_readfirstlane_b32 s30, v71
	v_lshrrev_b32_e32 v69, 3, v146
	v_and_b32_e32 v70, 7, v146
	v_xor_b32_e32 v70, v69, v70
	v_and_b32_e32 v70, 7, v70
	v_lshlrev_b32_e32 v70, 4, v70
	v_lshl_or_b32 v68, v69, 11, v70
	v_add_u32_e32 v69, 0x10000, v68
	v_add_u32_e32 v70, 0x20000, v68
	v_add_u32_e32 v71, 0x30000, v68
	s_and_b32 s98, s97, 7
	s_and_b32 s99, s69, 7
	s_lshl_b32 s99, s99, 3
	s_or_b32 s98, s98, s99
	s_lshl_b32 s98, s98, 18
	s_add_u32 s98, s98, 0x2000000
	s_lshr_b32 s99, s97, 3
	s_lshl_b32 s99, s99, 18
	s_add_u32 s99, s99, 0x9240000
	s_lshl_b32 s30, s30, 10
	s_waitcnt lgkmcnt(0)
	s_mov_b32 m0, s99
	s_add_u32 s98, s100, s98
	s_addc_u32 s99, s101, 0
	s_add_u32 s100, s100, m0
	s_addc_u32 s101, s101, 0
	s_add_u32 m0, s30, 0x0
	s_nop 0
	global_load_lds_dwordx4 v68, s[98:99]
	s_add_u32 m0, s30, 0x1000
	s_nop 0
	global_load_lds_dwordx4 v69, s[98:99]
	s_add_u32 m0, s30, 0x2000
	s_nop 0
	global_load_lds_dwordx4 v70, s[98:99]
	s_add_u32 m0, s30, 0x3000
	s_nop 0
	global_load_lds_dwordx4 v71, s[98:99]
	s_add_u32 m0, s30, 0x8000
	s_nop 0
	global_load_lds_dwordx4 v68, s[100:101]
	s_add_u32 m0, s30, 0x9000
	s_nop 0
	global_load_lds_dwordx4 v69, s[100:101]
	s_add_u32 m0, s30, 0xa000
	s_nop 0
	global_load_lds_dwordx4 v70, s[100:101]
	s_add_u32 m0, s30, 0xb000
	s_nop 0
	global_load_lds_dwordx4 v71, s[100:101]
	s_add_u32 s98, s98, 0x80
	s_addc_u32 s99, s99, 0
	s_add_u32 s100, s100, 0x80
	s_addc_u32 s101, s101, 0
	s_waitcnt vmcnt(0)
	s_waitcnt lgkmcnt(0)
	s_barrier
	s_bitcmp1_b32 s69, 8
	s_cbranch_scc1 .Lprio_h1345
	s_setprio 0
	s_branch .Lprio_j1345

.Lprio_j1345:
.LBB0_1345:
	s_add_i32 s25, s28, 2
	ds_read_b128 v[124:127], v119 offset:32768
	ds_read_b128 v[132:135], v119 offset:34816
	ds_read_b128 v[128:131], v118
	ds_read_b128 v[136:139], v118 offset:2048
	ds_read_b128 v[140:143], v118 offset:4096
	ds_read_b128 v[152:155], v118 offset:6144
	s_waitcnt lgkmcnt(3)
	v_mfma_f32_16x16x32_bf16 v[8:11], v[124:127], v[128:131], v[8:11]
	ds_read_b128 v[156:159], v119 offset:36864
	v_mfma_f32_16x16x32_bf16 v[4:7], v[132:135], v[128:131], v[4:7]
	ds_read_b128 v[160:163], v119 offset:38912
	s_waitcnt lgkmcnt(1)
	v_mfma_f32_16x16x32_bf16 v[12:15], v[156:159], v[128:131], v[12:15]
	s_waitcnt lgkmcnt(0)
	v_mfma_f32_16x16x32_bf16 v[0:3], v[160:163], v[128:131], v[0:3]
	s_add_u32 m0, s30, 0x4000
	s_nop 0
	global_load_lds_dwordx4 v68, s[98:99]
	ds_read_b128 v[164:167], v120
	v_mfma_f32_16x16x32_bf16 v[44:47], v[124:127], v[136:139], v[44:47]
	v_mfma_f32_16x16x32_bf16 v[36:39], v[132:135], v[136:139], v[36:39]
	s_add_u32 m0, s30, 0x5000
	s_nop 0
	global_load_lds_dwordx4 v69, s[98:99]
	ds_read_b128 v[172:175], v120 offset:2048
	v_mfma_f32_16x16x32_bf16 v[20:23], v[156:159], v[136:139], v[20:23]
	v_mfma_f32_16x16x32_bf16 v[16:19], v[160:163], v[136:139], v[16:19]
	s_add_u32 m0, s30, 0x6000
	s_nop 0
	global_load_lds_dwordx4 v70, s[98:99]
	ds_read_b128 v[176:179], v120 offset:4096
	v_mfma_f32_16x16x32_bf16 v[52:55], v[124:127], v[140:143], v[52:55]
	v_mfma_f32_16x16x32_bf16 v[48:51], v[132:135], v[140:143], v[48:51]
	s_add_u32 m0, s30, 0x7000
	s_nop 0
	global_load_lds_dwordx4 v71, s[98:99]
	ds_read_b128 v[184:187], v120 offset:6144
	v_mfma_f32_16x16x32_bf16 v[32:35], v[156:159], v[140:143], v[32:35]
	v_mfma_f32_16x16x32_bf16 v[24:27], v[160:163], v[140:143], v[24:27]
	s_add_u32 m0, s30, 0xc000
	s_nop 0
	global_load_lds_dwordx4 v68, s[100:101]
	ds_read_b128 v[188:191], v121 offset:32768
	v_mfma_f32_16x16x32_bf16 v[60:63], v[124:127], v[152:155], v[60:63]
	v_mfma_f32_16x16x32_bf16 v[56:59], v[132:135], v[152:155], v[56:59]
	s_add_u32 m0, s30, 0xd000
	s_nop 0
	global_load_lds_dwordx4 v69, s[100:101]
	ds_read_b128 v[132:135], v121 offset:34816
	v_mfma_f32_16x16x32_bf16 v[40:43], v[156:159], v[152:155], v[40:43]
	v_mfma_f32_16x16x32_bf16 v[28:31], v[160:163], v[152:155], v[28:31]
	s_add_u32 m0, s30, 0xe000
	s_nop 0
	global_load_lds_dwordx4 v70, s[100:101]
	ds_read_b128 v[156:159], v121 offset:36864
	s_waitcnt lgkmcnt(2)
	v_mfma_f32_16x16x32_bf16 v[8:11], v[188:191], v[164:167], v[8:11]
	s_waitcnt lgkmcnt(1)
	v_mfma_f32_16x16x32_bf16 v[4:7], v[132:135], v[164:167], v[4:7]
	s_add_u32 m0, s30, 0xf000
	s_nop 0
	global_load_lds_dwordx4 v71, s[100:101]
	s_add_u32 s98, s98, 0x80
	s_addc_u32 s99, s99, 0
	s_add_u32 s100, s100, 0x80
	s_addc_u32 s101, s101, 0
	ds_read_b128 v[192:195], v121 offset:38912
	s_waitcnt lgkmcnt(1)
	v_mfma_f32_16x16x32_bf16 v[12:15], v[156:159], v[164:167], v[12:15]
	s_waitcnt lgkmcnt(0)
	v_mfma_f32_16x16x32_bf16 v[0:3], v[192:195], v[164:167], v[0:3]
	v_mfma_f32_16x16x32_bf16 v[44:47], v[188:191], v[172:175], v[44:47]
	v_mfma_f32_16x16x32_bf16 v[36:39], v[132:135], v[172:175], v[36:39]
	v_mfma_f32_16x16x32_bf16 v[20:23], v[156:159], v[172:175], v[20:23]
	v_mfma_f32_16x16x32_bf16 v[16:19], v[192:195], v[172:175], v[16:19]
	v_mfma_f32_16x16x32_bf16 v[52:55], v[188:191], v[176:179], v[52:55]
	v_mfma_f32_16x16x32_bf16 v[48:51], v[132:135], v[176:179], v[48:51]
	v_mfma_f32_16x16x32_bf16 v[32:35], v[156:159], v[176:179], v[32:35]
	v_mfma_f32_16x16x32_bf16 v[24:27], v[192:195], v[176:179], v[24:27]
	v_mfma_f32_16x16x32_bf16 v[60:63], v[188:191], v[184:187], v[60:63]
	v_mfma_f32_16x16x32_bf16 v[56:59], v[132:135], v[184:187], v[56:59]
	v_mfma_f32_16x16x32_bf16 v[40:43], v[156:159], v[184:187], v[40:43]
	v_mfma_f32_16x16x32_bf16 v[28:31], v[192:195], v[184:187], v[28:31]
	s_waitcnt vmcnt(0) lgkmcnt(0)
	s_barrier
	ds_read_b128 v[84:87], v119 offset:49152
	ds_read_b128 v[88:91], v119 offset:51200
	ds_read_b128 v[64:67], v118 offset:16384
	ds_read_b128 v[72:75], v118 offset:18432
	ds_read_b128 v[76:79], v118 offset:20480
	ds_read_b128 v[92:95], v118 offset:22528
	s_waitcnt lgkmcnt(3)
	v_mfma_f32_16x16x32_bf16 v[8:11], v[84:87], v[64:67], v[8:11]
	ds_read_b128 v[132:135], v119 offset:53248
	v_mfma_f32_16x16x32_bf16 v[4:7], v[88:91], v[64:67], v[4:7]
	ds_read_b128 v[156:159], v119 offset:55296
	s_waitcnt lgkmcnt(1)
	v_mfma_f32_16x16x32_bf16 v[12:15], v[132:135], v[64:67], v[12:15]
	s_waitcnt lgkmcnt(0)
	v_mfma_f32_16x16x32_bf16 v[0:3], v[156:159], v[64:67], v[0:3]
	s_add_u32 m0, s30, 0x0
	s_nop 0
	global_load_lds_dwordx4 v68, s[98:99]
	ds_read_b128 v[164:167], v120 offset:16384
	v_mfma_f32_16x16x32_bf16 v[44:47], v[84:87], v[72:75], v[44:47]
	v_mfma_f32_16x16x32_bf16 v[36:39], v[88:91], v[72:75], v[36:39]
	s_add_u32 m0, s30, 0x1000
	s_nop 0
	global_load_lds_dwordx4 v69, s[98:99]
	ds_read_b128 v[172:175], v120 offset:18432
	v_mfma_f32_16x16x32_bf16 v[20:23], v[132:135], v[72:75], v[20:23]
	v_mfma_f32_16x16x32_bf16 v[16:19], v[156:159], v[72:75], v[16:19]
	s_add_u32 m0, s30, 0x2000
	s_nop 0
	global_load_lds_dwordx4 v70, s[98:99]
	ds_read_b128 v[176:179], v120 offset:20480
	v_mfma_f32_16x16x32_bf16 v[52:55], v[84:87], v[76:79], v[52:55]
	v_mfma_f32_16x16x32_bf16 v[48:51], v[88:91], v[76:79], v[48:51]
	s_add_u32 m0, s30, 0x3000
	s_nop 0
	global_load_lds_dwordx4 v71, s[98:99]
	ds_read_b128 v[184:187], v120 offset:22528
	v_mfma_f32_16x16x32_bf16 v[32:35], v[132:135], v[76:79], v[32:35]
	v_mfma_f32_16x16x32_bf16 v[24:27], v[156:159], v[76:79], v[24:27]
	s_add_u32 m0, s30, 0x8000
	s_nop 0
	global_load_lds_dwordx4 v68, s[100:101]
	ds_read_b128 v[188:191], v121 offset:49152
	v_mfma_f32_16x16x32_bf16 v[60:63], v[84:87], v[92:95], v[60:63]
	v_mfma_f32_16x16x32_bf16 v[56:59], v[88:91], v[92:95], v[56:59]
	s_add_u32 m0, s30, 0x9000
	s_nop 0
	global_load_lds_dwordx4 v69, s[100:101]
	ds_read_b128 v[192:195], v121 offset:51200
	v_mfma_f32_16x16x32_bf16 v[40:43], v[132:135], v[92:95], v[40:43]
	v_mfma_f32_16x16x32_bf16 v[28:31], v[156:159], v[92:95], v[28:31]
	s_add_u32 m0, s30, 0xa000
	s_nop 0
	global_load_lds_dwordx4 v70, s[100:101]
	ds_read_b128 v[132:135], v121 offset:53248
	s_waitcnt lgkmcnt(2)
	v_mfma_f32_16x16x32_bf16 v[8:11], v[188:191], v[164:167], v[8:11]
	s_waitcnt lgkmcnt(1)
	v_mfma_f32_16x16x32_bf16 v[4:7], v[192:195], v[164:167], v[4:7]
	s_add_u32 m0, s30, 0xb000
	s_nop 0
	global_load_lds_dwordx4 v71, s[100:101]
	s_add_u32 s98, s98, 0x80
	s_addc_u32 s99, s99, 0
	s_add_u32 s100, s100, 0x80
	s_addc_u32 s101, s101, 0
	ds_read_b128 v[156:159], v121 offset:55296
	s_waitcnt lgkmcnt(1)
	v_mfma_f32_16x16x32_bf16 v[12:15], v[132:135], v[164:167], v[12:15]
	s_waitcnt lgkmcnt(0)
	v_mfma_f32_16x16x32_bf16 v[0:3], v[156:159], v[164:167], v[0:3]
	v_mfma_f32_16x16x32_bf16 v[44:47], v[188:191], v[172:175], v[44:47]
	v_mfma_f32_16x16x32_bf16 v[36:39], v[192:195], v[172:175], v[36:39]
	v_mfma_f32_16x16x32_bf16 v[20:23], v[132:135], v[172:175], v[20:23]
	v_mfma_f32_16x16x32_bf16 v[16:19], v[156:159], v[172:175], v[16:19]
	v_mfma_f32_16x16x32_bf16 v[52:55], v[188:191], v[176:179], v[52:55]
	v_mfma_f32_16x16x32_bf16 v[48:51], v[192:195], v[176:179], v[48:51]
	v_mfma_f32_16x16x32_bf16 v[32:35], v[132:135], v[176:179], v[32:35]
	v_mfma_f32_16x16x32_bf16 v[24:27], v[156:159], v[176:179], v[24:27]
	v_mfma_f32_16x16x32_bf16 v[60:63], v[188:191], v[184:187], v[60:63]
	v_mfma_f32_16x16x32_bf16 v[56:59], v[192:195], v[184:187], v[56:59]
	v_mfma_f32_16x16x32_bf16 v[40:43], v[132:135], v[184:187], v[40:43]
	v_mfma_f32_16x16x32_bf16 v[28:31], v[156:159], v[184:187], v[28:31]
	s_mov_b32 s28, s25
	s_waitcnt vmcnt(0) lgkmcnt(0)
	s_barrier
	s_cmp_lt_u32 s28, 16
	s_cbranch_scc1 .LBB0_1345
	s_setprio 0
	s_add_i32 s18, s26, 0xfffff000
	s_ashr_i32 s18, s18, 10
	s_add_i32 s18, s18, 16
	s_and_b64 s[24:25], s[2:3], exec
	s_cselect_b32 s18, 15, s18
	s_mul_hi_u32 s24, s18, 0x3000
	s_mulk_i32 s18, 0x3000
	s_add_u32 s18, s6, s18
	v_or_b32_e32 v96, s27, v123
	s_addc_u32 s25, s7, s24
	s_waitcnt vmcnt(7)
	v_lshlrev_b64 v[64:65], 2, v[96:97]
	s_add_u32 s24, s18, 0xf442000
	s_waitcnt vmcnt(0)
	v_lshl_add_u64 v[94:95], s[6:7], 0, v[64:65]
	v_add_lshl_u32 v78, s26, v122, 12
	s_addc_u32 s25, s25, 0
	v_mov_b32_e32 v79, v97
	v_or_b32_e32 v114, 0x10000, v78
	v_mov_b32_e32 v115, v97
	v_or_b32_e32 v160, 0x20000, v78
	v_mov_b32_e32 v161, v97
	v_or_b32_e32 v164, 0x30000, v78
	v_mov_b32_e32 v165, v97
	v_or_b32_e32 v86, 16, v96
	v_mov_b32_e32 v87, v97
	v_lshl_add_u64 v[102:103], v[94:95], 0, 64
	v_or_b32_e32 v110, 32, v96
	v_mov_b32_e32 v111, v97
	v_lshl_add_u64 v[136:137], v[94:95], 0, s[20:21]
	v_or_b32_e32 v96, 48, v96
	v_lshl_add_u64 v[74:75], s[24:25], 0, v[64:65]
	v_lshl_add_u64 v[64:65], v[94:95], 0, v[78:79]
	v_lshl_add_u64 v[146:147], v[94:95], 0, v[114:115]
	v_lshl_add_u64 v[168:169], v[94:95], 0, v[160:161]
	v_lshl_add_u64 v[170:171], v[94:95], 0, v[164:165]
	v_lshl_add_u64 v[90:91], v[86:87], 2, s[24:25]
	v_lshl_add_u64 v[174:175], v[102:103], 0, v[160:161]
	v_lshl_add_u64 v[110:111], v[110:111], 2, s[24:25]
	v_lshl_add_u64 v[178:179], v[136:137], 0, v[114:115]
	v_lshl_add_u64 v[180:181], v[136:137], 0, v[160:161]
	v_lshl_add_u64 v[182:183], v[136:137], 0, v[164:165]
	v_lshl_add_u64 v[140:141], v[96:97], 2, s[24:25]
	v_lshl_add_u64 v[94:95], v[94:95], 0, s[22:23]
	global_load_dwordx4 v[66:69], v[74:75], off
	global_load_dwordx4 v[70:73], v[64:65], off
	v_lshl_add_u64 v[172:173], v[102:103], 0, v[114:115]
	global_load_dwordx4 v[74:77], v[146:147], off
	global_load_dwordx4 v[78:81], v[168:169], off
	global_load_dwordx4 v[82:85], v[170:171], off
	global_load_dwordx4 v[86:89], v[64:65], off offset:64
	s_nop 0
	global_load_dwordx4 v[90:93], v[90:91], off
	s_nop 0
	global_load_dwordx4 v[98:101], v[172:173], off
	v_lshl_add_u64 v[176:177], v[102:103], 0, v[164:165]
	global_load_dwordx4 v[102:105], v[174:175], off
	global_load_dwordx4 v[106:109], v[176:177], off
	s_nop 0
	global_load_dwordx4 v[110:113], v[110:111], off
	s_nop 0
	global_load_dwordx4 v[124:127], v[64:65], off offset:128
	global_load_dwordx4 v[128:131], v[178:179], off
	global_load_dwordx4 v[132:135], v[180:181], off
	global_load_dwordx4 v[136:139], v[182:183], off
	s_nop 0
	global_load_dwordx4 v[140:143], v[140:141], off
	s_nop 0
	global_load_dwordx4 v[152:155], v[64:65], off offset:192
	v_lshl_add_u64 v[114:115], v[94:95], 0, v[114:115]
	global_load_dwordx4 v[156:159], v[114:115], off
	v_lshl_add_u64 v[184:185], v[94:95], 0, v[160:161]
	global_load_dwordx4 v[160:163], v[184:185], off
	v_lshl_add_u64 v[94:95], v[94:95], 0, v[164:165]
	global_load_dwordx4 v[164:167], v[94:95], off
	s_add_i32 s97, s97, s96
	s_cmp_gt_u32 s97, 63
	s_waitcnt vmcnt(18)
	v_pk_fma_f32 v[8:9], v[8:9], v[66:67], v[70:71]
	v_pk_fma_f32 v[10:11], v[10:11], v[68:69], v[72:73]
	s_waitcnt vmcnt(17)
	v_pk_fma_f32 v[44:45], v[44:45], v[66:67], v[74:75]
	v_pk_fma_f32 v[46:47], v[46:47], v[68:69], v[76:77]
	s_waitcnt vmcnt(13)
	v_pk_fma_f32 v[4:5], v[4:5], v[90:91], v[86:87]
	v_pk_fma_f32 v[6:7], v[6:7], v[92:93], v[88:89]
	v_pk_fma_f32 v[52:53], v[52:53], v[66:67], v[78:79]
	v_pk_fma_f32 v[54:55], v[54:55], v[68:69], v[80:81]
	v_pk_fma_f32 v[60:61], v[60:61], v[66:67], v[82:83]
	v_pk_fma_f32 v[62:63], v[62:63], v[68:69], v[84:85]
	s_waitcnt vmcnt(12)
	v_pk_fma_f32 v[36:37], v[36:37], v[90:91], v[98:99]
	v_pk_fma_f32 v[38:39], v[38:39], v[92:93], v[100:101]
	s_waitcnt vmcnt(3)
	v_pk_fma_f32 v[0:1], v[0:1], v[140:141], v[152:153]
	v_pk_fma_f32 v[2:3], v[2:3], v[142:143], v[154:155]
	v_pk_fma_f32 v[48:49], v[48:49], v[90:91], v[102:103]
	v_pk_fma_f32 v[50:51], v[50:51], v[92:93], v[104:105]
	v_pk_fma_f32 v[56:57], v[56:57], v[90:91], v[106:107]
	v_pk_fma_f32 v[58:59], v[58:59], v[92:93], v[108:109]
	v_pk_fma_f32 v[12:13], v[12:13], v[110:111], v[124:125]
	v_pk_fma_f32 v[14:15], v[14:15], v[112:113], v[126:127]
	global_store_dwordx4 v[64:65], v[8:11], off
	global_store_dwordx4 v[146:147], v[44:47], off
	global_store_dwordx4 v[168:169], v[52:55], off
	global_store_dwordx4 v[170:171], v[60:63], off
	global_store_dwordx4 v[64:65], v[4:7], off offset:64
	global_store_dwordx4 v[172:173], v[36:39], off
	global_store_dwordx4 v[174:175], v[48:51], off
	global_store_dwordx4 v[176:177], v[56:59], off
	global_store_dwordx4 v[64:65], v[12:15], off offset:128
	v_pk_fma_f32 v[4:5], v[20:21], v[110:111], v[128:129]
	v_pk_fma_f32 v[6:7], v[22:23], v[112:113], v[130:131]
	global_store_dwordx4 v[64:65], v[0:3], off offset:192
	global_store_dwordx4 v[178:179], v[4:7], off
	s_waitcnt vmcnt(13)
	v_pk_fma_f32 v[0:1], v[16:17], v[140:141], v[156:157]
	v_pk_fma_f32 v[2:3], v[18:19], v[142:143], v[158:159]
	v_pk_fma_f32 v[4:5], v[32:33], v[110:111], v[132:133]
	v_pk_fma_f32 v[6:7], v[34:35], v[112:113], v[134:135]
	global_store_dwordx4 v[114:115], v[0:3], off
	global_store_dwordx4 v[180:181], v[4:7], off
	s_waitcnt vmcnt(14)
	v_pk_fma_f32 v[0:1], v[24:25], v[140:141], v[160:161]
	v_pk_fma_f32 v[2:3], v[26:27], v[142:143], v[162:163]
	v_pk_fma_f32 v[4:5], v[40:41], v[110:111], v[136:137]
	v_pk_fma_f32 v[6:7], v[42:43], v[112:113], v[138:139]
	global_store_dwordx4 v[184:185], v[0:3], off
	global_store_dwordx4 v[182:183], v[4:7], off
	s_waitcnt vmcnt(15)
	v_pk_fma_f32 v[0:1], v[28:29], v[140:141], v[164:165]
	v_pk_fma_f32 v[2:3], v[30:31], v[142:143], v[166:167]
	global_store_dwordx4 v[94:95], v[0:3], off
	s_cbranch_scc0 .LBB0_1344
